# epilogues of the one-round GEMM phases (w_out, down, merged) and the LoRA bias: loads hoisted and pipelined per row group, counted waits instead of vmcnt(0) per 16x16 piece; same arithmetic
# speedup vs baseline: 1.1070x; 1.0289x over previous
.LBB0_793:
	s_andn2_b64 vcc, exec, s[8:9]
	s_cbranch_vccnz .LBB0_795
	v_lshlrev_b32_e32 v140, 2, v134
	global_load_dwordx4 v[224:227], v140, s[64:65]
	global_load_dwordx4 v[228:231], v140, s[64:65] offset:64
	global_load_dwordx4 v[232:235], v140, s[64:65] offset:512
	global_load_dwordx4 v[236:239], v140, s[64:65] offset:576
	s_waitcnt vmcnt(0)
	v_add_f32_e32 v132, v128, v224
	v_add_f32_e32 v133, v129, v225
	v_add_f32_e32 v135, v130, v226
	v_add_f32_e32 v142, v131, v227
	v_mul_f32_e32 v132, 0xbfb8aa3b, v132
	v_mul_f32_e32 v133, 0xbfb8aa3b, v133
	v_mul_f32_e32 v135, 0xbfb8aa3b, v135
	v_mul_f32_e32 v142, 0xbfb8aa3b, v142
	v_exp_f32_e32 v132, v132
	v_exp_f32_e32 v133, v133
	v_exp_f32_e32 v135, v135
	v_exp_f32_e32 v142, v142
	v_add_f32_e32 v132, 1.0, v132
	v_add_f32_e32 v133, 1.0, v133
	v_add_f32_e32 v135, 1.0, v135
	v_add_f32_e32 v142, 1.0, v142
	v_rcp_f32_e32 v156, v132
	v_rcp_f32_e32 v157, v133
	v_rcp_f32_e32 v158, v135
	v_rcp_f32_e32 v159, v142
	v_lshlrev_b64 v[132:133], 12, v[148:149]
	v_lshl_add_u64 v[132:133], s[14:15], 0, v[132:133]
	v_lshl_add_u64 v[132:133], v[132:133], 0, v[140:141]
	global_store_dwordx4 v[132:133], v[156:159], off
	v_add_f32_e32 v135, v124, v228
	v_add_f32_e32 v142, v125, v229
	v_add_f32_e32 v143, v126, v230
	v_add_f32_e32 v146, v127, v231
	v_mul_f32_e32 v135, 0xbfb8aa3b, v135
	v_mul_f32_e32 v142, 0xbfb8aa3b, v142
	v_mul_f32_e32 v143, 0xbfb8aa3b, v143
	v_mul_f32_e32 v146, 0xbfb8aa3b, v146
	v_exp_f32_e32 v135, v135
	v_exp_f32_e32 v142, v142
	v_exp_f32_e32 v143, v143
	v_exp_f32_e32 v146, v146
	v_add_f32_e32 v135, 1.0, v135
	v_add_f32_e32 v142, 1.0, v142
	v_add_f32_e32 v143, 1.0, v143
	v_add_f32_e32 v146, 1.0, v146
	v_rcp_f32_e32 v156, v135
	v_rcp_f32_e32 v157, v142
	v_rcp_f32_e32 v158, v143
	v_rcp_f32_e32 v159, v146
	global_store_dwordx4 v[132:133], v[156:159], off offset:64
	v_add_f32_e32 v135, v120, v232
	v_add_f32_e32 v142, v121, v233
	v_add_f32_e32 v143, v122, v234
	v_add_f32_e32 v146, v123, v235
	v_mul_f32_e32 v135, 0xbfb8aa3b, v135
	v_mul_f32_e32 v142, 0xbfb8aa3b, v142
	v_mul_f32_e32 v143, 0xbfb8aa3b, v143
	v_mul_f32_e32 v146, 0xbfb8aa3b, v146
	v_exp_f32_e32 v135, v135
	v_exp_f32_e32 v142, v142
	v_exp_f32_e32 v143, v143
	v_exp_f32_e32 v146, v146
	v_add_f32_e32 v135, 1.0, v135
	v_add_f32_e32 v142, 1.0, v142
	v_add_f32_e32 v143, 1.0, v143
	v_add_f32_e32 v146, 1.0, v146
	v_rcp_f32_e32 v156, v135
	v_rcp_f32_e32 v157, v142
	v_rcp_f32_e32 v158, v143
	v_rcp_f32_e32 v159, v146
	global_store_dwordx4 v[132:133], v[156:159], off offset:512
	v_add_f32_e32 v135, v116, v236
	v_add_f32_e32 v142, v117, v237
	v_add_f32_e32 v143, v118, v238
	v_add_f32_e32 v146, v119, v239
	v_mul_f32_e32 v135, 0xbfb8aa3b, v135
	v_mul_f32_e32 v142, 0xbfb8aa3b, v142
	v_mul_f32_e32 v143, 0xbfb8aa3b, v143
	v_mul_f32_e32 v146, 0xbfb8aa3b, v146
	v_exp_f32_e32 v135, v135
	v_exp_f32_e32 v142, v142
	v_exp_f32_e32 v143, v143
	v_exp_f32_e32 v146, v146
	v_add_f32_e32 v135, 1.0, v135
	v_add_f32_e32 v142, 1.0, v142
	v_add_f32_e32 v143, 1.0, v143
	v_add_f32_e32 v146, 1.0, v146
	v_rcp_f32_e32 v156, v135
	v_rcp_f32_e32 v157, v142
	v_rcp_f32_e32 v158, v143
	v_rcp_f32_e32 v159, v146
	v_or_b32_e32 v142, 16, v148
	v_ashrrev_i32_e32 v143, 31, v142
	v_lshlrev_b64 v[142:143], 12, v[142:143]
	global_store_dwordx4 v[132:133], v[156:159], off offset:576
	v_lshl_add_u64 v[142:143], s[14:15], 0, v[142:143]
	v_lshl_add_u64 v[142:143], v[142:143], 0, v[140:141]
	v_add_f32_e32 v135, v112, v224
	v_add_f32_e32 v146, v113, v225
	v_add_f32_e32 v147, v114, v226
	v_add_f32_e32 v155, v115, v227
	v_mul_f32_e32 v135, 0xbfb8aa3b, v135
	v_mul_f32_e32 v146, 0xbfb8aa3b, v146
	v_mul_f32_e32 v147, 0xbfb8aa3b, v147
	v_mul_f32_e32 v155, 0xbfb8aa3b, v155
	v_exp_f32_e32 v135, v135
	v_exp_f32_e32 v146, v146
	v_exp_f32_e32 v147, v147
	v_exp_f32_e32 v155, v155
	v_add_f32_e32 v135, 1.0, v135
	v_add_f32_e32 v146, 1.0, v146
	v_add_f32_e32 v147, 1.0, v147
	v_add_f32_e32 v155, 1.0, v155
	v_rcp_f32_e32 v156, v135
	v_rcp_f32_e32 v157, v146
	v_rcp_f32_e32 v158, v147
	v_rcp_f32_e32 v159, v155
	global_store_dwordx4 v[142:143], v[156:159], off
	v_add_f32_e32 v135, v108, v228
	v_add_f32_e32 v146, v109, v229
	v_add_f32_e32 v147, v110, v230
	v_add_f32_e32 v155, v111, v231
	v_mul_f32_e32 v135, 0xbfb8aa3b, v135
	v_mul_f32_e32 v146, 0xbfb8aa3b, v146
	v_mul_f32_e32 v147, 0xbfb8aa3b, v147
	v_mul_f32_e32 v155, 0xbfb8aa3b, v155
	v_exp_f32_e32 v135, v135
	v_exp_f32_e32 v146, v146
	v_exp_f32_e32 v147, v147
	v_exp_f32_e32 v155, v155
	v_add_f32_e32 v135, 1.0, v135
	v_add_f32_e32 v146, 1.0, v146
	v_add_f32_e32 v147, 1.0, v147
	v_add_f32_e32 v155, 1.0, v155
	v_rcp_f32_e32 v156, v135
	v_rcp_f32_e32 v157, v146
	v_rcp_f32_e32 v158, v147
	v_rcp_f32_e32 v159, v155
	global_store_dwordx4 v[142:143], v[156:159], off offset:64
	v_add_f32_e32 v135, v104, v232
	v_add_f32_e32 v146, v105, v233
	v_add_f32_e32 v147, v106, v234
	v_add_f32_e32 v155, v107, v235
	v_mul_f32_e32 v135, 0xbfb8aa3b, v135
	v_mul_f32_e32 v146, 0xbfb8aa3b, v146
	v_mul_f32_e32 v147, 0xbfb8aa3b, v147
	v_mul_f32_e32 v155, 0xbfb8aa3b, v155
	v_exp_f32_e32 v135, v135
	v_exp_f32_e32 v146, v146
	v_exp_f32_e32 v147, v147
	v_exp_f32_e32 v155, v155
	v_add_f32_e32 v135, 1.0, v135
	v_add_f32_e32 v146, 1.0, v146
	v_add_f32_e32 v147, 1.0, v147
	v_add_f32_e32 v155, 1.0, v155
	v_rcp_f32_e32 v156, v135
	v_rcp_f32_e32 v157, v146
	v_rcp_f32_e32 v158, v147
	v_rcp_f32_e32 v159, v155
	global_store_dwordx4 v[142:143], v[156:159], off offset:512
	v_add_f32_e32 v135, v100, v236
	v_add_f32_e32 v146, v101, v237
	v_add_f32_e32 v147, v102, v238
	v_add_f32_e32 v155, v103, v239
	v_mul_f32_e32 v135, 0xbfb8aa3b, v135
	v_mul_f32_e32 v146, 0xbfb8aa3b, v146
	v_mul_f32_e32 v147, 0xbfb8aa3b, v147
	v_mul_f32_e32 v155, 0xbfb8aa3b, v155
	v_exp_f32_e32 v135, v135
	v_exp_f32_e32 v146, v146
	v_exp_f32_e32 v147, v147
	v_exp_f32_e32 v155, v155
	v_add_f32_e32 v135, 1.0, v135
	v_add_f32_e32 v146, 1.0, v146
	v_add_f32_e32 v147, 1.0, v147
	v_add_f32_e32 v155, 1.0, v155
	v_rcp_f32_e32 v156, v135
	v_rcp_f32_e32 v157, v146
	v_rcp_f32_e32 v158, v147
	v_rcp_f32_e32 v159, v155
	global_store_dwordx4 v[142:143], v[156:159], off offset:576
	v_or_b32_e32 v142, 32, v148
	v_ashrrev_i32_e32 v143, 31, v142
	v_lshlrev_b64 v[142:143], 12, v[142:143]
	v_lshl_add_u64 v[142:143], s[14:15], 0, v[142:143]
	v_lshl_add_u64 v[142:143], v[142:143], 0, v[140:141]
	v_add_f32_e32 v135, v96, v224
	v_add_f32_e32 v146, v97, v225
	v_add_f32_e32 v147, v98, v226
	v_add_f32_e32 v155, v99, v227
	v_mul_f32_e32 v135, 0xbfb8aa3b, v135
	v_mul_f32_e32 v146, 0xbfb8aa3b, v146
	v_mul_f32_e32 v147, 0xbfb8aa3b, v147
	v_mul_f32_e32 v155, 0xbfb8aa3b, v155
	v_exp_f32_e32 v135, v135
	v_exp_f32_e32 v146, v146
	v_exp_f32_e32 v147, v147
	v_exp_f32_e32 v155, v155
	v_add_f32_e32 v135, 1.0, v135
	v_add_f32_e32 v146, 1.0, v146
	v_add_f32_e32 v147, 1.0, v147
	v_add_f32_e32 v155, 1.0, v155
	v_rcp_f32_e32 v156, v135
	v_rcp_f32_e32 v157, v146
	v_rcp_f32_e32 v158, v147
	v_rcp_f32_e32 v159, v155
	global_store_dwordx4 v[142:143], v[156:159], off
	v_add_f32_e32 v135, v92, v228
	v_add_f32_e32 v146, v93, v229
	v_add_f32_e32 v147, v94, v230
	v_add_f32_e32 v155, v95, v231
	v_mul_f32_e32 v135, 0xbfb8aa3b, v135
	v_mul_f32_e32 v146, 0xbfb8aa3b, v146
	v_mul_f32_e32 v147, 0xbfb8aa3b, v147
	v_mul_f32_e32 v155, 0xbfb8aa3b, v155
	v_exp_f32_e32 v135, v135
	v_exp_f32_e32 v146, v146
	v_exp_f32_e32 v147, v147
	v_exp_f32_e32 v155, v155
	v_add_f32_e32 v135, 1.0, v135
	v_add_f32_e32 v146, 1.0, v146
	v_add_f32_e32 v147, 1.0, v147
	v_add_f32_e32 v155, 1.0, v155
	v_rcp_f32_e32 v156, v135
	v_rcp_f32_e32 v157, v146
	v_rcp_f32_e32 v158, v147
	v_rcp_f32_e32 v159, v155
	global_store_dwordx4 v[142:143], v[156:159], off offset:64
	v_add_f32_e32 v135, v88, v232
	v_add_f32_e32 v146, v89, v233
	v_add_f32_e32 v147, v90, v234
	v_add_f32_e32 v155, v91, v235
	v_mul_f32_e32 v135, 0xbfb8aa3b, v135
	v_mul_f32_e32 v146, 0xbfb8aa3b, v146
	v_mul_f32_e32 v147, 0xbfb8aa3b, v147
	v_mul_f32_e32 v155, 0xbfb8aa3b, v155
	v_exp_f32_e32 v135, v135
	v_exp_f32_e32 v146, v146
	v_exp_f32_e32 v147, v147
	v_exp_f32_e32 v155, v155
	v_add_f32_e32 v135, 1.0, v135
	v_add_f32_e32 v146, 1.0, v146
	v_add_f32_e32 v147, 1.0, v147
	v_add_f32_e32 v155, 1.0, v155
	v_rcp_f32_e32 v156, v135
	v_rcp_f32_e32 v157, v146
	v_rcp_f32_e32 v158, v147
	v_rcp_f32_e32 v159, v155
	global_store_dwordx4 v[142:143], v[156:159], off offset:512
	v_add_f32_e32 v135, v84, v236
	v_add_f32_e32 v146, v85, v237
	v_add_f32_e32 v147, v86, v238
	v_add_f32_e32 v155, v87, v239
	v_mul_f32_e32 v135, 0xbfb8aa3b, v135
	v_mul_f32_e32 v146, 0xbfb8aa3b, v146
	v_mul_f32_e32 v147, 0xbfb8aa3b, v147
	v_mul_f32_e32 v155, 0xbfb8aa3b, v155
	v_exp_f32_e32 v135, v135
	v_exp_f32_e32 v146, v146
	v_exp_f32_e32 v147, v147
	v_exp_f32_e32 v155, v155
	v_add_f32_e32 v135, 1.0, v135
	v_add_f32_e32 v146, 1.0, v146
	v_add_f32_e32 v147, 1.0, v147
	v_add_f32_e32 v155, 1.0, v155
	v_rcp_f32_e32 v156, v135
	v_rcp_f32_e32 v157, v146
	v_rcp_f32_e32 v158, v147
	v_rcp_f32_e32 v159, v155
	global_store_dwordx4 v[142:143], v[156:159], off offset:576
	v_or_b32_e32 v142, 48, v148
	v_ashrrev_i32_e32 v143, 31, v142
	v_lshlrev_b64 v[142:143], 12, v[142:143]
	v_lshl_add_u64 v[142:143], s[14:15], 0, v[142:143]
	v_lshl_add_u64 v[142:143], v[142:143], 0, v[140:141]
	v_add_f32_e32 v135, v80, v224
	v_add_f32_e32 v146, v81, v225
	v_add_f32_e32 v147, v82, v226
	v_add_f32_e32 v155, v83, v227
	v_mul_f32_e32 v135, 0xbfb8aa3b, v135
	v_mul_f32_e32 v146, 0xbfb8aa3b, v146
	v_mul_f32_e32 v147, 0xbfb8aa3b, v147
	v_mul_f32_e32 v155, 0xbfb8aa3b, v155
	v_exp_f32_e32 v135, v135
	v_exp_f32_e32 v146, v146
	v_exp_f32_e32 v147, v147
	v_exp_f32_e32 v155, v155
	v_add_f32_e32 v135, 1.0, v135
	v_add_f32_e32 v146, 1.0, v146
	v_add_f32_e32 v147, 1.0, v147
	v_add_f32_e32 v155, 1.0, v155
	v_rcp_f32_e32 v156, v135
	v_rcp_f32_e32 v157, v146
	v_rcp_f32_e32 v158, v147
	v_rcp_f32_e32 v159, v155
	global_store_dwordx4 v[142:143], v[156:159], off
	v_add_f32_e32 v135, v76, v228
	v_add_f32_e32 v146, v77, v229
	v_add_f32_e32 v147, v78, v230
	v_add_f32_e32 v155, v79, v231
	v_mul_f32_e32 v135, 0xbfb8aa3b, v135
	v_mul_f32_e32 v146, 0xbfb8aa3b, v146
	v_mul_f32_e32 v147, 0xbfb8aa3b, v147
	v_mul_f32_e32 v155, 0xbfb8aa3b, v155
	v_exp_f32_e32 v135, v135
	v_exp_f32_e32 v146, v146
	v_exp_f32_e32 v147, v147
	v_exp_f32_e32 v155, v155
	v_add_f32_e32 v135, 1.0, v135
	v_add_f32_e32 v146, 1.0, v146
	v_add_f32_e32 v147, 1.0, v147
	v_add_f32_e32 v155, 1.0, v155
	v_rcp_f32_e32 v156, v135
	v_rcp_f32_e32 v157, v146
	v_rcp_f32_e32 v158, v147
	v_rcp_f32_e32 v159, v155
	global_store_dwordx4 v[142:143], v[156:159], off offset:64
	v_add_f32_e32 v135, v72, v232
	v_add_f32_e32 v146, v73, v233
	v_add_f32_e32 v147, v74, v234
	v_add_f32_e32 v155, v75, v235
	v_mul_f32_e32 v135, 0xbfb8aa3b, v135
	v_mul_f32_e32 v146, 0xbfb8aa3b, v146
	v_mul_f32_e32 v147, 0xbfb8aa3b, v147
	v_mul_f32_e32 v155, 0xbfb8aa3b, v155
	v_exp_f32_e32 v135, v135
	v_exp_f32_e32 v146, v146
	v_exp_f32_e32 v147, v147
	v_exp_f32_e32 v155, v155
	v_add_f32_e32 v135, 1.0, v135
	v_add_f32_e32 v146, 1.0, v146
	v_add_f32_e32 v147, 1.0, v147
	v_add_f32_e32 v155, 1.0, v155
	v_rcp_f32_e32 v156, v135
	v_rcp_f32_e32 v157, v146
	v_rcp_f32_e32 v158, v147
	v_rcp_f32_e32 v159, v155
	global_store_dwordx4 v[142:143], v[156:159], off offset:512
	v_add_f32_e32 v135, v68, v236
	v_add_f32_e32 v146, v69, v237
	v_add_f32_e32 v147, v70, v238
	v_add_f32_e32 v155, v71, v239
	v_mul_f32_e32 v135, 0xbfb8aa3b, v135
	v_mul_f32_e32 v146, 0xbfb8aa3b, v146
	v_mul_f32_e32 v147, 0xbfb8aa3b, v147
	v_mul_f32_e32 v155, 0xbfb8aa3b, v155
	v_exp_f32_e32 v135, v135
	v_exp_f32_e32 v146, v146
	v_exp_f32_e32 v147, v147
	v_exp_f32_e32 v155, v155
	v_add_f32_e32 v135, 1.0, v135
	v_add_f32_e32 v146, 1.0, v146
	v_add_f32_e32 v147, 1.0, v147
	v_add_f32_e32 v155, 1.0, v155
	v_rcp_f32_e32 v156, v135
	v_rcp_f32_e32 v157, v146
	v_rcp_f32_e32 v158, v147
	v_rcp_f32_e32 v159, v155
	global_store_dwordx4 v[142:143], v[156:159], off offset:576
	v_add_f32_e32 v135, v64, v224
	v_add_f32_e32 v142, v65, v225
	v_add_f32_e32 v143, v66, v226
	v_add_f32_e32 v146, v67, v227
	v_mul_f32_e32 v135, 0xbfb8aa3b, v135
	v_mul_f32_e32 v142, 0xbfb8aa3b, v142
	v_mul_f32_e32 v143, 0xbfb8aa3b, v143
	v_mul_f32_e32 v146, 0xbfb8aa3b, v146
	v_exp_f32_e32 v135, v135
	v_exp_f32_e32 v142, v142
	v_exp_f32_e32 v143, v143
	v_exp_f32_e32 v146, v146
	v_add_f32_e32 v135, 1.0, v135
	v_add_f32_e32 v142, 1.0, v142
	v_add_f32_e32 v143, 1.0, v143
	v_add_f32_e32 v146, 1.0, v146
	v_rcp_f32_e32 v156, v135
	v_rcp_f32_e32 v157, v142
	v_rcp_f32_e32 v158, v143
	v_rcp_f32_e32 v159, v146
	v_add_co_u32_e32 v142, vcc, s37, v132
	s_nop 1
	v_addc_co_u32_e32 v143, vcc, 0, v133, vcc
	global_store_dwordx4 v[142:143], v[156:159], off
	v_add_f32_e32 v135, v60, v228
	v_add_f32_e32 v142, v61, v229
	v_add_f32_e32 v143, v62, v230
	v_add_f32_e32 v146, v63, v231
	v_mul_f32_e32 v135, 0xbfb8aa3b, v135
	v_mul_f32_e32 v142, 0xbfb8aa3b, v142
	v_mul_f32_e32 v143, 0xbfb8aa3b, v143
	v_mul_f32_e32 v146, 0xbfb8aa3b, v146
	v_exp_f32_e32 v135, v135
	v_exp_f32_e32 v142, v142
	v_exp_f32_e32 v143, v143
	v_exp_f32_e32 v146, v146
	v_add_f32_e32 v135, 1.0, v135
	v_add_f32_e32 v142, 1.0, v142
	v_add_f32_e32 v143, 1.0, v143
	v_add_f32_e32 v146, 1.0, v146
	v_rcp_f32_e32 v156, v135
	v_rcp_f32_e32 v157, v142
	v_rcp_f32_e32 v158, v143
	v_rcp_f32_e32 v159, v146
	v_lshl_add_u64 v[142:143], v[132:133], 0, s[38:39]
	global_store_dwordx4 v[142:143], v[156:159], off offset:64
	v_add_f32_e32 v135, v56, v232
	v_add_f32_e32 v146, v57, v233
	v_add_f32_e32 v147, v58, v234
	v_add_f32_e32 v155, v59, v235
	v_mul_f32_e32 v135, 0xbfb8aa3b, v135
	v_mul_f32_e32 v146, 0xbfb8aa3b, v146
	v_mul_f32_e32 v147, 0xbfb8aa3b, v147
	v_mul_f32_e32 v155, 0xbfb8aa3b, v155
	v_exp_f32_e32 v135, v135
	v_exp_f32_e32 v146, v146
	v_exp_f32_e32 v147, v147
	v_exp_f32_e32 v155, v155
	v_add_f32_e32 v135, 1.0, v135
	v_add_f32_e32 v146, 1.0, v146
	v_add_f32_e32 v147, 1.0, v147
	v_add_f32_e32 v155, 1.0, v155
	v_rcp_f32_e32 v156, v135
	v_rcp_f32_e32 v157, v146
	v_rcp_f32_e32 v158, v147
	v_rcp_f32_e32 v159, v155
	global_store_dwordx4 v[142:143], v[156:159], off offset:512
	v_add_f32_e32 v135, v52, v236
	v_add_f32_e32 v146, v53, v237
	v_add_f32_e32 v147, v54, v238
	v_add_f32_e32 v155, v55, v239
	v_mul_f32_e32 v135, 0xbfb8aa3b, v135
	v_mul_f32_e32 v146, 0xbfb8aa3b, v146
	v_mul_f32_e32 v147, 0xbfb8aa3b, v147
	v_mul_f32_e32 v155, 0xbfb8aa3b, v155
	v_exp_f32_e32 v135, v135
	v_exp_f32_e32 v146, v146
	v_exp_f32_e32 v147, v147
	v_exp_f32_e32 v155, v155
	v_add_f32_e32 v135, 1.0, v135
	v_add_f32_e32 v146, 1.0, v146
	v_add_f32_e32 v147, 1.0, v147
	v_add_f32_e32 v155, 1.0, v155
	v_rcp_f32_e32 v156, v135
	v_rcp_f32_e32 v157, v146
	v_rcp_f32_e32 v158, v147
	v_rcp_f32_e32 v159, v155
	global_store_dwordx4 v[142:143], v[156:159], off offset:576
	v_add_f32_e32 v135, v48, v224
	v_add_f32_e32 v142, v49, v225
	v_add_f32_e32 v143, v50, v226
	v_add_f32_e32 v146, v51, v227
	v_mul_f32_e32 v135, 0xbfb8aa3b, v135
	v_mul_f32_e32 v142, 0xbfb8aa3b, v142
	v_mul_f32_e32 v143, 0xbfb8aa3b, v143
	v_mul_f32_e32 v146, 0xbfb8aa3b, v146
	v_exp_f32_e32 v135, v135
	v_exp_f32_e32 v142, v142
	v_exp_f32_e32 v143, v143
	v_exp_f32_e32 v146, v146
	v_add_f32_e32 v135, 1.0, v135
	v_add_f32_e32 v142, 1.0, v142
	v_add_f32_e32 v143, 1.0, v143
	v_add_f32_e32 v146, 1.0, v146
	v_rcp_f32_e32 v156, v135
	v_rcp_f32_e32 v157, v142
	v_rcp_f32_e32 v158, v143
	v_rcp_f32_e32 v159, v146
	v_add_co_u32_e32 v142, vcc, s46, v132
	s_nop 1
	v_addc_co_u32_e32 v143, vcc, 0, v133, vcc
	global_store_dwordx4 v[142:143], v[156:159], off
	v_add_f32_e32 v135, v44, v228
	v_add_f32_e32 v142, v45, v229
	v_add_f32_e32 v143, v46, v230
	v_add_f32_e32 v146, v47, v231
	v_mul_f32_e32 v135, 0xbfb8aa3b, v135
	v_mul_f32_e32 v142, 0xbfb8aa3b, v142
	v_mul_f32_e32 v143, 0xbfb8aa3b, v143
	v_mul_f32_e32 v146, 0xbfb8aa3b, v146
	v_exp_f32_e32 v135, v135
	v_exp_f32_e32 v142, v142
	v_exp_f32_e32 v143, v143
	v_exp_f32_e32 v146, v146
	v_add_f32_e32 v135, 1.0, v135
	v_add_f32_e32 v142, 1.0, v142
	v_add_f32_e32 v143, 1.0, v143
	v_add_f32_e32 v146, 1.0, v146
	v_rcp_f32_e32 v156, v135
	v_rcp_f32_e32 v157, v142
	v_rcp_f32_e32 v158, v143
	v_rcp_f32_e32 v159, v146
	v_lshl_add_u64 v[142:143], v[132:133], 0, s[44:45]
	global_store_dwordx4 v[142:143], v[156:159], off offset:64
	v_add_f32_e32 v135, v40, v232
	v_add_f32_e32 v146, v41, v233
	v_add_f32_e32 v147, v42, v234
	v_add_f32_e32 v155, v43, v235
	v_mul_f32_e32 v135, 0xbfb8aa3b, v135
	v_mul_f32_e32 v146, 0xbfb8aa3b, v146
	v_mul_f32_e32 v147, 0xbfb8aa3b, v147
	v_mul_f32_e32 v155, 0xbfb8aa3b, v155
	v_exp_f32_e32 v135, v135
	v_exp_f32_e32 v146, v146
	v_exp_f32_e32 v147, v147
	v_exp_f32_e32 v155, v155
	v_add_f32_e32 v135, 1.0, v135
	v_add_f32_e32 v146, 1.0, v146
	v_add_f32_e32 v147, 1.0, v147
	v_add_f32_e32 v155, 1.0, v155
	v_rcp_f32_e32 v156, v135
	v_rcp_f32_e32 v157, v146
	v_rcp_f32_e32 v158, v147
	v_rcp_f32_e32 v159, v155
	global_store_dwordx4 v[142:143], v[156:159], off offset:512
	v_add_f32_e32 v135, v36, v236
	v_add_f32_e32 v146, v37, v237
	v_add_f32_e32 v147, v38, v238
	v_add_f32_e32 v155, v39, v239
	v_mul_f32_e32 v135, 0xbfb8aa3b, v135
	v_mul_f32_e32 v146, 0xbfb8aa3b, v146
	v_mul_f32_e32 v147, 0xbfb8aa3b, v147
	v_mul_f32_e32 v155, 0xbfb8aa3b, v155
	v_exp_f32_e32 v135, v135
	v_exp_f32_e32 v146, v146
	v_exp_f32_e32 v147, v147
	v_exp_f32_e32 v155, v155
	v_add_f32_e32 v135, 1.0, v135
	v_add_f32_e32 v146, 1.0, v146
	v_add_f32_e32 v147, 1.0, v147
	v_add_f32_e32 v155, 1.0, v155
	v_rcp_f32_e32 v156, v135
	v_rcp_f32_e32 v157, v146
	v_rcp_f32_e32 v158, v147
	v_rcp_f32_e32 v159, v155
	global_store_dwordx4 v[142:143], v[156:159], off offset:576
	v_add_f32_e32 v135, v30, v224
	v_add_f32_e32 v142, v31, v225
	v_add_f32_e32 v143, v32, v226
	v_add_f32_e32 v146, v33, v227
	v_mul_f32_e32 v135, 0xbfb8aa3b, v135
	v_mul_f32_e32 v142, 0xbfb8aa3b, v142
	v_mul_f32_e32 v143, 0xbfb8aa3b, v143
	v_mul_f32_e32 v146, 0xbfb8aa3b, v146
	v_exp_f32_e32 v135, v135
	v_exp_f32_e32 v142, v142
	v_exp_f32_e32 v143, v143
	v_exp_f32_e32 v146, v146
	v_add_f32_e32 v135, 1.0, v135
	v_add_f32_e32 v142, 1.0, v142
	v_add_f32_e32 v143, 1.0, v143
	v_add_f32_e32 v146, 1.0, v146
	v_rcp_f32_e32 v156, v135
	v_rcp_f32_e32 v157, v142
	v_rcp_f32_e32 v158, v143
	v_rcp_f32_e32 v159, v146
	v_add_co_u32_e32 v142, vcc, s47, v132
	s_nop 1
	v_addc_co_u32_e32 v143, vcc, 0, v133, vcc
	global_store_dwordx4 v[142:143], v[156:159], off
	v_add_f32_e32 v135, v26, v228
	v_add_f32_e32 v142, v27, v229
	v_add_f32_e32 v143, v28, v230
	v_add_f32_e32 v146, v29, v231
	v_mul_f32_e32 v135, 0xbfb8aa3b, v135
	v_mul_f32_e32 v142, 0xbfb8aa3b, v142
	v_mul_f32_e32 v143, 0xbfb8aa3b, v143
	v_mul_f32_e32 v146, 0xbfb8aa3b, v146
	v_exp_f32_e32 v135, v135
	v_exp_f32_e32 v142, v142
	v_exp_f32_e32 v143, v143
	v_exp_f32_e32 v146, v146
	v_add_f32_e32 v135, 1.0, v135
	v_add_f32_e32 v142, 1.0, v142
	v_add_f32_e32 v143, 1.0, v143
	v_add_f32_e32 v146, 1.0, v146
	v_rcp_f32_e32 v156, v135
	v_rcp_f32_e32 v157, v142
	v_rcp_f32_e32 v158, v143
	v_rcp_f32_e32 v159, v146
	v_lshl_add_u64 v[142:143], v[132:133], 0, s[48:49]
	global_store_dwordx4 v[142:143], v[156:159], off offset:64
	v_add_f32_e32 v135, v22, v232
	v_add_f32_e32 v146, v23, v233
	v_add_f32_e32 v147, v24, v234
	v_add_f32_e32 v155, v25, v235
	v_mul_f32_e32 v135, 0xbfb8aa3b, v135
	v_mul_f32_e32 v146, 0xbfb8aa3b, v146
	v_mul_f32_e32 v147, 0xbfb8aa3b, v147
	v_mul_f32_e32 v155, 0xbfb8aa3b, v155
	v_exp_f32_e32 v135, v135
	v_exp_f32_e32 v146, v146
	v_exp_f32_e32 v147, v147
	v_exp_f32_e32 v155, v155
	v_add_f32_e32 v135, 1.0, v135
	v_add_f32_e32 v146, 1.0, v146
	v_add_f32_e32 v147, 1.0, v147
	v_add_f32_e32 v155, 1.0, v155
	v_rcp_f32_e32 v156, v135
	v_rcp_f32_e32 v157, v146
	v_rcp_f32_e32 v158, v147
	v_rcp_f32_e32 v159, v155
	global_store_dwordx4 v[142:143], v[156:159], off offset:512
	v_add_f32_e32 v135, v18, v236
	v_add_f32_e32 v146, v19, v237
	v_add_f32_e32 v147, v20, v238
	v_add_f32_e32 v155, v21, v239
	v_mul_f32_e32 v135, 0xbfb8aa3b, v135
	v_mul_f32_e32 v146, 0xbfb8aa3b, v146
	v_mul_f32_e32 v147, 0xbfb8aa3b, v147
	v_mul_f32_e32 v155, 0xbfb8aa3b, v155
	v_exp_f32_e32 v135, v135
	v_exp_f32_e32 v146, v146
	v_exp_f32_e32 v147, v147
	v_exp_f32_e32 v155, v155
	v_add_f32_e32 v135, 1.0, v135
	v_add_f32_e32 v146, 1.0, v146
	v_add_f32_e32 v147, 1.0, v147
	v_add_f32_e32 v155, 1.0, v155
	v_rcp_f32_e32 v156, v135
	v_rcp_f32_e32 v157, v146
	v_rcp_f32_e32 v158, v147
	v_rcp_f32_e32 v159, v155
	global_store_dwordx4 v[142:143], v[156:159], off offset:576
	v_add_f32_e32 v135, v14, v224
	v_add_f32_e32 v142, v15, v225
	v_add_f32_e32 v143, v16, v226
	v_add_f32_e32 v146, v17, v227
	v_mul_f32_e32 v135, 0xbfb8aa3b, v135
	v_mul_f32_e32 v142, 0xbfb8aa3b, v142
	v_mul_f32_e32 v143, 0xbfb8aa3b, v143
	v_mul_f32_e32 v146, 0xbfb8aa3b, v146
	v_exp_f32_e32 v135, v135
	v_exp_f32_e32 v142, v142
	v_exp_f32_e32 v143, v143
	v_exp_f32_e32 v146, v146
	v_add_f32_e32 v135, 1.0, v135
	v_add_f32_e32 v142, 1.0, v142
	v_add_f32_e32 v143, 1.0, v143
	v_add_f32_e32 v146, 1.0, v146
	v_rcp_f32_e32 v156, v135
	v_rcp_f32_e32 v157, v142
	v_rcp_f32_e32 v158, v143
	v_rcp_f32_e32 v159, v146
	v_add_co_u32_e32 v142, vcc, s68, v132
	s_nop 1
	v_addc_co_u32_e32 v143, vcc, 0, v133, vcc
	global_store_dwordx4 v[142:143], v[156:159], off
	v_lshl_add_u64 v[132:133], v[132:133], 0, s[4:5]
	v_add_f32_e32 v135, v10, v228
	v_add_f32_e32 v142, v11, v229
	v_add_f32_e32 v143, v12, v230
	v_add_f32_e32 v146, v13, v231
	v_mul_f32_e32 v135, 0xbfb8aa3b, v135
	v_mul_f32_e32 v142, 0xbfb8aa3b, v142
	v_mul_f32_e32 v143, 0xbfb8aa3b, v143
	v_mul_f32_e32 v146, 0xbfb8aa3b, v146
	v_exp_f32_e32 v135, v135
	v_exp_f32_e32 v142, v142
	v_exp_f32_e32 v143, v143
	v_exp_f32_e32 v146, v146
	v_add_f32_e32 v135, 1.0, v135
	v_add_f32_e32 v142, 1.0, v142
	v_add_f32_e32 v143, 1.0, v143
	v_add_f32_e32 v146, 1.0, v146
	v_rcp_f32_e32 v156, v135
	v_rcp_f32_e32 v157, v142
	v_rcp_f32_e32 v158, v143
	v_rcp_f32_e32 v159, v146
	global_store_dwordx4 v[132:133], v[156:159], off offset:64
	v_add_f32_e32 v135, v6, v232
	v_add_f32_e32 v142, v7, v233
	v_add_f32_e32 v143, v8, v234
	v_add_f32_e32 v146, v9, v235
	v_mul_f32_e32 v135, 0xbfb8aa3b, v135
	v_mul_f32_e32 v142, 0xbfb8aa3b, v142
	v_mul_f32_e32 v143, 0xbfb8aa3b, v143
	v_mul_f32_e32 v146, 0xbfb8aa3b, v146
	v_exp_f32_e32 v135, v135
	v_exp_f32_e32 v142, v142
	v_exp_f32_e32 v143, v143
	v_exp_f32_e32 v146, v146
	v_add_f32_e32 v135, 1.0, v135
	v_add_f32_e32 v142, 1.0, v142
	v_add_f32_e32 v143, 1.0, v143
	v_add_f32_e32 v146, 1.0, v146
	v_rcp_f32_e32 v156, v135
	v_rcp_f32_e32 v157, v142
	v_rcp_f32_e32 v158, v143
	v_rcp_f32_e32 v159, v146
	global_store_dwordx4 v[132:133], v[156:159], off offset:512
	v_add_f32_e32 v135, v2, v236
	v_add_f32_e32 v140, v3, v237
	v_add_f32_e32 v142, v4, v238
	v_add_f32_e32 v143, v5, v239
	v_mul_f32_e32 v135, 0xbfb8aa3b, v135
	v_mul_f32_e32 v140, 0xbfb8aa3b, v140
	v_mul_f32_e32 v142, 0xbfb8aa3b, v142
	v_mul_f32_e32 v143, 0xbfb8aa3b, v143
	v_exp_f32_e32 v135, v135
	v_exp_f32_e32 v140, v140
	v_exp_f32_e32 v142, v142
	v_exp_f32_e32 v143, v143
	v_add_f32_e32 v135, 1.0, v135
	v_add_f32_e32 v140, 1.0, v140
	v_add_f32_e32 v142, 1.0, v142
	v_add_f32_e32 v143, 1.0, v143
	v_rcp_f32_e32 v156, v135
	v_rcp_f32_e32 v157, v140
	v_rcp_f32_e32 v158, v142
	v_rcp_f32_e32 v159, v143
	global_store_dwordx4 v[132:133], v[156:159], off offset:576

.LBB0_796:
	s_andn2_b64 vcc, exec, s[8:9]
	s_cbranch_vccnz .LBB0_779
	v_lshlrev_b64 v[132:133], 12, v[148:149]
	v_lshl_add_u64 v[132:133], s[12:13], 0, v[132:133]
	v_lshlrev_b32_e32 v140, 2, v134
	v_lshl_add_u64 v[146:147], v[132:133], 0, v[140:141]
	global_load_dwordx4 v[224:227], v140, s[60:61]
	global_load_dwordx4 v[228:231], v140, s[60:61] offset:64
	global_load_dwordx4 v[232:235], v140, s[60:61] offset:512
	global_load_dwordx4 v[236:239], v140, s[60:61] offset:576
	s_waitcnt vmcnt(0)
	v_add_f32_e32 v128, v128, v224
	v_max_f32_e64 v132, -v128, 0
	v_mul_f32_e64 v128, |v128|, s86
	v_exp_f32_e32 v128, v128
	v_add_f32_e32 v129, v129, v225
	v_add_f32_e32 v130, v130, v226
	v_add_f32_e32 v131, v131, v227
	v_add_f32_e32 v128, 1.0, v128
	v_cmp_gt_f32_e32 vcc, s30, v128
	s_nop 1
	v_cndmask_b32_e64 v142, 0, 32, vcc
	v_ldexp_f32 v128, v128, v142
	v_log_f32_e32 v128, v128
	s_nop 0
	v_mul_f32_e32 v142, 0x3f317217, v128
	v_fma_f32 v142, v128, s24, -v142
	v_fmac_f32_e32 v142, 0x3377d1cf, v128
	v_fmac_f32_e32 v142, 0x3f317217, v128
	v_cmp_lt_f32_e64 s[8:9], |v128|, s25
	s_nop 1
	v_cndmask_b32_e64 v128, v128, v142, s[8:9]
	v_cndmask_b32_e32 v142, 0, v154, vcc
	v_sub_f32_e32 v128, v128, v142
	v_add_f32_e32 v128, v132, v128
	v_max_f32_e64 v132, -v129, 0
	v_mul_f32_e64 v129, |v129|, s86
	v_exp_f32_e32 v129, v129
	v_sub_f32_e32 v128, -0.5, v128
	v_mul_f32_e32 v128, 0x3fb8aa3b, v128
	v_exp_f32_e32 v128, v128
	v_add_f32_e32 v129, 1.0, v129
	v_cmp_gt_f32_e32 vcc, s30, v129
	v_mul_f32_e32 v128, 0xbfb8aa3b, v128
	s_nop 0
	v_cndmask_b32_e64 v133, 0, 32, vcc
	v_ldexp_f32 v129, v129, v133
	v_log_f32_e32 v129, v129
	v_exp_f32_e32 v128, v128
	v_mul_f32_e32 v133, 0x3f317217, v129
	v_fma_f32 v133, v129, s24, -v133
	v_fmac_f32_e32 v133, 0x3377d1cf, v129
	v_fmac_f32_e32 v133, 0x3f317217, v129
	v_cmp_lt_f32_e64 s[8:9], |v129|, s25
	s_nop 1
	v_cndmask_b32_e64 v129, v129, v133, s[8:9]
	v_cndmask_b32_e32 v133, 0, v154, vcc
	v_sub_f32_e32 v129, v129, v133
	v_add_f32_e32 v129, v132, v129
	v_max_f32_e64 v132, -v130, 0
	v_mul_f32_e64 v130, |v130|, s86
	v_exp_f32_e32 v130, v130
	v_sub_f32_e32 v129, -0.5, v129
	v_mul_f32_e32 v129, 0x3fb8aa3b, v129
	v_exp_f32_e32 v129, v129
	v_add_f32_e32 v130, 1.0, v130
	v_cmp_gt_f32_e32 vcc, s30, v130
	v_mul_f32_e32 v129, 0xbfb8aa3b, v129
	s_nop 0
	v_cndmask_b32_e64 v133, 0, 32, vcc
	v_ldexp_f32 v130, v130, v133
	v_log_f32_e32 v130, v130
	v_exp_f32_e32 v129, v129
	v_mul_f32_e32 v133, 0x3f317217, v130
	v_fma_f32 v133, v130, s24, -v133
	v_fmac_f32_e32 v133, 0x3377d1cf, v130
	v_fmac_f32_e32 v133, 0x3f317217, v130
	v_cmp_lt_f32_e64 s[8:9], |v130|, s25
	s_nop 1
	v_cndmask_b32_e64 v130, v130, v133, s[8:9]
	v_cndmask_b32_e32 v133, 0, v154, vcc
	v_sub_f32_e32 v130, v130, v133
	v_add_f32_e32 v130, v132, v130
	v_max_f32_e64 v132, -v131, 0
	v_mul_f32_e64 v131, |v131|, s86
	v_exp_f32_e32 v131, v131
	v_sub_f32_e32 v130, -0.5, v130
	v_mul_f32_e32 v130, 0x3fb8aa3b, v130
	v_exp_f32_e32 v130, v130
	v_add_f32_e32 v131, 1.0, v131
	v_cmp_gt_f32_e32 vcc, s30, v131
	v_mul_f32_e32 v130, 0xbfb8aa3b, v130
	s_nop 0
	v_cndmask_b32_e64 v133, 0, 32, vcc
	v_ldexp_f32 v131, v131, v133
	v_log_f32_e32 v131, v131
	v_exp_f32_e32 v130, v130
	v_mul_f32_e32 v133, 0x3f317217, v131
	v_fma_f32 v133, v131, s24, -v133
	v_fmac_f32_e32 v133, 0x3377d1cf, v131
	v_fmac_f32_e32 v133, 0x3f317217, v131
	v_cmp_lt_f32_e64 s[8:9], |v131|, s25
	s_nop 1
	v_cndmask_b32_e64 v131, v131, v133, s[8:9]
	v_cndmask_b32_e32 v133, 0, v154, vcc
	v_sub_f32_e32 v131, v131, v133
	v_add_f32_e32 v131, v132, v131
	v_sub_f32_e32 v131, -0.5, v131
	v_mul_f32_e32 v131, 0x3fb8aa3b, v131
	v_exp_f32_e32 v131, v131
	s_nop 0
	v_mul_f32_e32 v131, 0xbfb8aa3b, v131
	v_exp_f32_e32 v131, v131
	global_store_dwordx4 v[146:147], v[128:131], off
	v_add_f32_e32 v124, v124, v228
	v_max_f32_e64 v128, -v124, 0
	v_mul_f32_e64 v124, |v124|, s86
	v_exp_f32_e32 v124, v124
	v_add_f32_e32 v125, v125, v229
	v_add_f32_e32 v126, v126, v230
	v_add_f32_e32 v127, v127, v231
	v_add_f32_e32 v124, 1.0, v124
	v_cmp_gt_f32_e32 vcc, s30, v124
	s_nop 1
	v_cndmask_b32_e64 v132, 0, 32, vcc
	v_ldexp_f32 v124, v124, v132
	v_log_f32_e32 v124, v124
	s_nop 0
	v_mul_f32_e32 v132, 0x3f317217, v124
	v_fma_f32 v132, v124, s24, -v132
	v_fmac_f32_e32 v132, 0x3377d1cf, v124
	v_fmac_f32_e32 v132, 0x3f317217, v124
	v_cmp_lt_f32_e64 s[8:9], |v124|, s25
	s_nop 1
	v_cndmask_b32_e64 v124, v124, v132, s[8:9]
	v_cndmask_b32_e32 v132, 0, v154, vcc
	v_sub_f32_e32 v124, v124, v132
	v_add_f32_e32 v124, v128, v124
	v_max_f32_e64 v128, -v125, 0
	v_mul_f32_e64 v125, |v125|, s86
	v_exp_f32_e32 v125, v125
	v_sub_f32_e32 v124, -0.5, v124
	v_mul_f32_e32 v124, 0x3fb8aa3b, v124
	v_exp_f32_e32 v124, v124
	v_add_f32_e32 v125, 1.0, v125
	v_cmp_gt_f32_e32 vcc, s30, v125
	v_mul_f32_e32 v124, 0xbfb8aa3b, v124
	s_nop 0
	v_cndmask_b32_e64 v129, 0, 32, vcc
	v_ldexp_f32 v125, v125, v129
	v_log_f32_e32 v125, v125
	v_exp_f32_e32 v124, v124
	v_mul_f32_e32 v129, 0x3f317217, v125
	v_fma_f32 v129, v125, s24, -v129
	v_fmac_f32_e32 v129, 0x3377d1cf, v125
	v_fmac_f32_e32 v129, 0x3f317217, v125
	v_cmp_lt_f32_e64 s[8:9], |v125|, s25
	s_nop 1
	v_cndmask_b32_e64 v125, v125, v129, s[8:9]
	v_cndmask_b32_e32 v129, 0, v154, vcc
	v_sub_f32_e32 v125, v125, v129
	v_add_f32_e32 v125, v128, v125
	v_max_f32_e64 v128, -v126, 0
	v_mul_f32_e64 v126, |v126|, s86
	v_exp_f32_e32 v126, v126
	v_sub_f32_e32 v125, -0.5, v125
	v_mul_f32_e32 v125, 0x3fb8aa3b, v125
	v_exp_f32_e32 v125, v125
	v_add_f32_e32 v126, 1.0, v126
	v_cmp_gt_f32_e32 vcc, s30, v126
	v_mul_f32_e32 v125, 0xbfb8aa3b, v125
	s_nop 0
	v_cndmask_b32_e64 v129, 0, 32, vcc
	v_ldexp_f32 v126, v126, v129
	v_log_f32_e32 v126, v126
	v_exp_f32_e32 v125, v125
	v_mul_f32_e32 v129, 0x3f317217, v126
	v_fma_f32 v129, v126, s24, -v129
	v_fmac_f32_e32 v129, 0x3377d1cf, v126
	v_fmac_f32_e32 v129, 0x3f317217, v126
	v_cmp_lt_f32_e64 s[8:9], |v126|, s25
	s_nop 1
	v_cndmask_b32_e64 v126, v126, v129, s[8:9]
	v_cndmask_b32_e32 v129, 0, v154, vcc
	v_sub_f32_e32 v126, v126, v129
	v_add_f32_e32 v126, v128, v126
	v_max_f32_e64 v128, -v127, 0
	v_mul_f32_e64 v127, |v127|, s86
	v_exp_f32_e32 v127, v127
	v_sub_f32_e32 v126, -0.5, v126
	v_mul_f32_e32 v126, 0x3fb8aa3b, v126
	v_exp_f32_e32 v126, v126
	v_add_f32_e32 v127, 1.0, v127
	v_cmp_gt_f32_e32 vcc, s30, v127
	v_mul_f32_e32 v126, 0xbfb8aa3b, v126
	s_nop 0
	v_cndmask_b32_e64 v129, 0, 32, vcc
	v_ldexp_f32 v127, v127, v129
	v_log_f32_e32 v127, v127
	v_exp_f32_e32 v126, v126
	v_mul_f32_e32 v129, 0x3f317217, v127
	v_fma_f32 v129, v127, s24, -v129
	v_fmac_f32_e32 v129, 0x3377d1cf, v127
	v_fmac_f32_e32 v129, 0x3f317217, v127
	v_cmp_lt_f32_e64 s[8:9], |v127|, s25
	s_nop 1
	v_cndmask_b32_e64 v127, v127, v129, s[8:9]
	v_cndmask_b32_e32 v129, 0, v154, vcc
	v_sub_f32_e32 v127, v127, v129
	v_add_f32_e32 v127, v128, v127
	v_sub_f32_e32 v127, -0.5, v127
	v_mul_f32_e32 v127, 0x3fb8aa3b, v127
	v_exp_f32_e32 v127, v127
	s_nop 0
	v_mul_f32_e32 v127, 0xbfb8aa3b, v127
	v_exp_f32_e32 v127, v127
	global_store_dwordx4 v[146:147], v[124:127], off offset:64
	v_add_f32_e32 v120, v120, v232
	v_max_f32_e64 v124, -v120, 0
	v_mul_f32_e64 v120, |v120|, s86
	v_exp_f32_e32 v120, v120
	v_add_f32_e32 v121, v121, v233
	v_add_f32_e32 v122, v122, v234
	v_add_f32_e32 v123, v123, v235
	v_add_f32_e32 v120, 1.0, v120
	v_cmp_gt_f32_e32 vcc, s30, v120
	s_nop 1
	v_cndmask_b32_e64 v128, 0, 32, vcc
	v_ldexp_f32 v120, v120, v128
	v_log_f32_e32 v120, v120
	s_nop 0
	v_mul_f32_e32 v128, 0x3f317217, v120
	v_fma_f32 v128, v120, s24, -v128
	v_fmac_f32_e32 v128, 0x3377d1cf, v120
	v_fmac_f32_e32 v128, 0x3f317217, v120
	v_cmp_lt_f32_e64 s[8:9], |v120|, s25
	s_nop 1
	v_cndmask_b32_e64 v120, v120, v128, s[8:9]
	v_cndmask_b32_e32 v128, 0, v154, vcc
	v_sub_f32_e32 v120, v120, v128
	v_add_f32_e32 v120, v124, v120
	v_max_f32_e64 v124, -v121, 0
	v_mul_f32_e64 v121, |v121|, s86
	v_exp_f32_e32 v121, v121
	v_sub_f32_e32 v120, -0.5, v120
	v_mul_f32_e32 v120, 0x3fb8aa3b, v120
	v_exp_f32_e32 v120, v120
	v_add_f32_e32 v121, 1.0, v121
	v_cmp_gt_f32_e32 vcc, s30, v121
	v_mul_f32_e32 v120, 0xbfb8aa3b, v120
	s_nop 0
	v_cndmask_b32_e64 v125, 0, 32, vcc
	v_ldexp_f32 v121, v121, v125
	v_log_f32_e32 v121, v121
	v_exp_f32_e32 v120, v120
	v_mul_f32_e32 v125, 0x3f317217, v121
	v_fma_f32 v125, v121, s24, -v125
	v_fmac_f32_e32 v125, 0x3377d1cf, v121
	v_fmac_f32_e32 v125, 0x3f317217, v121
	v_cmp_lt_f32_e64 s[8:9], |v121|, s25
	s_nop 1
	v_cndmask_b32_e64 v121, v121, v125, s[8:9]
	v_cndmask_b32_e32 v125, 0, v154, vcc
	v_sub_f32_e32 v121, v121, v125
	v_add_f32_e32 v121, v124, v121
	v_max_f32_e64 v124, -v122, 0
	v_mul_f32_e64 v122, |v122|, s86
	v_exp_f32_e32 v122, v122
	v_sub_f32_e32 v121, -0.5, v121
	v_mul_f32_e32 v121, 0x3fb8aa3b, v121
	v_exp_f32_e32 v121, v121
	v_add_f32_e32 v122, 1.0, v122
	v_cmp_gt_f32_e32 vcc, s30, v122
	v_mul_f32_e32 v121, 0xbfb8aa3b, v121
	s_nop 0
	v_cndmask_b32_e64 v125, 0, 32, vcc
	v_ldexp_f32 v122, v122, v125
	v_log_f32_e32 v122, v122
	v_exp_f32_e32 v121, v121
	v_mul_f32_e32 v125, 0x3f317217, v122
	v_fma_f32 v125, v122, s24, -v125
	v_fmac_f32_e32 v125, 0x3377d1cf, v122
	v_fmac_f32_e32 v125, 0x3f317217, v122
	v_cmp_lt_f32_e64 s[8:9], |v122|, s25
	s_nop 1
	v_cndmask_b32_e64 v122, v122, v125, s[8:9]
	v_cndmask_b32_e32 v125, 0, v154, vcc
	v_sub_f32_e32 v122, v122, v125
	v_add_f32_e32 v122, v124, v122
	v_max_f32_e64 v124, -v123, 0
	v_mul_f32_e64 v123, |v123|, s86
	v_exp_f32_e32 v123, v123
	v_sub_f32_e32 v122, -0.5, v122
	v_mul_f32_e32 v122, 0x3fb8aa3b, v122
	v_exp_f32_e32 v122, v122
	v_add_f32_e32 v123, 1.0, v123
	v_cmp_gt_f32_e32 vcc, s30, v123
	v_mul_f32_e32 v122, 0xbfb8aa3b, v122
	s_nop 0
	v_cndmask_b32_e64 v125, 0, 32, vcc
	v_ldexp_f32 v123, v123, v125
	v_log_f32_e32 v123, v123
	v_exp_f32_e32 v122, v122
	v_mul_f32_e32 v125, 0x3f317217, v123
	v_fma_f32 v125, v123, s24, -v125
	v_fmac_f32_e32 v125, 0x3377d1cf, v123
	v_fmac_f32_e32 v125, 0x3f317217, v123
	v_cmp_lt_f32_e64 s[8:9], |v123|, s25
	s_nop 1
	v_cndmask_b32_e64 v123, v123, v125, s[8:9]
	v_cndmask_b32_e32 v125, 0, v154, vcc
	v_sub_f32_e32 v123, v123, v125
	v_add_f32_e32 v123, v124, v123
	v_sub_f32_e32 v123, -0.5, v123
	v_mul_f32_e32 v123, 0x3fb8aa3b, v123
	v_exp_f32_e32 v123, v123
	s_nop 0
	v_mul_f32_e32 v123, 0xbfb8aa3b, v123
	v_exp_f32_e32 v123, v123
	global_store_dwordx4 v[146:147], v[120:123], off offset:512
	v_add_f32_e32 v116, v116, v236
	v_max_f32_e64 v120, -v116, 0
	v_mul_f32_e64 v116, |v116|, s86
	v_exp_f32_e32 v116, v116
	v_add_f32_e32 v117, v117, v237
	v_add_f32_e32 v118, v118, v238
	v_add_f32_e32 v119, v119, v239
	v_add_f32_e32 v116, 1.0, v116
	v_cmp_gt_f32_e32 vcc, s30, v116
	s_nop 1
	v_cndmask_b32_e64 v124, 0, 32, vcc
	v_ldexp_f32 v116, v116, v124
	v_log_f32_e32 v116, v116
	s_nop 0
	v_mul_f32_e32 v124, 0x3f317217, v116
	v_fma_f32 v124, v116, s24, -v124
	v_fmac_f32_e32 v124, 0x3377d1cf, v116
	v_fmac_f32_e32 v124, 0x3f317217, v116
	v_cmp_lt_f32_e64 s[8:9], |v116|, s25
	s_nop 1
	v_cndmask_b32_e64 v116, v116, v124, s[8:9]
	v_cndmask_b32_e32 v124, 0, v154, vcc
	v_sub_f32_e32 v116, v116, v124
	v_add_f32_e32 v116, v120, v116
	v_max_f32_e64 v120, -v117, 0
	v_mul_f32_e64 v117, |v117|, s86
	v_exp_f32_e32 v117, v117
	v_sub_f32_e32 v116, -0.5, v116
	v_mul_f32_e32 v116, 0x3fb8aa3b, v116
	v_exp_f32_e32 v116, v116
	v_add_f32_e32 v117, 1.0, v117
	v_cmp_gt_f32_e32 vcc, s30, v117
	v_mul_f32_e32 v116, 0xbfb8aa3b, v116
	s_nop 0
	v_cndmask_b32_e64 v121, 0, 32, vcc
	v_ldexp_f32 v117, v117, v121
	v_log_f32_e32 v117, v117
	v_exp_f32_e32 v116, v116
	v_mul_f32_e32 v121, 0x3f317217, v117
	v_fma_f32 v121, v117, s24, -v121
	v_fmac_f32_e32 v121, 0x3377d1cf, v117
	v_fmac_f32_e32 v121, 0x3f317217, v117
	v_cmp_lt_f32_e64 s[8:9], |v117|, s25
	s_nop 1
	v_cndmask_b32_e64 v117, v117, v121, s[8:9]
	v_cndmask_b32_e32 v121, 0, v154, vcc
	v_sub_f32_e32 v117, v117, v121
	v_add_f32_e32 v117, v120, v117
	v_max_f32_e64 v120, -v118, 0
	v_mul_f32_e64 v118, |v118|, s86
	v_exp_f32_e32 v118, v118
	v_sub_f32_e32 v117, -0.5, v117
	v_mul_f32_e32 v117, 0x3fb8aa3b, v117
	v_exp_f32_e32 v117, v117
	v_add_f32_e32 v118, 1.0, v118
	v_cmp_gt_f32_e32 vcc, s30, v118
	v_mul_f32_e32 v117, 0xbfb8aa3b, v117
	s_nop 0
	v_cndmask_b32_e64 v121, 0, 32, vcc
	v_ldexp_f32 v118, v118, v121
	v_log_f32_e32 v118, v118
	v_exp_f32_e32 v117, v117
	v_mul_f32_e32 v121, 0x3f317217, v118
	v_fma_f32 v121, v118, s24, -v121
	v_fmac_f32_e32 v121, 0x3377d1cf, v118
	v_fmac_f32_e32 v121, 0x3f317217, v118
	v_cmp_lt_f32_e64 s[8:9], |v118|, s25
	s_nop 1
	v_cndmask_b32_e64 v118, v118, v121, s[8:9]
	v_cndmask_b32_e32 v121, 0, v154, vcc
	v_sub_f32_e32 v118, v118, v121
	v_add_f32_e32 v118, v120, v118
	v_max_f32_e64 v120, -v119, 0
	v_mul_f32_e64 v119, |v119|, s86
	v_exp_f32_e32 v119, v119
	v_sub_f32_e32 v118, -0.5, v118
	v_mul_f32_e32 v118, 0x3fb8aa3b, v118
	v_exp_f32_e32 v118, v118
	v_add_f32_e32 v119, 1.0, v119
	v_cmp_gt_f32_e32 vcc, s30, v119
	v_mul_f32_e32 v118, 0xbfb8aa3b, v118
	s_nop 0
	v_cndmask_b32_e64 v121, 0, 32, vcc
	v_ldexp_f32 v119, v119, v121
	v_log_f32_e32 v119, v119
	v_exp_f32_e32 v118, v118
	v_mul_f32_e32 v121, 0x3f317217, v119
	v_fma_f32 v121, v119, s24, -v121
	v_fmac_f32_e32 v121, 0x3377d1cf, v119
	v_fmac_f32_e32 v121, 0x3f317217, v119
	v_cmp_lt_f32_e64 s[8:9], |v119|, s25
	s_nop 1
	v_cndmask_b32_e64 v119, v119, v121, s[8:9]
	v_cndmask_b32_e32 v121, 0, v154, vcc
	v_sub_f32_e32 v119, v119, v121
	v_add_f32_e32 v119, v120, v119
	v_sub_f32_e32 v119, -0.5, v119
	v_mul_f32_e32 v119, 0x3fb8aa3b, v119
	v_exp_f32_e32 v119, v119
	s_nop 0
	v_mul_f32_e32 v119, 0xbfb8aa3b, v119
	v_exp_f32_e32 v119, v119
	global_store_dwordx4 v[146:147], v[116:119], off offset:576
	s_nop 1
	v_or_b32_e32 v116, 16, v148
	v_ashrrev_i32_e32 v117, 31, v116
	v_lshlrev_b64 v[116:117], 12, v[116:117]
	v_lshl_add_u64 v[116:117], s[12:13], 0, v[116:117]
	v_lshl_add_u64 v[120:121], v[116:117], 0, v[140:141]
	v_add_f32_e32 v112, v112, v224
	v_max_f32_e64 v116, -v112, 0
	v_mul_f32_e64 v112, |v112|, s86
	v_exp_f32_e32 v112, v112
	v_add_f32_e32 v113, v113, v225
	v_add_f32_e32 v114, v114, v226
	v_add_f32_e32 v115, v115, v227
	v_add_f32_e32 v112, 1.0, v112
	v_cmp_gt_f32_e32 vcc, s30, v112
	s_nop 1
	v_cndmask_b32_e64 v122, 0, 32, vcc
	v_ldexp_f32 v112, v112, v122
	v_log_f32_e32 v112, v112
	s_nop 0
	v_mul_f32_e32 v122, 0x3f317217, v112
	v_fma_f32 v122, v112, s24, -v122
	v_fmac_f32_e32 v122, 0x3377d1cf, v112
	v_fmac_f32_e32 v122, 0x3f317217, v112
	v_cmp_lt_f32_e64 s[8:9], |v112|, s25
	s_nop 1
	v_cndmask_b32_e64 v112, v112, v122, s[8:9]
	v_cndmask_b32_e32 v122, 0, v154, vcc
	v_sub_f32_e32 v112, v112, v122
	v_add_f32_e32 v112, v116, v112
	v_max_f32_e64 v116, -v113, 0
	v_mul_f32_e64 v113, |v113|, s86
	v_exp_f32_e32 v113, v113
	v_sub_f32_e32 v112, -0.5, v112
	v_mul_f32_e32 v112, 0x3fb8aa3b, v112
	v_exp_f32_e32 v112, v112
	v_add_f32_e32 v113, 1.0, v113
	v_cmp_gt_f32_e32 vcc, s30, v113
	v_mul_f32_e32 v112, 0xbfb8aa3b, v112
	s_nop 0
	v_cndmask_b32_e64 v117, 0, 32, vcc
	v_ldexp_f32 v113, v113, v117
	v_log_f32_e32 v113, v113
	v_exp_f32_e32 v112, v112
	v_mul_f32_e32 v117, 0x3f317217, v113
	v_fma_f32 v117, v113, s24, -v117
	v_fmac_f32_e32 v117, 0x3377d1cf, v113
	v_fmac_f32_e32 v117, 0x3f317217, v113
	v_cmp_lt_f32_e64 s[8:9], |v113|, s25
	s_nop 1
	v_cndmask_b32_e64 v113, v113, v117, s[8:9]
	v_cndmask_b32_e32 v117, 0, v154, vcc
	v_sub_f32_e32 v113, v113, v117
	v_add_f32_e32 v113, v116, v113
	v_max_f32_e64 v116, -v114, 0
	v_mul_f32_e64 v114, |v114|, s86
	v_exp_f32_e32 v114, v114
	v_sub_f32_e32 v113, -0.5, v113
	v_mul_f32_e32 v113, 0x3fb8aa3b, v113
	v_exp_f32_e32 v113, v113
	v_add_f32_e32 v114, 1.0, v114
	v_cmp_gt_f32_e32 vcc, s30, v114
	v_mul_f32_e32 v113, 0xbfb8aa3b, v113
	s_nop 0
	v_cndmask_b32_e64 v117, 0, 32, vcc
	v_ldexp_f32 v114, v114, v117
	v_log_f32_e32 v114, v114
	v_exp_f32_e32 v113, v113
	v_mul_f32_e32 v117, 0x3f317217, v114
	v_fma_f32 v117, v114, s24, -v117
	v_fmac_f32_e32 v117, 0x3377d1cf, v114
	v_fmac_f32_e32 v117, 0x3f317217, v114
	v_cmp_lt_f32_e64 s[8:9], |v114|, s25
	s_nop 1
	v_cndmask_b32_e64 v114, v114, v117, s[8:9]
	v_cndmask_b32_e32 v117, 0, v154, vcc
	v_sub_f32_e32 v114, v114, v117
	v_add_f32_e32 v114, v116, v114
	v_max_f32_e64 v116, -v115, 0
	v_mul_f32_e64 v115, |v115|, s86
	v_exp_f32_e32 v115, v115
	v_sub_f32_e32 v114, -0.5, v114
	v_mul_f32_e32 v114, 0x3fb8aa3b, v114
	v_exp_f32_e32 v114, v114
	v_add_f32_e32 v115, 1.0, v115
	v_cmp_gt_f32_e32 vcc, s30, v115
	v_mul_f32_e32 v114, 0xbfb8aa3b, v114
	s_nop 0
	v_cndmask_b32_e64 v117, 0, 32, vcc
	v_ldexp_f32 v115, v115, v117
	v_log_f32_e32 v115, v115
	v_exp_f32_e32 v114, v114
	v_mul_f32_e32 v117, 0x3f317217, v115
	v_fma_f32 v117, v115, s24, -v117
	v_fmac_f32_e32 v117, 0x3377d1cf, v115
	v_fmac_f32_e32 v117, 0x3f317217, v115
	v_cmp_lt_f32_e64 s[8:9], |v115|, s25
	s_nop 1
	v_cndmask_b32_e64 v115, v115, v117, s[8:9]
	v_cndmask_b32_e32 v117, 0, v154, vcc
	v_sub_f32_e32 v115, v115, v117
	v_add_f32_e32 v115, v116, v115
	v_sub_f32_e32 v115, -0.5, v115
	v_mul_f32_e32 v115, 0x3fb8aa3b, v115
	v_exp_f32_e32 v115, v115
	s_nop 0
	v_mul_f32_e32 v115, 0xbfb8aa3b, v115
	v_exp_f32_e32 v115, v115
	global_store_dwordx4 v[120:121], v[112:115], off
	v_add_f32_e32 v108, v108, v228
	v_max_f32_e64 v112, -v108, 0
	v_mul_f32_e64 v108, |v108|, s86
	v_exp_f32_e32 v108, v108
	v_add_f32_e32 v109, v109, v229
	v_add_f32_e32 v110, v110, v230
	v_add_f32_e32 v111, v111, v231
	v_add_f32_e32 v108, 1.0, v108
	v_cmp_gt_f32_e32 vcc, s30, v108
	s_nop 1
	v_cndmask_b32_e64 v116, 0, 32, vcc
	v_ldexp_f32 v108, v108, v116
	v_log_f32_e32 v108, v108
	s_nop 0
	v_mul_f32_e32 v116, 0x3f317217, v108
	v_fma_f32 v116, v108, s24, -v116
	v_fmac_f32_e32 v116, 0x3377d1cf, v108
	v_fmac_f32_e32 v116, 0x3f317217, v108
	v_cmp_lt_f32_e64 s[8:9], |v108|, s25
	s_nop 1
	v_cndmask_b32_e64 v108, v108, v116, s[8:9]
	v_cndmask_b32_e32 v116, 0, v154, vcc
	v_sub_f32_e32 v108, v108, v116
	v_add_f32_e32 v108, v112, v108
	v_max_f32_e64 v112, -v109, 0
	v_mul_f32_e64 v109, |v109|, s86
	v_exp_f32_e32 v109, v109
	v_sub_f32_e32 v108, -0.5, v108
	v_mul_f32_e32 v108, 0x3fb8aa3b, v108
	v_exp_f32_e32 v108, v108
	v_add_f32_e32 v109, 1.0, v109
	v_cmp_gt_f32_e32 vcc, s30, v109
	v_mul_f32_e32 v108, 0xbfb8aa3b, v108
	s_nop 0
	v_cndmask_b32_e64 v113, 0, 32, vcc
	v_ldexp_f32 v109, v109, v113
	v_log_f32_e32 v109, v109
	v_exp_f32_e32 v108, v108
	v_mul_f32_e32 v113, 0x3f317217, v109
	v_fma_f32 v113, v109, s24, -v113
	v_fmac_f32_e32 v113, 0x3377d1cf, v109
	v_fmac_f32_e32 v113, 0x3f317217, v109
	v_cmp_lt_f32_e64 s[8:9], |v109|, s25
	s_nop 1
	v_cndmask_b32_e64 v109, v109, v113, s[8:9]
	v_cndmask_b32_e32 v113, 0, v154, vcc
	v_sub_f32_e32 v109, v109, v113
	v_add_f32_e32 v109, v112, v109
	v_max_f32_e64 v112, -v110, 0
	v_mul_f32_e64 v110, |v110|, s86
	v_exp_f32_e32 v110, v110
	v_sub_f32_e32 v109, -0.5, v109
	v_mul_f32_e32 v109, 0x3fb8aa3b, v109
	v_exp_f32_e32 v109, v109
	v_add_f32_e32 v110, 1.0, v110
	v_cmp_gt_f32_e32 vcc, s30, v110
	v_mul_f32_e32 v109, 0xbfb8aa3b, v109
	s_nop 0
	v_cndmask_b32_e64 v113, 0, 32, vcc
	v_ldexp_f32 v110, v110, v113
	v_log_f32_e32 v110, v110
	v_exp_f32_e32 v109, v109
	v_mul_f32_e32 v113, 0x3f317217, v110
	v_fma_f32 v113, v110, s24, -v113
	v_fmac_f32_e32 v113, 0x3377d1cf, v110
	v_fmac_f32_e32 v113, 0x3f317217, v110
	v_cmp_lt_f32_e64 s[8:9], |v110|, s25
	s_nop 1
	v_cndmask_b32_e64 v110, v110, v113, s[8:9]
	v_cndmask_b32_e32 v113, 0, v154, vcc
	v_sub_f32_e32 v110, v110, v113
	v_add_f32_e32 v110, v112, v110
	v_max_f32_e64 v112, -v111, 0
	v_mul_f32_e64 v111, |v111|, s86
	v_exp_f32_e32 v111, v111
	v_sub_f32_e32 v110, -0.5, v110
	v_mul_f32_e32 v110, 0x3fb8aa3b, v110
	v_exp_f32_e32 v110, v110
	v_add_f32_e32 v111, 1.0, v111
	v_cmp_gt_f32_e32 vcc, s30, v111
	v_mul_f32_e32 v110, 0xbfb8aa3b, v110
	s_nop 0
	v_cndmask_b32_e64 v113, 0, 32, vcc
	v_ldexp_f32 v111, v111, v113
	v_log_f32_e32 v111, v111
	v_exp_f32_e32 v110, v110
	v_mul_f32_e32 v113, 0x3f317217, v111
	v_fma_f32 v113, v111, s24, -v113
	v_fmac_f32_e32 v113, 0x3377d1cf, v111
	v_fmac_f32_e32 v113, 0x3f317217, v111
	v_cmp_lt_f32_e64 s[8:9], |v111|, s25
	s_nop 1
	v_cndmask_b32_e64 v111, v111, v113, s[8:9]
	v_cndmask_b32_e32 v113, 0, v154, vcc
	v_sub_f32_e32 v111, v111, v113
	v_add_f32_e32 v111, v112, v111
	v_sub_f32_e32 v111, -0.5, v111
	v_mul_f32_e32 v111, 0x3fb8aa3b, v111
	v_exp_f32_e32 v111, v111
	s_nop 0
	v_mul_f32_e32 v111, 0xbfb8aa3b, v111
	v_exp_f32_e32 v111, v111
	global_store_dwordx4 v[120:121], v[108:111], off offset:64
	v_add_f32_e32 v104, v104, v232
	v_max_f32_e64 v108, -v104, 0
	v_mul_f32_e64 v104, |v104|, s86
	v_exp_f32_e32 v104, v104
	v_add_f32_e32 v105, v105, v233
	v_add_f32_e32 v106, v106, v234
	v_add_f32_e32 v107, v107, v235
	v_add_f32_e32 v104, 1.0, v104
	v_cmp_gt_f32_e32 vcc, s30, v104
	s_nop 1
	v_cndmask_b32_e64 v112, 0, 32, vcc
	v_ldexp_f32 v104, v104, v112
	v_log_f32_e32 v104, v104
	s_nop 0
	v_mul_f32_e32 v112, 0x3f317217, v104
	v_fma_f32 v112, v104, s24, -v112
	v_fmac_f32_e32 v112, 0x3377d1cf, v104
	v_fmac_f32_e32 v112, 0x3f317217, v104
	v_cmp_lt_f32_e64 s[8:9], |v104|, s25
	s_nop 1
	v_cndmask_b32_e64 v104, v104, v112, s[8:9]
	v_cndmask_b32_e32 v112, 0, v154, vcc
	v_sub_f32_e32 v104, v104, v112
	v_add_f32_e32 v104, v108, v104
	v_max_f32_e64 v108, -v105, 0
	v_mul_f32_e64 v105, |v105|, s86
	v_exp_f32_e32 v105, v105
	v_sub_f32_e32 v104, -0.5, v104
	v_mul_f32_e32 v104, 0x3fb8aa3b, v104
	v_exp_f32_e32 v104, v104
	v_add_f32_e32 v105, 1.0, v105
	v_cmp_gt_f32_e32 vcc, s30, v105
	v_mul_f32_e32 v104, 0xbfb8aa3b, v104
	s_nop 0
	v_cndmask_b32_e64 v109, 0, 32, vcc
	v_ldexp_f32 v105, v105, v109
	v_log_f32_e32 v105, v105
	v_exp_f32_e32 v104, v104
	v_mul_f32_e32 v109, 0x3f317217, v105
	v_fma_f32 v109, v105, s24, -v109
	v_fmac_f32_e32 v109, 0x3377d1cf, v105
	v_fmac_f32_e32 v109, 0x3f317217, v105
	v_cmp_lt_f32_e64 s[8:9], |v105|, s25
	s_nop 1
	v_cndmask_b32_e64 v105, v105, v109, s[8:9]
	v_cndmask_b32_e32 v109, 0, v154, vcc
	v_sub_f32_e32 v105, v105, v109
	v_add_f32_e32 v105, v108, v105
	v_max_f32_e64 v108, -v106, 0
	v_mul_f32_e64 v106, |v106|, s86
	v_exp_f32_e32 v106, v106
	v_sub_f32_e32 v105, -0.5, v105
	v_mul_f32_e32 v105, 0x3fb8aa3b, v105
	v_exp_f32_e32 v105, v105
	v_add_f32_e32 v106, 1.0, v106
	v_cmp_gt_f32_e32 vcc, s30, v106
	v_mul_f32_e32 v105, 0xbfb8aa3b, v105
	s_nop 0
	v_cndmask_b32_e64 v109, 0, 32, vcc
	v_ldexp_f32 v106, v106, v109
	v_log_f32_e32 v106, v106
	v_exp_f32_e32 v105, v105
	v_mul_f32_e32 v109, 0x3f317217, v106
	v_fma_f32 v109, v106, s24, -v109
	v_fmac_f32_e32 v109, 0x3377d1cf, v106
	v_fmac_f32_e32 v109, 0x3f317217, v106
	v_cmp_lt_f32_e64 s[8:9], |v106|, s25
	s_nop 1
	v_cndmask_b32_e64 v106, v106, v109, s[8:9]
	v_cndmask_b32_e32 v109, 0, v154, vcc
	v_sub_f32_e32 v106, v106, v109
	v_add_f32_e32 v106, v108, v106
	v_max_f32_e64 v108, -v107, 0
	v_mul_f32_e64 v107, |v107|, s86
	v_exp_f32_e32 v107, v107
	v_sub_f32_e32 v106, -0.5, v106
	v_mul_f32_e32 v106, 0x3fb8aa3b, v106
	v_exp_f32_e32 v106, v106
	v_add_f32_e32 v107, 1.0, v107
	v_cmp_gt_f32_e32 vcc, s30, v107
	v_mul_f32_e32 v106, 0xbfb8aa3b, v106
	s_nop 0
	v_cndmask_b32_e64 v109, 0, 32, vcc
	v_ldexp_f32 v107, v107, v109
	v_log_f32_e32 v107, v107
	v_exp_f32_e32 v106, v106
	v_mul_f32_e32 v109, 0x3f317217, v107
	v_fma_f32 v109, v107, s24, -v109
	v_fmac_f32_e32 v109, 0x3377d1cf, v107
	v_fmac_f32_e32 v109, 0x3f317217, v107
	v_cmp_lt_f32_e64 s[8:9], |v107|, s25
	s_nop 1
	v_cndmask_b32_e64 v107, v107, v109, s[8:9]
	v_cndmask_b32_e32 v109, 0, v154, vcc
	v_sub_f32_e32 v107, v107, v109
	v_add_f32_e32 v107, v108, v107
	v_sub_f32_e32 v107, -0.5, v107
	v_mul_f32_e32 v107, 0x3fb8aa3b, v107
	v_exp_f32_e32 v107, v107
	s_nop 0
	v_mul_f32_e32 v107, 0xbfb8aa3b, v107
	v_exp_f32_e32 v107, v107
	global_store_dwordx4 v[120:121], v[104:107], off offset:512
	v_add_f32_e32 v100, v100, v236
	v_max_f32_e64 v104, -v100, 0
	v_mul_f32_e64 v100, |v100|, s86
	v_exp_f32_e32 v100, v100
	v_add_f32_e32 v101, v101, v237
	v_add_f32_e32 v102, v102, v238
	v_add_f32_e32 v103, v103, v239
	v_add_f32_e32 v100, 1.0, v100
	v_cmp_gt_f32_e32 vcc, s30, v100
	s_nop 1
	v_cndmask_b32_e64 v108, 0, 32, vcc
	v_ldexp_f32 v100, v100, v108
	v_log_f32_e32 v100, v100
	s_nop 0
	v_mul_f32_e32 v108, 0x3f317217, v100
	v_fma_f32 v108, v100, s24, -v108
	v_fmac_f32_e32 v108, 0x3377d1cf, v100
	v_fmac_f32_e32 v108, 0x3f317217, v100
	v_cmp_lt_f32_e64 s[8:9], |v100|, s25
	s_nop 1
	v_cndmask_b32_e64 v100, v100, v108, s[8:9]
	v_cndmask_b32_e32 v108, 0, v154, vcc
	v_sub_f32_e32 v100, v100, v108
	v_add_f32_e32 v100, v104, v100
	v_max_f32_e64 v104, -v101, 0
	v_mul_f32_e64 v101, |v101|, s86
	v_exp_f32_e32 v101, v101
	v_sub_f32_e32 v100, -0.5, v100
	v_mul_f32_e32 v100, 0x3fb8aa3b, v100
	v_exp_f32_e32 v100, v100
	v_add_f32_e32 v101, 1.0, v101
	v_cmp_gt_f32_e32 vcc, s30, v101
	v_mul_f32_e32 v100, 0xbfb8aa3b, v100
	s_nop 0
	v_cndmask_b32_e64 v105, 0, 32, vcc
	v_ldexp_f32 v101, v101, v105
	v_log_f32_e32 v101, v101
	v_exp_f32_e32 v100, v100
	v_mul_f32_e32 v105, 0x3f317217, v101
	v_fma_f32 v105, v101, s24, -v105
	v_fmac_f32_e32 v105, 0x3377d1cf, v101
	v_fmac_f32_e32 v105, 0x3f317217, v101
	v_cmp_lt_f32_e64 s[8:9], |v101|, s25
	s_nop 1
	v_cndmask_b32_e64 v101, v101, v105, s[8:9]
	v_cndmask_b32_e32 v105, 0, v154, vcc
	v_sub_f32_e32 v101, v101, v105
	v_add_f32_e32 v101, v104, v101
	v_max_f32_e64 v104, -v102, 0
	v_mul_f32_e64 v102, |v102|, s86
	v_exp_f32_e32 v102, v102
	v_sub_f32_e32 v101, -0.5, v101
	v_mul_f32_e32 v101, 0x3fb8aa3b, v101
	v_exp_f32_e32 v101, v101
	v_add_f32_e32 v102, 1.0, v102
	v_cmp_gt_f32_e32 vcc, s30, v102
	v_mul_f32_e32 v101, 0xbfb8aa3b, v101
	s_nop 0
	v_cndmask_b32_e64 v105, 0, 32, vcc
	v_ldexp_f32 v102, v102, v105
	v_log_f32_e32 v102, v102
	v_exp_f32_e32 v101, v101
	v_mul_f32_e32 v105, 0x3f317217, v102
	v_fma_f32 v105, v102, s24, -v105
	v_fmac_f32_e32 v105, 0x3377d1cf, v102
	v_fmac_f32_e32 v105, 0x3f317217, v102
	v_cmp_lt_f32_e64 s[8:9], |v102|, s25
	s_nop 1
	v_cndmask_b32_e64 v102, v102, v105, s[8:9]
	v_cndmask_b32_e32 v105, 0, v154, vcc
	v_sub_f32_e32 v102, v102, v105
	v_add_f32_e32 v102, v104, v102
	v_max_f32_e64 v104, -v103, 0
	v_mul_f32_e64 v103, |v103|, s86
	v_exp_f32_e32 v103, v103
	v_sub_f32_e32 v102, -0.5, v102
	v_mul_f32_e32 v102, 0x3fb8aa3b, v102
	v_exp_f32_e32 v102, v102
	v_add_f32_e32 v103, 1.0, v103
	v_cmp_gt_f32_e32 vcc, s30, v103
	v_mul_f32_e32 v102, 0xbfb8aa3b, v102
	s_nop 0
	v_cndmask_b32_e64 v105, 0, 32, vcc
	v_ldexp_f32 v103, v103, v105
	v_log_f32_e32 v103, v103
	v_exp_f32_e32 v102, v102
	v_mul_f32_e32 v105, 0x3f317217, v103
	v_fma_f32 v105, v103, s24, -v105
	v_fmac_f32_e32 v105, 0x3377d1cf, v103
	v_fmac_f32_e32 v105, 0x3f317217, v103
	v_cmp_lt_f32_e64 s[8:9], |v103|, s25
	s_nop 1
	v_cndmask_b32_e64 v103, v103, v105, s[8:9]
	v_cndmask_b32_e32 v105, 0, v154, vcc
	v_sub_f32_e32 v103, v103, v105
	v_add_f32_e32 v103, v104, v103
	v_sub_f32_e32 v103, -0.5, v103
	v_mul_f32_e32 v103, 0x3fb8aa3b, v103
	v_exp_f32_e32 v103, v103
	s_nop 0
	v_mul_f32_e32 v103, 0xbfb8aa3b, v103
	v_exp_f32_e32 v103, v103
	global_store_dwordx4 v[120:121], v[100:103], off offset:576
	s_nop 1
	v_or_b32_e32 v100, 32, v148
	v_ashrrev_i32_e32 v101, 31, v100
	v_lshlrev_b64 v[100:101], 12, v[100:101]
	v_lshl_add_u64 v[100:101], s[12:13], 0, v[100:101]
	v_lshl_add_u64 v[104:105], v[100:101], 0, v[140:141]
	v_add_f32_e32 v96, v96, v224
	v_max_f32_e64 v100, -v96, 0
	v_mul_f32_e64 v96, |v96|, s86
	v_exp_f32_e32 v96, v96
	v_add_f32_e32 v97, v97, v225
	v_add_f32_e32 v98, v98, v226
	v_add_f32_e32 v99, v99, v227
	v_add_f32_e32 v96, 1.0, v96
	v_cmp_gt_f32_e32 vcc, s30, v96
	s_nop 1
	v_cndmask_b32_e64 v106, 0, 32, vcc
	v_ldexp_f32 v96, v96, v106
	v_log_f32_e32 v96, v96
	s_nop 0
	v_mul_f32_e32 v106, 0x3f317217, v96
	v_fma_f32 v106, v96, s24, -v106
	v_fmac_f32_e32 v106, 0x3377d1cf, v96
	v_fmac_f32_e32 v106, 0x3f317217, v96
	v_cmp_lt_f32_e64 s[8:9], |v96|, s25
	s_nop 1
	v_cndmask_b32_e64 v96, v96, v106, s[8:9]
	v_cndmask_b32_e32 v106, 0, v154, vcc
	v_sub_f32_e32 v96, v96, v106
	v_add_f32_e32 v96, v100, v96
	v_max_f32_e64 v100, -v97, 0
	v_mul_f32_e64 v97, |v97|, s86
	v_exp_f32_e32 v97, v97
	v_sub_f32_e32 v96, -0.5, v96
	v_mul_f32_e32 v96, 0x3fb8aa3b, v96
	v_exp_f32_e32 v96, v96
	v_add_f32_e32 v97, 1.0, v97
	v_cmp_gt_f32_e32 vcc, s30, v97
	v_mul_f32_e32 v96, 0xbfb8aa3b, v96
	s_nop 0
	v_cndmask_b32_e64 v101, 0, 32, vcc
	v_ldexp_f32 v97, v97, v101
	v_log_f32_e32 v97, v97
	v_exp_f32_e32 v96, v96
	v_mul_f32_e32 v101, 0x3f317217, v97
	v_fma_f32 v101, v97, s24, -v101
	v_fmac_f32_e32 v101, 0x3377d1cf, v97
	v_fmac_f32_e32 v101, 0x3f317217, v97
	v_cmp_lt_f32_e64 s[8:9], |v97|, s25
	s_nop 1
	v_cndmask_b32_e64 v97, v97, v101, s[8:9]
	v_cndmask_b32_e32 v101, 0, v154, vcc
	v_sub_f32_e32 v97, v97, v101
	v_add_f32_e32 v97, v100, v97
	v_max_f32_e64 v100, -v98, 0
	v_mul_f32_e64 v98, |v98|, s86
	v_exp_f32_e32 v98, v98
	v_sub_f32_e32 v97, -0.5, v97
	v_mul_f32_e32 v97, 0x3fb8aa3b, v97
	v_exp_f32_e32 v97, v97
	v_add_f32_e32 v98, 1.0, v98
	v_cmp_gt_f32_e32 vcc, s30, v98
	v_mul_f32_e32 v97, 0xbfb8aa3b, v97
	s_nop 0
	v_cndmask_b32_e64 v101, 0, 32, vcc
	v_ldexp_f32 v98, v98, v101
	v_log_f32_e32 v98, v98
	v_exp_f32_e32 v97, v97
	v_mul_f32_e32 v101, 0x3f317217, v98
	v_fma_f32 v101, v98, s24, -v101
	v_fmac_f32_e32 v101, 0x3377d1cf, v98
	v_fmac_f32_e32 v101, 0x3f317217, v98
	v_cmp_lt_f32_e64 s[8:9], |v98|, s25
	s_nop 1
	v_cndmask_b32_e64 v98, v98, v101, s[8:9]
	v_cndmask_b32_e32 v101, 0, v154, vcc
	v_sub_f32_e32 v98, v98, v101
	v_add_f32_e32 v98, v100, v98
	v_max_f32_e64 v100, -v99, 0
	v_mul_f32_e64 v99, |v99|, s86
	v_exp_f32_e32 v99, v99
	v_sub_f32_e32 v98, -0.5, v98
	v_mul_f32_e32 v98, 0x3fb8aa3b, v98
	v_exp_f32_e32 v98, v98
	v_add_f32_e32 v99, 1.0, v99
	v_cmp_gt_f32_e32 vcc, s30, v99
	v_mul_f32_e32 v98, 0xbfb8aa3b, v98
	s_nop 0
	v_cndmask_b32_e64 v101, 0, 32, vcc
	v_ldexp_f32 v99, v99, v101
	v_log_f32_e32 v99, v99
	v_exp_f32_e32 v98, v98
	v_mul_f32_e32 v101, 0x3f317217, v99
	v_fma_f32 v101, v99, s24, -v101
	v_fmac_f32_e32 v101, 0x3377d1cf, v99
	v_fmac_f32_e32 v101, 0x3f317217, v99
	v_cmp_lt_f32_e64 s[8:9], |v99|, s25
	s_nop 1
	v_cndmask_b32_e64 v99, v99, v101, s[8:9]
	v_cndmask_b32_e32 v101, 0, v154, vcc
	v_sub_f32_e32 v99, v99, v101
	v_add_f32_e32 v99, v100, v99
	v_sub_f32_e32 v99, -0.5, v99
	v_mul_f32_e32 v99, 0x3fb8aa3b, v99
	v_exp_f32_e32 v99, v99
	s_nop 0
	v_mul_f32_e32 v99, 0xbfb8aa3b, v99
	v_exp_f32_e32 v99, v99
	global_store_dwordx4 v[104:105], v[96:99], off
	v_add_f32_e32 v92, v92, v228
	v_max_f32_e64 v96, -v92, 0
	v_mul_f32_e64 v92, |v92|, s86
	v_exp_f32_e32 v92, v92
	v_add_f32_e32 v93, v93, v229
	v_add_f32_e32 v94, v94, v230
	v_add_f32_e32 v95, v95, v231
	v_add_f32_e32 v92, 1.0, v92
	v_cmp_gt_f32_e32 vcc, s30, v92
	s_nop 1
	v_cndmask_b32_e64 v100, 0, 32, vcc
	v_ldexp_f32 v92, v92, v100
	v_log_f32_e32 v92, v92
	s_nop 0
	v_mul_f32_e32 v100, 0x3f317217, v92
	v_fma_f32 v100, v92, s24, -v100
	v_fmac_f32_e32 v100, 0x3377d1cf, v92
	v_fmac_f32_e32 v100, 0x3f317217, v92
	v_cmp_lt_f32_e64 s[8:9], |v92|, s25
	s_nop 1
	v_cndmask_b32_e64 v92, v92, v100, s[8:9]
	v_cndmask_b32_e32 v100, 0, v154, vcc
	v_sub_f32_e32 v92, v92, v100
	v_add_f32_e32 v92, v96, v92
	v_max_f32_e64 v96, -v93, 0
	v_mul_f32_e64 v93, |v93|, s86
	v_exp_f32_e32 v93, v93
	v_sub_f32_e32 v92, -0.5, v92
	v_mul_f32_e32 v92, 0x3fb8aa3b, v92
	v_exp_f32_e32 v92, v92
	v_add_f32_e32 v93, 1.0, v93
	v_cmp_gt_f32_e32 vcc, s30, v93
	v_mul_f32_e32 v92, 0xbfb8aa3b, v92
	s_nop 0
	v_cndmask_b32_e64 v97, 0, 32, vcc
	v_ldexp_f32 v93, v93, v97
	v_log_f32_e32 v93, v93
	v_exp_f32_e32 v92, v92
	v_mul_f32_e32 v97, 0x3f317217, v93
	v_fma_f32 v97, v93, s24, -v97
	v_fmac_f32_e32 v97, 0x3377d1cf, v93
	v_fmac_f32_e32 v97, 0x3f317217, v93
	v_cmp_lt_f32_e64 s[8:9], |v93|, s25
	s_nop 1
	v_cndmask_b32_e64 v93, v93, v97, s[8:9]
	v_cndmask_b32_e32 v97, 0, v154, vcc
	v_sub_f32_e32 v93, v93, v97
	v_add_f32_e32 v93, v96, v93
	v_max_f32_e64 v96, -v94, 0
	v_mul_f32_e64 v94, |v94|, s86
	v_exp_f32_e32 v94, v94
	v_sub_f32_e32 v93, -0.5, v93
	v_mul_f32_e32 v93, 0x3fb8aa3b, v93
	v_exp_f32_e32 v93, v93
	v_add_f32_e32 v94, 1.0, v94
	v_cmp_gt_f32_e32 vcc, s30, v94
	v_mul_f32_e32 v93, 0xbfb8aa3b, v93
	s_nop 0
	v_cndmask_b32_e64 v97, 0, 32, vcc
	v_ldexp_f32 v94, v94, v97
	v_log_f32_e32 v94, v94
	v_exp_f32_e32 v93, v93
	v_mul_f32_e32 v97, 0x3f317217, v94
	v_fma_f32 v97, v94, s24, -v97
	v_fmac_f32_e32 v97, 0x3377d1cf, v94
	v_fmac_f32_e32 v97, 0x3f317217, v94
	v_cmp_lt_f32_e64 s[8:9], |v94|, s25
	s_nop 1
	v_cndmask_b32_e64 v94, v94, v97, s[8:9]
	v_cndmask_b32_e32 v97, 0, v154, vcc
	v_sub_f32_e32 v94, v94, v97
	v_add_f32_e32 v94, v96, v94
	v_max_f32_e64 v96, -v95, 0
	v_mul_f32_e64 v95, |v95|, s86
	v_exp_f32_e32 v95, v95
	v_sub_f32_e32 v94, -0.5, v94
	v_mul_f32_e32 v94, 0x3fb8aa3b, v94
	v_exp_f32_e32 v94, v94
	v_add_f32_e32 v95, 1.0, v95
	v_cmp_gt_f32_e32 vcc, s30, v95
	v_mul_f32_e32 v94, 0xbfb8aa3b, v94
	s_nop 0
	v_cndmask_b32_e64 v97, 0, 32, vcc
	v_ldexp_f32 v95, v95, v97
	v_log_f32_e32 v95, v95
	v_exp_f32_e32 v94, v94
	v_mul_f32_e32 v97, 0x3f317217, v95
	v_fma_f32 v97, v95, s24, -v97
	v_fmac_f32_e32 v97, 0x3377d1cf, v95
	v_fmac_f32_e32 v97, 0x3f317217, v95
	v_cmp_lt_f32_e64 s[8:9], |v95|, s25
	s_nop 1
	v_cndmask_b32_e64 v95, v95, v97, s[8:9]
	v_cndmask_b32_e32 v97, 0, v154, vcc
	v_sub_f32_e32 v95, v95, v97
	v_add_f32_e32 v95, v96, v95
	v_sub_f32_e32 v95, -0.5, v95
	v_mul_f32_e32 v95, 0x3fb8aa3b, v95
	v_exp_f32_e32 v95, v95
	s_nop 0
	v_mul_f32_e32 v95, 0xbfb8aa3b, v95
	v_exp_f32_e32 v95, v95
	global_store_dwordx4 v[104:105], v[92:95], off offset:64
	v_add_f32_e32 v88, v88, v232
	v_max_f32_e64 v92, -v88, 0
	v_mul_f32_e64 v88, |v88|, s86
	v_exp_f32_e32 v88, v88
	v_add_f32_e32 v89, v89, v233
	v_add_f32_e32 v90, v90, v234
	v_add_f32_e32 v91, v91, v235
	v_add_f32_e32 v88, 1.0, v88
	v_cmp_gt_f32_e32 vcc, s30, v88
	s_nop 1
	v_cndmask_b32_e64 v96, 0, 32, vcc
	v_ldexp_f32 v88, v88, v96
	v_log_f32_e32 v88, v88
	s_nop 0
	v_mul_f32_e32 v96, 0x3f317217, v88
	v_fma_f32 v96, v88, s24, -v96
	v_fmac_f32_e32 v96, 0x3377d1cf, v88
	v_fmac_f32_e32 v96, 0x3f317217, v88
	v_cmp_lt_f32_e64 s[8:9], |v88|, s25
	s_nop 1
	v_cndmask_b32_e64 v88, v88, v96, s[8:9]
	v_cndmask_b32_e32 v96, 0, v154, vcc
	v_sub_f32_e32 v88, v88, v96
	v_add_f32_e32 v88, v92, v88
	v_max_f32_e64 v92, -v89, 0
	v_mul_f32_e64 v89, |v89|, s86
	v_exp_f32_e32 v89, v89
	v_sub_f32_e32 v88, -0.5, v88
	v_mul_f32_e32 v88, 0x3fb8aa3b, v88
	v_exp_f32_e32 v88, v88
	v_add_f32_e32 v89, 1.0, v89
	v_cmp_gt_f32_e32 vcc, s30, v89
	v_mul_f32_e32 v88, 0xbfb8aa3b, v88
	s_nop 0
	v_cndmask_b32_e64 v93, 0, 32, vcc
	v_ldexp_f32 v89, v89, v93
	v_log_f32_e32 v89, v89
	v_exp_f32_e32 v88, v88
	v_mul_f32_e32 v93, 0x3f317217, v89
	v_fma_f32 v93, v89, s24, -v93
	v_fmac_f32_e32 v93, 0x3377d1cf, v89
	v_fmac_f32_e32 v93, 0x3f317217, v89
	v_cmp_lt_f32_e64 s[8:9], |v89|, s25
	s_nop 1
	v_cndmask_b32_e64 v89, v89, v93, s[8:9]
	v_cndmask_b32_e32 v93, 0, v154, vcc
	v_sub_f32_e32 v89, v89, v93
	v_add_f32_e32 v89, v92, v89
	v_max_f32_e64 v92, -v90, 0
	v_mul_f32_e64 v90, |v90|, s86
	v_exp_f32_e32 v90, v90
	v_sub_f32_e32 v89, -0.5, v89
	v_mul_f32_e32 v89, 0x3fb8aa3b, v89
	v_exp_f32_e32 v89, v89
	v_add_f32_e32 v90, 1.0, v90
	v_cmp_gt_f32_e32 vcc, s30, v90
	v_mul_f32_e32 v89, 0xbfb8aa3b, v89
	s_nop 0
	v_cndmask_b32_e64 v93, 0, 32, vcc
	v_ldexp_f32 v90, v90, v93
	v_log_f32_e32 v90, v90
	v_exp_f32_e32 v89, v89
	v_mul_f32_e32 v93, 0x3f317217, v90
	v_fma_f32 v93, v90, s24, -v93
	v_fmac_f32_e32 v93, 0x3377d1cf, v90
	v_fmac_f32_e32 v93, 0x3f317217, v90
	v_cmp_lt_f32_e64 s[8:9], |v90|, s25
	s_nop 1
	v_cndmask_b32_e64 v90, v90, v93, s[8:9]
	v_cndmask_b32_e32 v93, 0, v154, vcc
	v_sub_f32_e32 v90, v90, v93
	v_add_f32_e32 v90, v92, v90
	v_max_f32_e64 v92, -v91, 0
	v_mul_f32_e64 v91, |v91|, s86
	v_exp_f32_e32 v91, v91
	v_sub_f32_e32 v90, -0.5, v90
	v_mul_f32_e32 v90, 0x3fb8aa3b, v90
	v_exp_f32_e32 v90, v90
	v_add_f32_e32 v91, 1.0, v91
	v_cmp_gt_f32_e32 vcc, s30, v91
	v_mul_f32_e32 v90, 0xbfb8aa3b, v90
	s_nop 0
	v_cndmask_b32_e64 v93, 0, 32, vcc
	v_ldexp_f32 v91, v91, v93
	v_log_f32_e32 v91, v91
	v_exp_f32_e32 v90, v90
	v_mul_f32_e32 v93, 0x3f317217, v91
	v_fma_f32 v93, v91, s24, -v93
	v_fmac_f32_e32 v93, 0x3377d1cf, v91
	v_fmac_f32_e32 v93, 0x3f317217, v91
	v_cmp_lt_f32_e64 s[8:9], |v91|, s25
	s_nop 1
	v_cndmask_b32_e64 v91, v91, v93, s[8:9]
	v_cndmask_b32_e32 v93, 0, v154, vcc
	v_sub_f32_e32 v91, v91, v93
	v_add_f32_e32 v91, v92, v91
	v_sub_f32_e32 v91, -0.5, v91
	v_mul_f32_e32 v91, 0x3fb8aa3b, v91
	v_exp_f32_e32 v91, v91
	s_nop 0
	v_mul_f32_e32 v91, 0xbfb8aa3b, v91
	v_exp_f32_e32 v91, v91
	global_store_dwordx4 v[104:105], v[88:91], off offset:512
	v_add_f32_e32 v84, v84, v236
	v_max_f32_e64 v88, -v84, 0
	v_mul_f32_e64 v84, |v84|, s86
	v_exp_f32_e32 v84, v84
	v_add_f32_e32 v85, v85, v237
	v_add_f32_e32 v86, v86, v238
	v_add_f32_e32 v87, v87, v239
	v_add_f32_e32 v84, 1.0, v84
	v_cmp_gt_f32_e32 vcc, s30, v84
	s_nop 1
	v_cndmask_b32_e64 v92, 0, 32, vcc
	v_ldexp_f32 v84, v84, v92
	v_log_f32_e32 v84, v84
	s_nop 0
	v_mul_f32_e32 v92, 0x3f317217, v84
	v_fma_f32 v92, v84, s24, -v92
	v_fmac_f32_e32 v92, 0x3377d1cf, v84
	v_fmac_f32_e32 v92, 0x3f317217, v84
	v_cmp_lt_f32_e64 s[8:9], |v84|, s25
	s_nop 1
	v_cndmask_b32_e64 v84, v84, v92, s[8:9]
	v_cndmask_b32_e32 v92, 0, v154, vcc
	v_sub_f32_e32 v84, v84, v92
	v_add_f32_e32 v84, v88, v84
	v_max_f32_e64 v88, -v85, 0
	v_mul_f32_e64 v85, |v85|, s86
	v_exp_f32_e32 v85, v85
	v_sub_f32_e32 v84, -0.5, v84
	v_mul_f32_e32 v84, 0x3fb8aa3b, v84
	v_exp_f32_e32 v84, v84
	v_add_f32_e32 v85, 1.0, v85
	v_cmp_gt_f32_e32 vcc, s30, v85
	v_mul_f32_e32 v84, 0xbfb8aa3b, v84
	s_nop 0
	v_cndmask_b32_e64 v89, 0, 32, vcc
	v_ldexp_f32 v85, v85, v89
	v_log_f32_e32 v85, v85
	v_exp_f32_e32 v84, v84
	v_mul_f32_e32 v89, 0x3f317217, v85
	v_fma_f32 v89, v85, s24, -v89
	v_fmac_f32_e32 v89, 0x3377d1cf, v85
	v_fmac_f32_e32 v89, 0x3f317217, v85
	v_cmp_lt_f32_e64 s[8:9], |v85|, s25
	s_nop 1
	v_cndmask_b32_e64 v85, v85, v89, s[8:9]
	v_cndmask_b32_e32 v89, 0, v154, vcc
	v_sub_f32_e32 v85, v85, v89
	v_add_f32_e32 v85, v88, v85
	v_max_f32_e64 v88, -v86, 0
	v_mul_f32_e64 v86, |v86|, s86
	v_exp_f32_e32 v86, v86
	v_sub_f32_e32 v85, -0.5, v85
	v_mul_f32_e32 v85, 0x3fb8aa3b, v85
	v_exp_f32_e32 v85, v85
	v_add_f32_e32 v86, 1.0, v86
	v_cmp_gt_f32_e32 vcc, s30, v86
	v_mul_f32_e32 v85, 0xbfb8aa3b, v85
	s_nop 0
	v_cndmask_b32_e64 v89, 0, 32, vcc
	v_ldexp_f32 v86, v86, v89
	v_log_f32_e32 v86, v86
	v_exp_f32_e32 v85, v85
	v_mul_f32_e32 v89, 0x3f317217, v86
	v_fma_f32 v89, v86, s24, -v89
	v_fmac_f32_e32 v89, 0x3377d1cf, v86
	v_fmac_f32_e32 v89, 0x3f317217, v86
	v_cmp_lt_f32_e64 s[8:9], |v86|, s25
	s_nop 1
	v_cndmask_b32_e64 v86, v86, v89, s[8:9]
	v_cndmask_b32_e32 v89, 0, v154, vcc
	v_sub_f32_e32 v86, v86, v89
	v_add_f32_e32 v86, v88, v86
	v_max_f32_e64 v88, -v87, 0
	v_mul_f32_e64 v87, |v87|, s86
	v_exp_f32_e32 v87, v87
	v_sub_f32_e32 v86, -0.5, v86
	v_mul_f32_e32 v86, 0x3fb8aa3b, v86
	v_exp_f32_e32 v86, v86
	v_add_f32_e32 v87, 1.0, v87
	v_cmp_gt_f32_e32 vcc, s30, v87
	v_mul_f32_e32 v86, 0xbfb8aa3b, v86
	s_nop 0
	v_cndmask_b32_e64 v89, 0, 32, vcc
	v_ldexp_f32 v87, v87, v89
	v_log_f32_e32 v87, v87
	v_exp_f32_e32 v86, v86
	v_mul_f32_e32 v89, 0x3f317217, v87
	v_fma_f32 v89, v87, s24, -v89
	v_fmac_f32_e32 v89, 0x3377d1cf, v87
	v_fmac_f32_e32 v89, 0x3f317217, v87
	v_cmp_lt_f32_e64 s[8:9], |v87|, s25
	s_nop 1
	v_cndmask_b32_e64 v87, v87, v89, s[8:9]
	v_cndmask_b32_e32 v89, 0, v154, vcc
	v_sub_f32_e32 v87, v87, v89
	v_add_f32_e32 v87, v88, v87
	v_sub_f32_e32 v87, -0.5, v87
	v_mul_f32_e32 v87, 0x3fb8aa3b, v87
	v_exp_f32_e32 v87, v87
	s_nop 0
	v_mul_f32_e32 v87, 0xbfb8aa3b, v87
	v_exp_f32_e32 v87, v87
	global_store_dwordx4 v[104:105], v[84:87], off offset:576
	s_nop 1
	v_or_b32_e32 v84, 48, v148
	v_ashrrev_i32_e32 v85, 31, v84
	v_lshlrev_b64 v[84:85], 12, v[84:85]
	v_lshl_add_u64 v[84:85], s[12:13], 0, v[84:85]
	v_lshl_add_u64 v[88:89], v[84:85], 0, v[140:141]
	v_add_f32_e32 v80, v80, v224
	v_max_f32_e64 v84, -v80, 0
	v_mul_f32_e64 v80, |v80|, s86
	v_exp_f32_e32 v80, v80
	v_add_f32_e32 v81, v81, v225
	v_add_f32_e32 v82, v82, v226
	v_add_f32_e32 v83, v83, v227
	v_add_f32_e32 v80, 1.0, v80
	v_cmp_gt_f32_e32 vcc, s30, v80
	s_nop 1
	v_cndmask_b32_e64 v90, 0, 32, vcc
	v_ldexp_f32 v80, v80, v90
	v_log_f32_e32 v80, v80
	s_nop 0
	v_mul_f32_e32 v90, 0x3f317217, v80
	v_fma_f32 v90, v80, s24, -v90
	v_fmac_f32_e32 v90, 0x3377d1cf, v80
	v_fmac_f32_e32 v90, 0x3f317217, v80
	v_cmp_lt_f32_e64 s[8:9], |v80|, s25
	s_nop 1
	v_cndmask_b32_e64 v80, v80, v90, s[8:9]
	v_cndmask_b32_e32 v90, 0, v154, vcc
	v_sub_f32_e32 v80, v80, v90
	v_add_f32_e32 v80, v84, v80
	v_max_f32_e64 v84, -v81, 0
	v_mul_f32_e64 v81, |v81|, s86
	v_exp_f32_e32 v81, v81
	v_sub_f32_e32 v80, -0.5, v80
	v_mul_f32_e32 v80, 0x3fb8aa3b, v80
	v_exp_f32_e32 v80, v80
	v_add_f32_e32 v81, 1.0, v81
	v_cmp_gt_f32_e32 vcc, s30, v81
	v_mul_f32_e32 v80, 0xbfb8aa3b, v80
	s_nop 0
	v_cndmask_b32_e64 v85, 0, 32, vcc
	v_ldexp_f32 v81, v81, v85
	v_log_f32_e32 v81, v81
	v_exp_f32_e32 v80, v80
	v_mul_f32_e32 v85, 0x3f317217, v81
	v_fma_f32 v85, v81, s24, -v85
	v_fmac_f32_e32 v85, 0x3377d1cf, v81
	v_fmac_f32_e32 v85, 0x3f317217, v81
	v_cmp_lt_f32_e64 s[8:9], |v81|, s25
	s_nop 1
	v_cndmask_b32_e64 v81, v81, v85, s[8:9]
	v_cndmask_b32_e32 v85, 0, v154, vcc
	v_sub_f32_e32 v81, v81, v85
	v_add_f32_e32 v81, v84, v81
	v_max_f32_e64 v84, -v82, 0
	v_mul_f32_e64 v82, |v82|, s86
	v_exp_f32_e32 v82, v82
	v_sub_f32_e32 v81, -0.5, v81
	v_mul_f32_e32 v81, 0x3fb8aa3b, v81
	v_exp_f32_e32 v81, v81
	v_add_f32_e32 v82, 1.0, v82
	v_cmp_gt_f32_e32 vcc, s30, v82
	v_mul_f32_e32 v81, 0xbfb8aa3b, v81
	s_nop 0
	v_cndmask_b32_e64 v85, 0, 32, vcc
	v_ldexp_f32 v82, v82, v85
	v_log_f32_e32 v82, v82
	v_exp_f32_e32 v81, v81
	v_mul_f32_e32 v85, 0x3f317217, v82
	v_fma_f32 v85, v82, s24, -v85
	v_fmac_f32_e32 v85, 0x3377d1cf, v82
	v_fmac_f32_e32 v85, 0x3f317217, v82
	v_cmp_lt_f32_e64 s[8:9], |v82|, s25
	s_nop 1
	v_cndmask_b32_e64 v82, v82, v85, s[8:9]
	v_cndmask_b32_e32 v85, 0, v154, vcc
	v_sub_f32_e32 v82, v82, v85
	v_add_f32_e32 v82, v84, v82
	v_max_f32_e64 v84, -v83, 0
	v_mul_f32_e64 v83, |v83|, s86
	v_exp_f32_e32 v83, v83
	v_sub_f32_e32 v82, -0.5, v82
	v_mul_f32_e32 v82, 0x3fb8aa3b, v82
	v_exp_f32_e32 v82, v82
	v_add_f32_e32 v83, 1.0, v83
	v_cmp_gt_f32_e32 vcc, s30, v83
	v_mul_f32_e32 v82, 0xbfb8aa3b, v82
	s_nop 0
	v_cndmask_b32_e64 v85, 0, 32, vcc
	v_ldexp_f32 v83, v83, v85
	v_log_f32_e32 v83, v83
	v_exp_f32_e32 v82, v82
	v_mul_f32_e32 v85, 0x3f317217, v83
	v_fma_f32 v85, v83, s24, -v85
	v_fmac_f32_e32 v85, 0x3377d1cf, v83
	v_fmac_f32_e32 v85, 0x3f317217, v83
	v_cmp_lt_f32_e64 s[8:9], |v83|, s25
	s_nop 1
	v_cndmask_b32_e64 v83, v83, v85, s[8:9]
	v_cndmask_b32_e32 v85, 0, v154, vcc
	v_sub_f32_e32 v83, v83, v85
	v_add_f32_e32 v83, v84, v83
	v_sub_f32_e32 v83, -0.5, v83
	v_mul_f32_e32 v83, 0x3fb8aa3b, v83
	v_exp_f32_e32 v83, v83
	s_nop 0
	v_mul_f32_e32 v83, 0xbfb8aa3b, v83
	v_exp_f32_e32 v83, v83
	global_store_dwordx4 v[88:89], v[80:83], off
	v_add_f32_e32 v76, v76, v228
	v_max_f32_e64 v80, -v76, 0
	v_mul_f32_e64 v76, |v76|, s86
	v_exp_f32_e32 v76, v76
	v_add_f32_e32 v77, v77, v229
	v_add_f32_e32 v78, v78, v230
	v_add_f32_e32 v79, v79, v231
	v_add_f32_e32 v76, 1.0, v76
	v_cmp_gt_f32_e32 vcc, s30, v76
	s_nop 1
	v_cndmask_b32_e64 v84, 0, 32, vcc
	v_ldexp_f32 v76, v76, v84
	v_log_f32_e32 v76, v76
	s_nop 0
	v_mul_f32_e32 v84, 0x3f317217, v76
	v_fma_f32 v84, v76, s24, -v84
	v_fmac_f32_e32 v84, 0x3377d1cf, v76
	v_fmac_f32_e32 v84, 0x3f317217, v76
	v_cmp_lt_f32_e64 s[8:9], |v76|, s25
	s_nop 1
	v_cndmask_b32_e64 v76, v76, v84, s[8:9]
	v_cndmask_b32_e32 v84, 0, v154, vcc
	v_sub_f32_e32 v76, v76, v84
	v_add_f32_e32 v76, v80, v76
	v_max_f32_e64 v80, -v77, 0
	v_mul_f32_e64 v77, |v77|, s86
	v_exp_f32_e32 v77, v77
	v_sub_f32_e32 v76, -0.5, v76
	v_mul_f32_e32 v76, 0x3fb8aa3b, v76
	v_exp_f32_e32 v76, v76
	v_add_f32_e32 v77, 1.0, v77
	v_cmp_gt_f32_e32 vcc, s30, v77
	v_mul_f32_e32 v76, 0xbfb8aa3b, v76
	s_nop 0
	v_cndmask_b32_e64 v81, 0, 32, vcc
	v_ldexp_f32 v77, v77, v81
	v_log_f32_e32 v77, v77
	v_exp_f32_e32 v76, v76
	v_mul_f32_e32 v81, 0x3f317217, v77
	v_fma_f32 v81, v77, s24, -v81
	v_fmac_f32_e32 v81, 0x3377d1cf, v77
	v_fmac_f32_e32 v81, 0x3f317217, v77
	v_cmp_lt_f32_e64 s[8:9], |v77|, s25
	s_nop 1
	v_cndmask_b32_e64 v77, v77, v81, s[8:9]
	v_cndmask_b32_e32 v81, 0, v154, vcc
	v_sub_f32_e32 v77, v77, v81
	v_add_f32_e32 v77, v80, v77
	v_max_f32_e64 v80, -v78, 0
	v_mul_f32_e64 v78, |v78|, s86
	v_exp_f32_e32 v78, v78
	v_sub_f32_e32 v77, -0.5, v77
	v_mul_f32_e32 v77, 0x3fb8aa3b, v77
	v_exp_f32_e32 v77, v77
	v_add_f32_e32 v78, 1.0, v78
	v_cmp_gt_f32_e32 vcc, s30, v78
	v_mul_f32_e32 v77, 0xbfb8aa3b, v77
	s_nop 0
	v_cndmask_b32_e64 v81, 0, 32, vcc
	v_ldexp_f32 v78, v78, v81
	v_log_f32_e32 v78, v78
	v_exp_f32_e32 v77, v77
	v_mul_f32_e32 v81, 0x3f317217, v78
	v_fma_f32 v81, v78, s24, -v81
	v_fmac_f32_e32 v81, 0x3377d1cf, v78
	v_fmac_f32_e32 v81, 0x3f317217, v78
	v_cmp_lt_f32_e64 s[8:9], |v78|, s25
	s_nop 1
	v_cndmask_b32_e64 v78, v78, v81, s[8:9]
	v_cndmask_b32_e32 v81, 0, v154, vcc
	v_sub_f32_e32 v78, v78, v81
	v_add_f32_e32 v78, v80, v78
	v_max_f32_e64 v80, -v79, 0
	v_mul_f32_e64 v79, |v79|, s86
	v_exp_f32_e32 v79, v79
	v_sub_f32_e32 v78, -0.5, v78
	v_mul_f32_e32 v78, 0x3fb8aa3b, v78
	v_exp_f32_e32 v78, v78
	v_add_f32_e32 v79, 1.0, v79
	v_cmp_gt_f32_e32 vcc, s30, v79
	v_mul_f32_e32 v78, 0xbfb8aa3b, v78
	s_nop 0
	v_cndmask_b32_e64 v81, 0, 32, vcc
	v_ldexp_f32 v79, v79, v81
	v_log_f32_e32 v79, v79
	v_exp_f32_e32 v78, v78
	v_mul_f32_e32 v81, 0x3f317217, v79
	v_fma_f32 v81, v79, s24, -v81
	v_fmac_f32_e32 v81, 0x3377d1cf, v79
	v_fmac_f32_e32 v81, 0x3f317217, v79
	v_cmp_lt_f32_e64 s[8:9], |v79|, s25
	s_nop 1
	v_cndmask_b32_e64 v79, v79, v81, s[8:9]
	v_cndmask_b32_e32 v81, 0, v154, vcc
	v_sub_f32_e32 v79, v79, v81
	v_add_f32_e32 v79, v80, v79
	v_sub_f32_e32 v79, -0.5, v79
	v_mul_f32_e32 v79, 0x3fb8aa3b, v79
	v_exp_f32_e32 v79, v79
	s_nop 0
	v_mul_f32_e32 v79, 0xbfb8aa3b, v79
	v_exp_f32_e32 v79, v79
	global_store_dwordx4 v[88:89], v[76:79], off offset:64
	v_add_f32_e32 v72, v72, v232
	v_max_f32_e64 v76, -v72, 0
	v_mul_f32_e64 v72, |v72|, s86
	v_exp_f32_e32 v72, v72
	v_add_f32_e32 v73, v73, v233
	v_add_f32_e32 v74, v74, v234
	v_add_f32_e32 v75, v75, v235
	v_add_f32_e32 v72, 1.0, v72
	v_cmp_gt_f32_e32 vcc, s30, v72
	s_nop 1
	v_cndmask_b32_e64 v80, 0, 32, vcc
	v_ldexp_f32 v72, v72, v80
	v_log_f32_e32 v72, v72
	s_nop 0
	v_mul_f32_e32 v80, 0x3f317217, v72
	v_fma_f32 v80, v72, s24, -v80
	v_fmac_f32_e32 v80, 0x3377d1cf, v72
	v_fmac_f32_e32 v80, 0x3f317217, v72
	v_cmp_lt_f32_e64 s[8:9], |v72|, s25
	s_nop 1
	v_cndmask_b32_e64 v72, v72, v80, s[8:9]
	v_cndmask_b32_e32 v80, 0, v154, vcc
	v_sub_f32_e32 v72, v72, v80
	v_add_f32_e32 v72, v76, v72
	v_max_f32_e64 v76, -v73, 0
	v_mul_f32_e64 v73, |v73|, s86
	v_exp_f32_e32 v73, v73
	v_sub_f32_e32 v72, -0.5, v72
	v_mul_f32_e32 v72, 0x3fb8aa3b, v72
	v_exp_f32_e32 v72, v72
	v_add_f32_e32 v73, 1.0, v73
	v_cmp_gt_f32_e32 vcc, s30, v73
	v_mul_f32_e32 v72, 0xbfb8aa3b, v72
	s_nop 0
	v_cndmask_b32_e64 v77, 0, 32, vcc
	v_ldexp_f32 v73, v73, v77
	v_log_f32_e32 v73, v73
	v_exp_f32_e32 v72, v72
	v_mul_f32_e32 v77, 0x3f317217, v73
	v_fma_f32 v77, v73, s24, -v77
	v_fmac_f32_e32 v77, 0x3377d1cf, v73
	v_fmac_f32_e32 v77, 0x3f317217, v73
	v_cmp_lt_f32_e64 s[8:9], |v73|, s25
	s_nop 1
	v_cndmask_b32_e64 v73, v73, v77, s[8:9]
	v_cndmask_b32_e32 v77, 0, v154, vcc
	v_sub_f32_e32 v73, v73, v77
	v_add_f32_e32 v73, v76, v73
	v_max_f32_e64 v76, -v74, 0
	v_mul_f32_e64 v74, |v74|, s86
	v_exp_f32_e32 v74, v74
	v_sub_f32_e32 v73, -0.5, v73
	v_mul_f32_e32 v73, 0x3fb8aa3b, v73
	v_exp_f32_e32 v73, v73
	v_add_f32_e32 v74, 1.0, v74
	v_cmp_gt_f32_e32 vcc, s30, v74
	v_mul_f32_e32 v73, 0xbfb8aa3b, v73
	s_nop 0
	v_cndmask_b32_e64 v77, 0, 32, vcc
	v_ldexp_f32 v74, v74, v77
	v_log_f32_e32 v74, v74
	v_exp_f32_e32 v73, v73
	v_mul_f32_e32 v77, 0x3f317217, v74
	v_fma_f32 v77, v74, s24, -v77
	v_fmac_f32_e32 v77, 0x3377d1cf, v74
	v_fmac_f32_e32 v77, 0x3f317217, v74
	v_cmp_lt_f32_e64 s[8:9], |v74|, s25
	s_nop 1
	v_cndmask_b32_e64 v74, v74, v77, s[8:9]
	v_cndmask_b32_e32 v77, 0, v154, vcc
	v_sub_f32_e32 v74, v74, v77
	v_add_f32_e32 v74, v76, v74
	v_max_f32_e64 v76, -v75, 0
	v_mul_f32_e64 v75, |v75|, s86
	v_exp_f32_e32 v75, v75
	v_sub_f32_e32 v74, -0.5, v74
	v_mul_f32_e32 v74, 0x3fb8aa3b, v74
	v_exp_f32_e32 v74, v74
	v_add_f32_e32 v75, 1.0, v75
	v_cmp_gt_f32_e32 vcc, s30, v75
	v_mul_f32_e32 v74, 0xbfb8aa3b, v74
	s_nop 0
	v_cndmask_b32_e64 v77, 0, 32, vcc
	v_ldexp_f32 v75, v75, v77
	v_log_f32_e32 v75, v75
	v_exp_f32_e32 v74, v74
	v_mul_f32_e32 v77, 0x3f317217, v75
	v_fma_f32 v77, v75, s24, -v77
	v_fmac_f32_e32 v77, 0x3377d1cf, v75
	v_fmac_f32_e32 v77, 0x3f317217, v75
	v_cmp_lt_f32_e64 s[8:9], |v75|, s25
	s_nop 1
	v_cndmask_b32_e64 v75, v75, v77, s[8:9]
	v_cndmask_b32_e32 v77, 0, v154, vcc
	v_sub_f32_e32 v75, v75, v77
	v_add_f32_e32 v75, v76, v75
	v_sub_f32_e32 v75, -0.5, v75
	v_mul_f32_e32 v75, 0x3fb8aa3b, v75
	v_exp_f32_e32 v75, v75
	s_nop 0
	v_mul_f32_e32 v75, 0xbfb8aa3b, v75
	v_exp_f32_e32 v75, v75
	global_store_dwordx4 v[88:89], v[72:75], off offset:512
	v_add_f32_e32 v68, v68, v236
	v_max_f32_e64 v72, -v68, 0
	v_mul_f32_e64 v68, |v68|, s86
	v_exp_f32_e32 v68, v68
	v_add_f32_e32 v69, v69, v237
	v_add_f32_e32 v70, v70, v238
	v_add_f32_e32 v71, v71, v239
	v_add_f32_e32 v68, 1.0, v68
	v_cmp_gt_f32_e32 vcc, s30, v68
	s_nop 1
	v_cndmask_b32_e64 v76, 0, 32, vcc
	v_ldexp_f32 v68, v68, v76
	v_log_f32_e32 v68, v68
	s_nop 0
	v_mul_f32_e32 v76, 0x3f317217, v68
	v_fma_f32 v76, v68, s24, -v76
	v_fmac_f32_e32 v76, 0x3377d1cf, v68
	v_fmac_f32_e32 v76, 0x3f317217, v68
	v_cmp_lt_f32_e64 s[8:9], |v68|, s25
	s_nop 1
	v_cndmask_b32_e64 v68, v68, v76, s[8:9]
	v_cndmask_b32_e32 v76, 0, v154, vcc
	v_sub_f32_e32 v68, v68, v76
	v_add_f32_e32 v68, v72, v68
	v_max_f32_e64 v72, -v69, 0
	v_mul_f32_e64 v69, |v69|, s86
	v_exp_f32_e32 v69, v69
	v_sub_f32_e32 v68, -0.5, v68
	v_mul_f32_e32 v68, 0x3fb8aa3b, v68
	v_exp_f32_e32 v68, v68
	v_add_f32_e32 v69, 1.0, v69
	v_cmp_gt_f32_e32 vcc, s30, v69
	v_mul_f32_e32 v68, 0xbfb8aa3b, v68
	s_nop 0
	v_cndmask_b32_e64 v73, 0, 32, vcc
	v_ldexp_f32 v69, v69, v73
	v_log_f32_e32 v69, v69
	v_exp_f32_e32 v68, v68
	v_mul_f32_e32 v73, 0x3f317217, v69
	v_fma_f32 v73, v69, s24, -v73
	v_fmac_f32_e32 v73, 0x3377d1cf, v69
	v_fmac_f32_e32 v73, 0x3f317217, v69
	v_cmp_lt_f32_e64 s[8:9], |v69|, s25
	s_nop 1
	v_cndmask_b32_e64 v69, v69, v73, s[8:9]
	v_cndmask_b32_e32 v73, 0, v154, vcc
	v_sub_f32_e32 v69, v69, v73
	v_add_f32_e32 v69, v72, v69
	v_max_f32_e64 v72, -v70, 0
	v_mul_f32_e64 v70, |v70|, s86
	v_exp_f32_e32 v70, v70
	v_sub_f32_e32 v69, -0.5, v69
	v_mul_f32_e32 v69, 0x3fb8aa3b, v69
	v_exp_f32_e32 v69, v69
	v_add_f32_e32 v70, 1.0, v70
	v_cmp_gt_f32_e32 vcc, s30, v70
	v_mul_f32_e32 v69, 0xbfb8aa3b, v69
	s_nop 0
	v_cndmask_b32_e64 v73, 0, 32, vcc
	v_ldexp_f32 v70, v70, v73
	v_log_f32_e32 v70, v70
	v_exp_f32_e32 v69, v69
	v_mul_f32_e32 v73, 0x3f317217, v70
	v_fma_f32 v73, v70, s24, -v73
	v_fmac_f32_e32 v73, 0x3377d1cf, v70
	v_fmac_f32_e32 v73, 0x3f317217, v70
	v_cmp_lt_f32_e64 s[8:9], |v70|, s25
	s_nop 1
	v_cndmask_b32_e64 v70, v70, v73, s[8:9]
	v_cndmask_b32_e32 v73, 0, v154, vcc
	v_sub_f32_e32 v70, v70, v73
	v_add_f32_e32 v70, v72, v70
	v_max_f32_e64 v72, -v71, 0
	v_mul_f32_e64 v71, |v71|, s86
	v_exp_f32_e32 v71, v71
	v_sub_f32_e32 v70, -0.5, v70
	v_mul_f32_e32 v70, 0x3fb8aa3b, v70
	v_exp_f32_e32 v70, v70
	v_add_f32_e32 v71, 1.0, v71
	v_cmp_gt_f32_e32 vcc, s30, v71
	v_mul_f32_e32 v70, 0xbfb8aa3b, v70
	s_nop 0
	v_cndmask_b32_e64 v73, 0, 32, vcc
	v_ldexp_f32 v71, v71, v73
	v_log_f32_e32 v71, v71
	v_exp_f32_e32 v70, v70
	v_mul_f32_e32 v73, 0x3f317217, v71
	v_fma_f32 v73, v71, s24, -v73
	v_fmac_f32_e32 v73, 0x3377d1cf, v71
	v_fmac_f32_e32 v73, 0x3f317217, v71
	v_cmp_lt_f32_e64 s[8:9], |v71|, s25
	s_nop 1
	v_cndmask_b32_e64 v71, v71, v73, s[8:9]
	v_cndmask_b32_e32 v73, 0, v154, vcc
	v_sub_f32_e32 v71, v71, v73
	v_add_f32_e32 v71, v72, v71
	v_sub_f32_e32 v71, -0.5, v71
	v_mul_f32_e32 v71, 0x3fb8aa3b, v71
	v_exp_f32_e32 v71, v71
	v_lshl_add_u64 v[72:73], v[146:147], 0, s[38:39]
	v_mul_f32_e32 v71, 0xbfb8aa3b, v71
	v_exp_f32_e32 v71, v71
	global_store_dwordx4 v[88:89], v[68:71], off offset:576
	v_add_f32_e32 v64, v64, v224
	v_max_f32_e64 v68, -v64, 0
	v_mul_f32_e64 v64, |v64|, s86
	v_exp_f32_e32 v64, v64
	v_add_f32_e32 v65, v65, v225
	v_add_f32_e32 v66, v66, v226
	v_add_f32_e32 v67, v67, v227
	v_add_f32_e32 v64, 1.0, v64
	v_cmp_gt_f32_e32 vcc, s30, v64
	s_nop 1
	v_cndmask_b32_e64 v74, 0, 32, vcc
	v_ldexp_f32 v64, v64, v74
	v_log_f32_e32 v64, v64
	s_nop 0
	v_mul_f32_e32 v74, 0x3f317217, v64
	v_fma_f32 v74, v64, s24, -v74
	v_fmac_f32_e32 v74, 0x3377d1cf, v64
	v_fmac_f32_e32 v74, 0x3f317217, v64
	v_cmp_lt_f32_e64 s[8:9], |v64|, s25
	s_nop 1
	v_cndmask_b32_e64 v64, v64, v74, s[8:9]
	v_cndmask_b32_e32 v74, 0, v154, vcc
	v_sub_f32_e32 v64, v64, v74
	v_add_f32_e32 v64, v68, v64
	v_max_f32_e64 v68, -v65, 0
	v_mul_f32_e64 v65, |v65|, s86
	v_exp_f32_e32 v65, v65
	v_sub_f32_e32 v64, -0.5, v64
	v_mul_f32_e32 v64, 0x3fb8aa3b, v64
	v_exp_f32_e32 v64, v64
	v_add_f32_e32 v65, 1.0, v65
	v_cmp_gt_f32_e32 vcc, s30, v65
	v_mul_f32_e32 v64, 0xbfb8aa3b, v64
	s_nop 0
	v_cndmask_b32_e64 v69, 0, 32, vcc
	v_ldexp_f32 v65, v65, v69
	v_log_f32_e32 v65, v65
	v_exp_f32_e32 v64, v64
	v_mul_f32_e32 v69, 0x3f317217, v65
	v_fma_f32 v69, v65, s24, -v69
	v_fmac_f32_e32 v69, 0x3377d1cf, v65
	v_fmac_f32_e32 v69, 0x3f317217, v65
	v_cmp_lt_f32_e64 s[8:9], |v65|, s25
	s_nop 1
	v_cndmask_b32_e64 v65, v65, v69, s[8:9]
	v_cndmask_b32_e32 v69, 0, v154, vcc
	v_sub_f32_e32 v65, v65, v69
	v_add_f32_e32 v65, v68, v65
	v_max_f32_e64 v68, -v66, 0
	v_mul_f32_e64 v66, |v66|, s86
	v_exp_f32_e32 v66, v66
	v_sub_f32_e32 v65, -0.5, v65
	v_mul_f32_e32 v65, 0x3fb8aa3b, v65
	v_exp_f32_e32 v65, v65
	v_add_f32_e32 v66, 1.0, v66
	v_cmp_gt_f32_e32 vcc, s30, v66
	v_mul_f32_e32 v65, 0xbfb8aa3b, v65
	s_nop 0
	v_cndmask_b32_e64 v69, 0, 32, vcc
	v_ldexp_f32 v66, v66, v69
	v_log_f32_e32 v66, v66
	v_exp_f32_e32 v65, v65
	v_mul_f32_e32 v69, 0x3f317217, v66
	v_fma_f32 v69, v66, s24, -v69
	v_fmac_f32_e32 v69, 0x3377d1cf, v66
	v_fmac_f32_e32 v69, 0x3f317217, v66
	v_cmp_lt_f32_e64 s[8:9], |v66|, s25
	s_nop 1
	v_cndmask_b32_e64 v66, v66, v69, s[8:9]
	v_cndmask_b32_e32 v69, 0, v154, vcc
	v_sub_f32_e32 v66, v66, v69
	v_add_f32_e32 v66, v68, v66
	v_max_f32_e64 v68, -v67, 0
	v_mul_f32_e64 v67, |v67|, s86
	v_exp_f32_e32 v67, v67
	v_sub_f32_e32 v66, -0.5, v66
	v_mul_f32_e32 v66, 0x3fb8aa3b, v66
	v_exp_f32_e32 v66, v66
	v_add_f32_e32 v67, 1.0, v67
	v_cmp_gt_f32_e32 vcc, s30, v67
	v_mul_f32_e32 v66, 0xbfb8aa3b, v66
	s_nop 0
	v_cndmask_b32_e64 v69, 0, 32, vcc
	v_ldexp_f32 v67, v67, v69
	v_log_f32_e32 v67, v67
	v_exp_f32_e32 v66, v66
	v_mul_f32_e32 v69, 0x3f317217, v67
	v_fma_f32 v69, v67, s24, -v69
	v_fmac_f32_e32 v69, 0x3377d1cf, v67
	v_fmac_f32_e32 v69, 0x3f317217, v67
	v_cmp_lt_f32_e64 s[8:9], |v67|, s25
	s_nop 1
	v_cndmask_b32_e64 v67, v67, v69, s[8:9]
	v_cndmask_b32_e32 v69, 0, v154, vcc
	v_sub_f32_e32 v67, v67, v69
	v_add_f32_e32 v67, v68, v67
	v_sub_f32_e32 v67, -0.5, v67
	v_mul_f32_e32 v67, 0x3fb8aa3b, v67
	v_exp_f32_e32 v67, v67
	v_add_co_u32_e32 v68, vcc, s37, v146
	v_mul_f32_e32 v67, 0xbfb8aa3b, v67
	v_exp_f32_e32 v67, v67
	v_addc_co_u32_e32 v69, vcc, 0, v147, vcc
	global_store_dwordx4 v[68:69], v[64:67], off
	v_add_f32_e32 v60, v60, v228
	v_max_f32_e64 v64, -v60, 0
	v_mul_f32_e64 v60, |v60|, s86
	v_exp_f32_e32 v60, v60
	v_add_f32_e32 v61, v61, v229
	v_add_f32_e32 v62, v62, v230
	v_add_f32_e32 v63, v63, v231
	v_add_f32_e32 v60, 1.0, v60
	v_cmp_gt_f32_e32 vcc, s30, v60
	s_nop 1
	v_cndmask_b32_e64 v68, 0, 32, vcc
	v_ldexp_f32 v60, v60, v68
	v_log_f32_e32 v60, v60
	s_nop 0
	v_mul_f32_e32 v68, 0x3f317217, v60
	v_fma_f32 v68, v60, s24, -v68
	v_fmac_f32_e32 v68, 0x3377d1cf, v60
	v_fmac_f32_e32 v68, 0x3f317217, v60
	v_cmp_lt_f32_e64 s[8:9], |v60|, s25
	s_nop 1
	v_cndmask_b32_e64 v60, v60, v68, s[8:9]
	v_cndmask_b32_e32 v68, 0, v154, vcc
	v_sub_f32_e32 v60, v60, v68
	v_add_f32_e32 v60, v64, v60
	v_max_f32_e64 v64, -v61, 0
	v_mul_f32_e64 v61, |v61|, s86
	v_exp_f32_e32 v61, v61
	v_sub_f32_e32 v60, -0.5, v60
	v_mul_f32_e32 v60, 0x3fb8aa3b, v60
	v_exp_f32_e32 v60, v60
	v_add_f32_e32 v61, 1.0, v61
	v_cmp_gt_f32_e32 vcc, s30, v61
	v_mul_f32_e32 v60, 0xbfb8aa3b, v60
	s_nop 0
	v_cndmask_b32_e64 v65, 0, 32, vcc
	v_ldexp_f32 v61, v61, v65
	v_log_f32_e32 v61, v61
	v_exp_f32_e32 v60, v60
	v_mul_f32_e32 v65, 0x3f317217, v61
	v_fma_f32 v65, v61, s24, -v65
	v_fmac_f32_e32 v65, 0x3377d1cf, v61
	v_fmac_f32_e32 v65, 0x3f317217, v61
	v_cmp_lt_f32_e64 s[8:9], |v61|, s25
	s_nop 1
	v_cndmask_b32_e64 v61, v61, v65, s[8:9]
	v_cndmask_b32_e32 v65, 0, v154, vcc
	v_sub_f32_e32 v61, v61, v65
	v_add_f32_e32 v61, v64, v61
	v_max_f32_e64 v64, -v62, 0
	v_mul_f32_e64 v62, |v62|, s86
	v_exp_f32_e32 v62, v62
	v_sub_f32_e32 v61, -0.5, v61
	v_mul_f32_e32 v61, 0x3fb8aa3b, v61
	v_exp_f32_e32 v61, v61
	v_add_f32_e32 v62, 1.0, v62
	v_cmp_gt_f32_e32 vcc, s30, v62
	v_mul_f32_e32 v61, 0xbfb8aa3b, v61
	s_nop 0
	v_cndmask_b32_e64 v65, 0, 32, vcc
	v_ldexp_f32 v62, v62, v65
	v_log_f32_e32 v62, v62
	v_exp_f32_e32 v61, v61
	v_mul_f32_e32 v65, 0x3f317217, v62
	v_fma_f32 v65, v62, s24, -v65
	v_fmac_f32_e32 v65, 0x3377d1cf, v62
	v_fmac_f32_e32 v65, 0x3f317217, v62
	v_cmp_lt_f32_e64 s[8:9], |v62|, s25
	s_nop 1
	v_cndmask_b32_e64 v62, v62, v65, s[8:9]
	v_cndmask_b32_e32 v65, 0, v154, vcc
	v_sub_f32_e32 v62, v62, v65
	v_add_f32_e32 v62, v64, v62
	v_max_f32_e64 v64, -v63, 0
	v_mul_f32_e64 v63, |v63|, s86
	v_exp_f32_e32 v63, v63
	v_sub_f32_e32 v62, -0.5, v62
	v_mul_f32_e32 v62, 0x3fb8aa3b, v62
	v_exp_f32_e32 v62, v62
	v_add_f32_e32 v63, 1.0, v63
	v_cmp_gt_f32_e32 vcc, s30, v63
	v_mul_f32_e32 v62, 0xbfb8aa3b, v62
	s_nop 0
	v_cndmask_b32_e64 v65, 0, 32, vcc
	v_ldexp_f32 v63, v63, v65
	v_log_f32_e32 v63, v63
	v_exp_f32_e32 v62, v62
	v_mul_f32_e32 v65, 0x3f317217, v63
	v_fma_f32 v65, v63, s24, -v65
	v_fmac_f32_e32 v65, 0x3377d1cf, v63
	v_fmac_f32_e32 v65, 0x3f317217, v63
	v_cmp_lt_f32_e64 s[8:9], |v63|, s25
	s_nop 1
	v_cndmask_b32_e64 v63, v63, v65, s[8:9]
	v_cndmask_b32_e32 v65, 0, v154, vcc
	v_sub_f32_e32 v63, v63, v65
	v_add_f32_e32 v63, v64, v63
	v_sub_f32_e32 v63, -0.5, v63
	v_mul_f32_e32 v63, 0x3fb8aa3b, v63
	v_exp_f32_e32 v63, v63
	s_nop 0
	v_mul_f32_e32 v63, 0xbfb8aa3b, v63
	v_exp_f32_e32 v63, v63
	global_store_dwordx4 v[72:73], v[60:63], off offset:64
	v_add_f32_e32 v56, v56, v232
	v_max_f32_e64 v60, -v56, 0
	v_mul_f32_e64 v56, |v56|, s86
	v_exp_f32_e32 v56, v56
	v_add_f32_e32 v57, v57, v233
	v_add_f32_e32 v58, v58, v234
	v_add_f32_e32 v59, v59, v235
	v_add_f32_e32 v56, 1.0, v56
	v_cmp_gt_f32_e32 vcc, s30, v56
	s_nop 1
	v_cndmask_b32_e64 v64, 0, 32, vcc
	v_ldexp_f32 v56, v56, v64
	v_log_f32_e32 v56, v56
	s_nop 0
	v_mul_f32_e32 v64, 0x3f317217, v56
	v_fma_f32 v64, v56, s24, -v64
	v_fmac_f32_e32 v64, 0x3377d1cf, v56
	v_fmac_f32_e32 v64, 0x3f317217, v56
	v_cmp_lt_f32_e64 s[8:9], |v56|, s25
	s_nop 1
	v_cndmask_b32_e64 v56, v56, v64, s[8:9]
	v_cndmask_b32_e32 v64, 0, v154, vcc
	v_sub_f32_e32 v56, v56, v64
	v_add_f32_e32 v56, v60, v56
	v_max_f32_e64 v60, -v57, 0
	v_mul_f32_e64 v57, |v57|, s86
	v_exp_f32_e32 v57, v57
	v_sub_f32_e32 v56, -0.5, v56
	v_mul_f32_e32 v56, 0x3fb8aa3b, v56
	v_exp_f32_e32 v56, v56
	v_add_f32_e32 v57, 1.0, v57
	v_cmp_gt_f32_e32 vcc, s30, v57
	v_mul_f32_e32 v56, 0xbfb8aa3b, v56
	s_nop 0
	v_cndmask_b32_e64 v61, 0, 32, vcc
	v_ldexp_f32 v57, v57, v61
	v_log_f32_e32 v57, v57
	v_exp_f32_e32 v56, v56
	v_mul_f32_e32 v61, 0x3f317217, v57
	v_fma_f32 v61, v57, s24, -v61
	v_fmac_f32_e32 v61, 0x3377d1cf, v57
	v_fmac_f32_e32 v61, 0x3f317217, v57
	v_cmp_lt_f32_e64 s[8:9], |v57|, s25
	s_nop 1
	v_cndmask_b32_e64 v57, v57, v61, s[8:9]
	v_cndmask_b32_e32 v61, 0, v154, vcc
	v_sub_f32_e32 v57, v57, v61
	v_add_f32_e32 v57, v60, v57
	v_max_f32_e64 v60, -v58, 0
	v_mul_f32_e64 v58, |v58|, s86
	v_exp_f32_e32 v58, v58
	v_sub_f32_e32 v57, -0.5, v57
	v_mul_f32_e32 v57, 0x3fb8aa3b, v57
	v_exp_f32_e32 v57, v57
	v_add_f32_e32 v58, 1.0, v58
	v_cmp_gt_f32_e32 vcc, s30, v58
	v_mul_f32_e32 v57, 0xbfb8aa3b, v57
	s_nop 0
	v_cndmask_b32_e64 v61, 0, 32, vcc
	v_ldexp_f32 v58, v58, v61
	v_log_f32_e32 v58, v58
	v_exp_f32_e32 v57, v57
	v_mul_f32_e32 v61, 0x3f317217, v58
	v_fma_f32 v61, v58, s24, -v61
	v_fmac_f32_e32 v61, 0x3377d1cf, v58
	v_fmac_f32_e32 v61, 0x3f317217, v58
	v_cmp_lt_f32_e64 s[8:9], |v58|, s25
	s_nop 1
	v_cndmask_b32_e64 v58, v58, v61, s[8:9]
	v_cndmask_b32_e32 v61, 0, v154, vcc
	v_sub_f32_e32 v58, v58, v61
	v_add_f32_e32 v58, v60, v58
	v_max_f32_e64 v60, -v59, 0
	v_mul_f32_e64 v59, |v59|, s86
	v_exp_f32_e32 v59, v59
	v_sub_f32_e32 v58, -0.5, v58
	v_mul_f32_e32 v58, 0x3fb8aa3b, v58
	v_exp_f32_e32 v58, v58
	v_add_f32_e32 v59, 1.0, v59
	v_cmp_gt_f32_e32 vcc, s30, v59
	v_mul_f32_e32 v58, 0xbfb8aa3b, v58
	s_nop 0
	v_cndmask_b32_e64 v61, 0, 32, vcc
	v_ldexp_f32 v59, v59, v61
	v_log_f32_e32 v59, v59
	v_exp_f32_e32 v58, v58
	v_mul_f32_e32 v61, 0x3f317217, v59
	v_fma_f32 v61, v59, s24, -v61
	v_fmac_f32_e32 v61, 0x3377d1cf, v59
	v_fmac_f32_e32 v61, 0x3f317217, v59
	v_cmp_lt_f32_e64 s[8:9], |v59|, s25
	s_nop 1
	v_cndmask_b32_e64 v59, v59, v61, s[8:9]
	v_cndmask_b32_e32 v61, 0, v154, vcc
	v_sub_f32_e32 v59, v59, v61
	v_add_f32_e32 v59, v60, v59
	v_sub_f32_e32 v59, -0.5, v59
	v_mul_f32_e32 v59, 0x3fb8aa3b, v59
	v_exp_f32_e32 v59, v59
	s_nop 0
	v_mul_f32_e32 v59, 0xbfb8aa3b, v59
	v_exp_f32_e32 v59, v59
	global_store_dwordx4 v[72:73], v[56:59], off offset:512
	v_add_f32_e32 v52, v52, v236
	v_max_f32_e64 v56, -v52, 0
	v_mul_f32_e64 v52, |v52|, s86
	v_exp_f32_e32 v52, v52
	v_add_f32_e32 v53, v53, v237
	v_add_f32_e32 v54, v54, v238
	v_add_f32_e32 v55, v55, v239
	v_add_f32_e32 v52, 1.0, v52
	v_cmp_gt_f32_e32 vcc, s30, v52
	s_nop 1
	v_cndmask_b32_e64 v60, 0, 32, vcc
	v_ldexp_f32 v52, v52, v60
	v_log_f32_e32 v52, v52
	s_nop 0
	v_mul_f32_e32 v60, 0x3f317217, v52
	v_fma_f32 v60, v52, s24, -v60
	v_fmac_f32_e32 v60, 0x3377d1cf, v52
	v_fmac_f32_e32 v60, 0x3f317217, v52
	v_cmp_lt_f32_e64 s[8:9], |v52|, s25
	s_nop 1
	v_cndmask_b32_e64 v52, v52, v60, s[8:9]
	v_cndmask_b32_e32 v60, 0, v154, vcc
	v_sub_f32_e32 v52, v52, v60
	v_add_f32_e32 v52, v56, v52
	v_max_f32_e64 v56, -v53, 0
	v_mul_f32_e64 v53, |v53|, s86
	v_exp_f32_e32 v53, v53
	v_sub_f32_e32 v52, -0.5, v52
	v_mul_f32_e32 v52, 0x3fb8aa3b, v52
	v_exp_f32_e32 v52, v52
	v_add_f32_e32 v53, 1.0, v53
	v_cmp_gt_f32_e32 vcc, s30, v53
	v_mul_f32_e32 v52, 0xbfb8aa3b, v52
	s_nop 0
	v_cndmask_b32_e64 v57, 0, 32, vcc
	v_ldexp_f32 v53, v53, v57
	v_log_f32_e32 v53, v53
	v_exp_f32_e32 v52, v52
	v_mul_f32_e32 v57, 0x3f317217, v53
	v_fma_f32 v57, v53, s24, -v57
	v_fmac_f32_e32 v57, 0x3377d1cf, v53
	v_fmac_f32_e32 v57, 0x3f317217, v53
	v_cmp_lt_f32_e64 s[8:9], |v53|, s25
	s_nop 1
	v_cndmask_b32_e64 v53, v53, v57, s[8:9]
	v_cndmask_b32_e32 v57, 0, v154, vcc
	v_sub_f32_e32 v53, v53, v57
	v_add_f32_e32 v53, v56, v53
	v_max_f32_e64 v56, -v54, 0
	v_mul_f32_e64 v54, |v54|, s86
	v_exp_f32_e32 v54, v54
	v_sub_f32_e32 v53, -0.5, v53
	v_mul_f32_e32 v53, 0x3fb8aa3b, v53
	v_exp_f32_e32 v53, v53
	v_add_f32_e32 v54, 1.0, v54
	v_cmp_gt_f32_e32 vcc, s30, v54
	v_mul_f32_e32 v53, 0xbfb8aa3b, v53
	s_nop 0
	v_cndmask_b32_e64 v57, 0, 32, vcc
	v_ldexp_f32 v54, v54, v57
	v_log_f32_e32 v54, v54
	v_exp_f32_e32 v53, v53
	v_mul_f32_e32 v57, 0x3f317217, v54
	v_fma_f32 v57, v54, s24, -v57
	v_fmac_f32_e32 v57, 0x3377d1cf, v54
	v_fmac_f32_e32 v57, 0x3f317217, v54
	v_cmp_lt_f32_e64 s[8:9], |v54|, s25
	s_nop 1
	v_cndmask_b32_e64 v54, v54, v57, s[8:9]
	v_cndmask_b32_e32 v57, 0, v154, vcc
	v_sub_f32_e32 v54, v54, v57
	v_add_f32_e32 v54, v56, v54
	v_max_f32_e64 v56, -v55, 0
	v_mul_f32_e64 v55, |v55|, s86
	v_exp_f32_e32 v55, v55
	v_sub_f32_e32 v54, -0.5, v54
	v_mul_f32_e32 v54, 0x3fb8aa3b, v54
	v_exp_f32_e32 v54, v54
	v_add_f32_e32 v55, 1.0, v55
	v_cmp_gt_f32_e32 vcc, s30, v55
	v_mul_f32_e32 v54, 0xbfb8aa3b, v54
	s_nop 0
	v_cndmask_b32_e64 v57, 0, 32, vcc
	v_ldexp_f32 v55, v55, v57
	v_log_f32_e32 v55, v55
	v_exp_f32_e32 v54, v54
	v_mul_f32_e32 v57, 0x3f317217, v55
	v_fma_f32 v57, v55, s24, -v57
	v_fmac_f32_e32 v57, 0x3377d1cf, v55
	v_fmac_f32_e32 v57, 0x3f317217, v55
	v_cmp_lt_f32_e64 s[8:9], |v55|, s25
	s_nop 1
	v_cndmask_b32_e64 v55, v55, v57, s[8:9]
	v_cndmask_b32_e32 v57, 0, v154, vcc
	v_sub_f32_e32 v55, v55, v57
	v_add_f32_e32 v55, v56, v55
	v_sub_f32_e32 v55, -0.5, v55
	v_mul_f32_e32 v55, 0x3fb8aa3b, v55
	v_exp_f32_e32 v55, v55
	v_lshl_add_u64 v[56:57], v[146:147], 0, s[44:45]
	v_mul_f32_e32 v55, 0xbfb8aa3b, v55
	v_exp_f32_e32 v55, v55
	global_store_dwordx4 v[72:73], v[52:55], off offset:576
	v_add_f32_e32 v48, v48, v224
	v_max_f32_e64 v52, -v48, 0
	v_mul_f32_e64 v48, |v48|, s86
	v_exp_f32_e32 v48, v48
	v_add_f32_e32 v49, v49, v225
	v_add_f32_e32 v50, v50, v226
	v_add_f32_e32 v51, v51, v227
	v_add_f32_e32 v48, 1.0, v48
	v_cmp_gt_f32_e32 vcc, s30, v48
	s_nop 1
	v_cndmask_b32_e64 v58, 0, 32, vcc
	v_ldexp_f32 v48, v48, v58
	v_log_f32_e32 v48, v48
	s_nop 0
	v_mul_f32_e32 v58, 0x3f317217, v48
	v_fma_f32 v58, v48, s24, -v58
	v_fmac_f32_e32 v58, 0x3377d1cf, v48
	v_fmac_f32_e32 v58, 0x3f317217, v48
	v_cmp_lt_f32_e64 s[8:9], |v48|, s25
	s_nop 1
	v_cndmask_b32_e64 v48, v48, v58, s[8:9]
	v_cndmask_b32_e32 v58, 0, v154, vcc
	v_sub_f32_e32 v48, v48, v58
	v_add_f32_e32 v48, v52, v48
	v_max_f32_e64 v52, -v49, 0
	v_mul_f32_e64 v49, |v49|, s86
	v_exp_f32_e32 v49, v49
	v_sub_f32_e32 v48, -0.5, v48
	v_mul_f32_e32 v48, 0x3fb8aa3b, v48
	v_exp_f32_e32 v48, v48
	v_add_f32_e32 v49, 1.0, v49
	v_cmp_gt_f32_e32 vcc, s30, v49
	v_mul_f32_e32 v48, 0xbfb8aa3b, v48
	s_nop 0
	v_cndmask_b32_e64 v53, 0, 32, vcc
	v_ldexp_f32 v49, v49, v53
	v_log_f32_e32 v49, v49
	v_exp_f32_e32 v48, v48
	v_mul_f32_e32 v53, 0x3f317217, v49
	v_fma_f32 v53, v49, s24, -v53
	v_fmac_f32_e32 v53, 0x3377d1cf, v49
	v_fmac_f32_e32 v53, 0x3f317217, v49
	v_cmp_lt_f32_e64 s[8:9], |v49|, s25
	s_nop 1
	v_cndmask_b32_e64 v49, v49, v53, s[8:9]
	v_cndmask_b32_e32 v53, 0, v154, vcc
	v_sub_f32_e32 v49, v49, v53
	v_add_f32_e32 v49, v52, v49
	v_max_f32_e64 v52, -v50, 0
	v_mul_f32_e64 v50, |v50|, s86
	v_exp_f32_e32 v50, v50
	v_sub_f32_e32 v49, -0.5, v49
	v_mul_f32_e32 v49, 0x3fb8aa3b, v49
	v_exp_f32_e32 v49, v49
	v_add_f32_e32 v50, 1.0, v50
	v_cmp_gt_f32_e32 vcc, s30, v50
	v_mul_f32_e32 v49, 0xbfb8aa3b, v49
	s_nop 0
	v_cndmask_b32_e64 v53, 0, 32, vcc
	v_ldexp_f32 v50, v50, v53
	v_log_f32_e32 v50, v50
	v_exp_f32_e32 v49, v49
	v_mul_f32_e32 v53, 0x3f317217, v50
	v_fma_f32 v53, v50, s24, -v53
	v_fmac_f32_e32 v53, 0x3377d1cf, v50
	v_fmac_f32_e32 v53, 0x3f317217, v50
	v_cmp_lt_f32_e64 s[8:9], |v50|, s25
	s_nop 1
	v_cndmask_b32_e64 v50, v50, v53, s[8:9]
	v_cndmask_b32_e32 v53, 0, v154, vcc
	v_sub_f32_e32 v50, v50, v53
	v_add_f32_e32 v50, v52, v50
	v_max_f32_e64 v52, -v51, 0
	v_mul_f32_e64 v51, |v51|, s86
	v_exp_f32_e32 v51, v51
	v_sub_f32_e32 v50, -0.5, v50
	v_mul_f32_e32 v50, 0x3fb8aa3b, v50
	v_exp_f32_e32 v50, v50
	v_add_f32_e32 v51, 1.0, v51
	v_cmp_gt_f32_e32 vcc, s30, v51
	v_mul_f32_e32 v50, 0xbfb8aa3b, v50
	s_nop 0
	v_cndmask_b32_e64 v53, 0, 32, vcc
	v_ldexp_f32 v51, v51, v53
	v_log_f32_e32 v51, v51
	v_exp_f32_e32 v50, v50
	v_mul_f32_e32 v53, 0x3f317217, v51
	v_fma_f32 v53, v51, s24, -v53
	v_fmac_f32_e32 v53, 0x3377d1cf, v51
	v_fmac_f32_e32 v53, 0x3f317217, v51
	v_cmp_lt_f32_e64 s[8:9], |v51|, s25
	s_nop 1
	v_cndmask_b32_e64 v51, v51, v53, s[8:9]
	v_cndmask_b32_e32 v53, 0, v154, vcc
	v_sub_f32_e32 v51, v51, v53
	v_add_f32_e32 v51, v52, v51
	v_sub_f32_e32 v51, -0.5, v51
	v_mul_f32_e32 v51, 0x3fb8aa3b, v51
	v_exp_f32_e32 v51, v51
	v_add_co_u32_e32 v52, vcc, s46, v146
	v_mul_f32_e32 v51, 0xbfb8aa3b, v51
	v_exp_f32_e32 v51, v51
	v_addc_co_u32_e32 v53, vcc, 0, v147, vcc
	global_store_dwordx4 v[52:53], v[48:51], off
	v_add_f32_e32 v44, v44, v228
	v_max_f32_e64 v48, -v44, 0
	v_mul_f32_e64 v44, |v44|, s86
	v_exp_f32_e32 v44, v44
	v_add_f32_e32 v45, v45, v229
	v_add_f32_e32 v46, v46, v230
	v_add_f32_e32 v47, v47, v231
	v_add_f32_e32 v44, 1.0, v44
	v_cmp_gt_f32_e32 vcc, s30, v44
	s_nop 1
	v_cndmask_b32_e64 v52, 0, 32, vcc
	v_ldexp_f32 v44, v44, v52
	v_log_f32_e32 v44, v44
	s_nop 0
	v_mul_f32_e32 v52, 0x3f317217, v44
	v_fma_f32 v52, v44, s24, -v52
	v_fmac_f32_e32 v52, 0x3377d1cf, v44
	v_fmac_f32_e32 v52, 0x3f317217, v44
	v_cmp_lt_f32_e64 s[8:9], |v44|, s25
	s_nop 1
	v_cndmask_b32_e64 v44, v44, v52, s[8:9]
	v_cndmask_b32_e32 v52, 0, v154, vcc
	v_sub_f32_e32 v44, v44, v52
	v_add_f32_e32 v44, v48, v44
	v_max_f32_e64 v48, -v45, 0
	v_mul_f32_e64 v45, |v45|, s86
	v_exp_f32_e32 v45, v45
	v_sub_f32_e32 v44, -0.5, v44
	v_mul_f32_e32 v44, 0x3fb8aa3b, v44
	v_exp_f32_e32 v44, v44
	v_add_f32_e32 v45, 1.0, v45
	v_cmp_gt_f32_e32 vcc, s30, v45
	v_mul_f32_e32 v44, 0xbfb8aa3b, v44
	s_nop 0
	v_cndmask_b32_e64 v49, 0, 32, vcc
	v_ldexp_f32 v45, v45, v49
	v_log_f32_e32 v45, v45
	v_exp_f32_e32 v44, v44
	v_mul_f32_e32 v49, 0x3f317217, v45
	v_fma_f32 v49, v45, s24, -v49
	v_fmac_f32_e32 v49, 0x3377d1cf, v45
	v_fmac_f32_e32 v49, 0x3f317217, v45
	v_cmp_lt_f32_e64 s[8:9], |v45|, s25
	s_nop 1
	v_cndmask_b32_e64 v45, v45, v49, s[8:9]
	v_cndmask_b32_e32 v49, 0, v154, vcc
	v_sub_f32_e32 v45, v45, v49
	v_add_f32_e32 v45, v48, v45
	v_max_f32_e64 v48, -v46, 0
	v_mul_f32_e64 v46, |v46|, s86
	v_exp_f32_e32 v46, v46
	v_sub_f32_e32 v45, -0.5, v45
	v_mul_f32_e32 v45, 0x3fb8aa3b, v45
	v_exp_f32_e32 v45, v45
	v_add_f32_e32 v46, 1.0, v46
	v_cmp_gt_f32_e32 vcc, s30, v46
	v_mul_f32_e32 v45, 0xbfb8aa3b, v45
	s_nop 0
	v_cndmask_b32_e64 v49, 0, 32, vcc
	v_ldexp_f32 v46, v46, v49
	v_log_f32_e32 v46, v46
	v_exp_f32_e32 v45, v45
	v_mul_f32_e32 v49, 0x3f317217, v46
	v_fma_f32 v49, v46, s24, -v49
	v_fmac_f32_e32 v49, 0x3377d1cf, v46
	v_fmac_f32_e32 v49, 0x3f317217, v46
	v_cmp_lt_f32_e64 s[8:9], |v46|, s25
	s_nop 1
	v_cndmask_b32_e64 v46, v46, v49, s[8:9]
	v_cndmask_b32_e32 v49, 0, v154, vcc
	v_sub_f32_e32 v46, v46, v49
	v_add_f32_e32 v46, v48, v46
	v_max_f32_e64 v48, -v47, 0
	v_mul_f32_e64 v47, |v47|, s86
	v_exp_f32_e32 v47, v47
	v_sub_f32_e32 v46, -0.5, v46
	v_mul_f32_e32 v46, 0x3fb8aa3b, v46
	v_exp_f32_e32 v46, v46
	v_add_f32_e32 v47, 1.0, v47
	v_cmp_gt_f32_e32 vcc, s30, v47
	v_mul_f32_e32 v46, 0xbfb8aa3b, v46
	s_nop 0
	v_cndmask_b32_e64 v49, 0, 32, vcc
	v_ldexp_f32 v47, v47, v49
	v_log_f32_e32 v47, v47
	v_exp_f32_e32 v46, v46
	v_mul_f32_e32 v49, 0x3f317217, v47
	v_fma_f32 v49, v47, s24, -v49
	v_fmac_f32_e32 v49, 0x3377d1cf, v47
	v_fmac_f32_e32 v49, 0x3f317217, v47
	v_cmp_lt_f32_e64 s[8:9], |v47|, s25
	s_nop 1
	v_cndmask_b32_e64 v47, v47, v49, s[8:9]
	v_cndmask_b32_e32 v49, 0, v154, vcc
	v_sub_f32_e32 v47, v47, v49
	v_add_f32_e32 v47, v48, v47
	v_sub_f32_e32 v47, -0.5, v47
	v_mul_f32_e32 v47, 0x3fb8aa3b, v47
	v_exp_f32_e32 v47, v47
	s_nop 0
	v_mul_f32_e32 v47, 0xbfb8aa3b, v47
	v_exp_f32_e32 v47, v47
	global_store_dwordx4 v[56:57], v[44:47], off offset:64
	v_add_f32_e32 v40, v40, v232
	v_max_f32_e64 v44, -v40, 0
	v_mul_f32_e64 v40, |v40|, s86
	v_exp_f32_e32 v40, v40
	v_add_f32_e32 v41, v41, v233
	v_add_f32_e32 v42, v42, v234
	v_add_f32_e32 v43, v43, v235
	v_add_f32_e32 v40, 1.0, v40
	v_cmp_gt_f32_e32 vcc, s30, v40
	s_nop 1
	v_cndmask_b32_e64 v48, 0, 32, vcc
	v_ldexp_f32 v40, v40, v48
	v_log_f32_e32 v40, v40
	s_nop 0
	v_mul_f32_e32 v48, 0x3f317217, v40
	v_fma_f32 v48, v40, s24, -v48
	v_fmac_f32_e32 v48, 0x3377d1cf, v40
	v_fmac_f32_e32 v48, 0x3f317217, v40
	v_cmp_lt_f32_e64 s[8:9], |v40|, s25
	s_nop 1
	v_cndmask_b32_e64 v40, v40, v48, s[8:9]
	v_cndmask_b32_e32 v48, 0, v154, vcc
	v_sub_f32_e32 v40, v40, v48
	v_add_f32_e32 v40, v44, v40
	v_max_f32_e64 v44, -v41, 0
	v_mul_f32_e64 v41, |v41|, s86
	v_exp_f32_e32 v41, v41
	v_sub_f32_e32 v40, -0.5, v40
	v_mul_f32_e32 v40, 0x3fb8aa3b, v40
	v_exp_f32_e32 v40, v40
	v_add_f32_e32 v41, 1.0, v41
	v_cmp_gt_f32_e32 vcc, s30, v41
	v_mul_f32_e32 v40, 0xbfb8aa3b, v40
	s_nop 0
	v_cndmask_b32_e64 v45, 0, 32, vcc
	v_ldexp_f32 v41, v41, v45
	v_log_f32_e32 v41, v41
	v_exp_f32_e32 v40, v40
	v_mul_f32_e32 v45, 0x3f317217, v41
	v_fma_f32 v45, v41, s24, -v45
	v_fmac_f32_e32 v45, 0x3377d1cf, v41
	v_fmac_f32_e32 v45, 0x3f317217, v41
	v_cmp_lt_f32_e64 s[8:9], |v41|, s25
	s_nop 1
	v_cndmask_b32_e64 v41, v41, v45, s[8:9]
	v_cndmask_b32_e32 v45, 0, v154, vcc
	v_sub_f32_e32 v41, v41, v45
	v_add_f32_e32 v41, v44, v41
	v_max_f32_e64 v44, -v42, 0
	v_mul_f32_e64 v42, |v42|, s86
	v_exp_f32_e32 v42, v42
	v_sub_f32_e32 v41, -0.5, v41
	v_mul_f32_e32 v41, 0x3fb8aa3b, v41
	v_exp_f32_e32 v41, v41
	v_add_f32_e32 v42, 1.0, v42
	v_cmp_gt_f32_e32 vcc, s30, v42
	v_mul_f32_e32 v41, 0xbfb8aa3b, v41
	s_nop 0
	v_cndmask_b32_e64 v45, 0, 32, vcc
	v_ldexp_f32 v42, v42, v45
	v_log_f32_e32 v42, v42
	v_exp_f32_e32 v41, v41
	v_mul_f32_e32 v45, 0x3f317217, v42
	v_fma_f32 v45, v42, s24, -v45
	v_fmac_f32_e32 v45, 0x3377d1cf, v42
	v_fmac_f32_e32 v45, 0x3f317217, v42
	v_cmp_lt_f32_e64 s[8:9], |v42|, s25
	s_nop 1
	v_cndmask_b32_e64 v42, v42, v45, s[8:9]
	v_cndmask_b32_e32 v45, 0, v154, vcc
	v_sub_f32_e32 v42, v42, v45
	v_add_f32_e32 v42, v44, v42
	v_max_f32_e64 v44, -v43, 0
	v_mul_f32_e64 v43, |v43|, s86
	v_exp_f32_e32 v43, v43
	v_sub_f32_e32 v42, -0.5, v42
	v_mul_f32_e32 v42, 0x3fb8aa3b, v42
	v_exp_f32_e32 v42, v42
	v_add_f32_e32 v43, 1.0, v43
	v_cmp_gt_f32_e32 vcc, s30, v43
	v_mul_f32_e32 v42, 0xbfb8aa3b, v42
	s_nop 0
	v_cndmask_b32_e64 v45, 0, 32, vcc
	v_ldexp_f32 v43, v43, v45
	v_log_f32_e32 v43, v43
	v_exp_f32_e32 v42, v42
	v_mul_f32_e32 v45, 0x3f317217, v43
	v_fma_f32 v45, v43, s24, -v45
	v_fmac_f32_e32 v45, 0x3377d1cf, v43
	v_fmac_f32_e32 v45, 0x3f317217, v43
	v_cmp_lt_f32_e64 s[8:9], |v43|, s25
	s_nop 1
	v_cndmask_b32_e64 v43, v43, v45, s[8:9]
	v_cndmask_b32_e32 v45, 0, v154, vcc
	v_sub_f32_e32 v43, v43, v45
	v_add_f32_e32 v43, v44, v43
	v_sub_f32_e32 v43, -0.5, v43
	v_mul_f32_e32 v43, 0x3fb8aa3b, v43
	v_exp_f32_e32 v43, v43
	s_nop 0
	v_mul_f32_e32 v43, 0xbfb8aa3b, v43
	v_exp_f32_e32 v43, v43
	global_store_dwordx4 v[56:57], v[40:43], off offset:512
	v_add_f32_e32 v36, v36, v236
	v_max_f32_e64 v40, -v36, 0
	v_mul_f32_e64 v36, |v36|, s86
	v_exp_f32_e32 v36, v36
	v_add_f32_e32 v37, v37, v237
	v_add_f32_e32 v38, v38, v238
	v_add_f32_e32 v39, v39, v239
	v_add_f32_e32 v36, 1.0, v36
	v_cmp_gt_f32_e32 vcc, s30, v36
	s_nop 1
	v_cndmask_b32_e64 v44, 0, 32, vcc
	v_ldexp_f32 v36, v36, v44
	v_log_f32_e32 v36, v36
	s_nop 0
	v_mul_f32_e32 v44, 0x3f317217, v36
	v_fma_f32 v44, v36, s24, -v44
	v_fmac_f32_e32 v44, 0x3377d1cf, v36
	v_fmac_f32_e32 v44, 0x3f317217, v36
	v_cmp_lt_f32_e64 s[8:9], |v36|, s25
	s_nop 1
	v_cndmask_b32_e64 v36, v36, v44, s[8:9]
	v_cndmask_b32_e32 v44, 0, v154, vcc
	v_sub_f32_e32 v36, v36, v44
	v_add_f32_e32 v36, v40, v36
	v_max_f32_e64 v40, -v37, 0
	v_mul_f32_e64 v37, |v37|, s86
	v_exp_f32_e32 v37, v37
	v_sub_f32_e32 v36, -0.5, v36
	v_mul_f32_e32 v36, 0x3fb8aa3b, v36
	v_exp_f32_e32 v36, v36
	v_add_f32_e32 v37, 1.0, v37
	v_cmp_gt_f32_e32 vcc, s30, v37
	v_mul_f32_e32 v36, 0xbfb8aa3b, v36
	s_nop 0
	v_cndmask_b32_e64 v41, 0, 32, vcc
	v_ldexp_f32 v37, v37, v41
	v_log_f32_e32 v37, v37
	v_exp_f32_e32 v36, v36
	v_mul_f32_e32 v41, 0x3f317217, v37
	v_fma_f32 v41, v37, s24, -v41
	v_fmac_f32_e32 v41, 0x3377d1cf, v37
	v_fmac_f32_e32 v41, 0x3f317217, v37
	v_cmp_lt_f32_e64 s[8:9], |v37|, s25
	s_nop 1
	v_cndmask_b32_e64 v37, v37, v41, s[8:9]
	v_cndmask_b32_e32 v41, 0, v154, vcc
	v_sub_f32_e32 v37, v37, v41
	v_add_f32_e32 v37, v40, v37
	v_max_f32_e64 v40, -v38, 0
	v_mul_f32_e64 v38, |v38|, s86
	v_exp_f32_e32 v38, v38
	v_sub_f32_e32 v37, -0.5, v37
	v_mul_f32_e32 v37, 0x3fb8aa3b, v37
	v_exp_f32_e32 v37, v37
	v_add_f32_e32 v38, 1.0, v38
	v_cmp_gt_f32_e32 vcc, s30, v38
	v_mul_f32_e32 v37, 0xbfb8aa3b, v37
	s_nop 0
	v_cndmask_b32_e64 v41, 0, 32, vcc
	v_ldexp_f32 v38, v38, v41
	v_log_f32_e32 v38, v38
	v_exp_f32_e32 v37, v37
	v_mul_f32_e32 v41, 0x3f317217, v38
	v_fma_f32 v41, v38, s24, -v41
	v_fmac_f32_e32 v41, 0x3377d1cf, v38
	v_fmac_f32_e32 v41, 0x3f317217, v38
	v_cmp_lt_f32_e64 s[8:9], |v38|, s25
	s_nop 1
	v_cndmask_b32_e64 v38, v38, v41, s[8:9]
	v_cndmask_b32_e32 v41, 0, v154, vcc
	v_sub_f32_e32 v38, v38, v41
	v_add_f32_e32 v38, v40, v38
	v_max_f32_e64 v40, -v39, 0
	v_mul_f32_e64 v39, |v39|, s86
	v_exp_f32_e32 v39, v39
	v_sub_f32_e32 v38, -0.5, v38
	v_mul_f32_e32 v38, 0x3fb8aa3b, v38
	v_exp_f32_e32 v38, v38
	v_add_f32_e32 v39, 1.0, v39
	v_cmp_gt_f32_e32 vcc, s30, v39
	v_mul_f32_e32 v38, 0xbfb8aa3b, v38
	s_nop 0
	v_cndmask_b32_e64 v41, 0, 32, vcc
	v_ldexp_f32 v39, v39, v41
	v_log_f32_e32 v39, v39
	v_exp_f32_e32 v38, v38
	v_mul_f32_e32 v41, 0x3f317217, v39
	v_fma_f32 v41, v39, s24, -v41
	v_fmac_f32_e32 v41, 0x3377d1cf, v39
	v_fmac_f32_e32 v41, 0x3f317217, v39
	v_cmp_lt_f32_e64 s[8:9], |v39|, s25
	s_nop 1
	v_cndmask_b32_e64 v39, v39, v41, s[8:9]
	v_cndmask_b32_e32 v41, 0, v154, vcc
	v_sub_f32_e32 v39, v39, v41
	v_add_f32_e32 v39, v40, v39
	v_sub_f32_e32 v39, -0.5, v39
	v_mul_f32_e32 v39, 0x3fb8aa3b, v39
	v_exp_f32_e32 v39, v39
	v_lshl_add_u64 v[40:41], v[146:147], 0, s[48:49]
	v_mul_f32_e32 v39, 0xbfb8aa3b, v39
	v_exp_f32_e32 v39, v39
	global_store_dwordx4 v[56:57], v[36:39], off offset:576
	v_add_f32_e32 v30, v30, v224
	v_max_f32_e64 v36, -v30, 0
	v_mul_f32_e64 v30, |v30|, s86
	v_exp_f32_e32 v30, v30
	v_add_f32_e32 v31, v31, v225
	v_add_f32_e32 v32, v32, v226
	v_add_f32_e32 v33, v33, v227
	v_add_f32_e32 v30, 1.0, v30
	v_cmp_gt_f32_e32 vcc, s30, v30
	s_nop 1
	v_cndmask_b32_e64 v42, 0, 32, vcc
	v_ldexp_f32 v30, v30, v42
	v_log_f32_e32 v30, v30
	s_nop 0
	v_mul_f32_e32 v42, 0x3f317217, v30
	v_fma_f32 v42, v30, s24, -v42
	v_fmac_f32_e32 v42, 0x3377d1cf, v30
	v_fmac_f32_e32 v42, 0x3f317217, v30
	v_cmp_lt_f32_e64 s[8:9], |v30|, s25
	s_nop 1
	v_cndmask_b32_e64 v30, v30, v42, s[8:9]
	v_cndmask_b32_e32 v42, 0, v154, vcc
	v_sub_f32_e32 v30, v30, v42
	v_add_f32_e32 v30, v36, v30
	v_max_f32_e64 v36, -v31, 0
	v_mul_f32_e64 v31, |v31|, s86
	v_exp_f32_e32 v31, v31
	v_sub_f32_e32 v30, -0.5, v30
	v_mul_f32_e32 v30, 0x3fb8aa3b, v30
	v_exp_f32_e32 v30, v30
	v_add_f32_e32 v31, 1.0, v31
	v_cmp_gt_f32_e32 vcc, s30, v31
	v_mul_f32_e32 v30, 0xbfb8aa3b, v30
	s_nop 0
	v_cndmask_b32_e64 v37, 0, 32, vcc
	v_ldexp_f32 v31, v31, v37
	v_log_f32_e32 v31, v31
	v_exp_f32_e32 v30, v30
	v_mul_f32_e32 v37, 0x3f317217, v31
	v_fma_f32 v37, v31, s24, -v37
	v_fmac_f32_e32 v37, 0x3377d1cf, v31
	v_fmac_f32_e32 v37, 0x3f317217, v31
	v_cmp_lt_f32_e64 s[8:9], |v31|, s25
	s_nop 1
	v_cndmask_b32_e64 v31, v31, v37, s[8:9]
	v_cndmask_b32_e32 v37, 0, v154, vcc
	v_sub_f32_e32 v31, v31, v37
	v_add_f32_e32 v31, v36, v31
	v_max_f32_e64 v36, -v32, 0
	v_mul_f32_e64 v32, |v32|, s86
	v_exp_f32_e32 v32, v32
	v_sub_f32_e32 v31, -0.5, v31
	v_mul_f32_e32 v31, 0x3fb8aa3b, v31
	v_exp_f32_e32 v31, v31
	v_add_f32_e32 v32, 1.0, v32
	v_cmp_gt_f32_e32 vcc, s30, v32
	v_mul_f32_e32 v31, 0xbfb8aa3b, v31
	s_nop 0
	v_cndmask_b32_e64 v37, 0, 32, vcc
	v_ldexp_f32 v32, v32, v37
	v_log_f32_e32 v32, v32
	v_exp_f32_e32 v31, v31
	v_mul_f32_e32 v37, 0x3f317217, v32
	v_fma_f32 v37, v32, s24, -v37
	v_fmac_f32_e32 v37, 0x3377d1cf, v32
	v_fmac_f32_e32 v37, 0x3f317217, v32
	v_cmp_lt_f32_e64 s[8:9], |v32|, s25
	s_nop 1
	v_cndmask_b32_e64 v32, v32, v37, s[8:9]
	v_cndmask_b32_e32 v37, 0, v154, vcc
	v_sub_f32_e32 v32, v32, v37
	v_add_f32_e32 v32, v36, v32
	v_max_f32_e64 v36, -v33, 0
	v_mul_f32_e64 v33, |v33|, s86
	v_exp_f32_e32 v33, v33
	v_sub_f32_e32 v32, -0.5, v32
	v_mul_f32_e32 v32, 0x3fb8aa3b, v32
	v_exp_f32_e32 v32, v32
	v_add_f32_e32 v33, 1.0, v33
	v_cmp_gt_f32_e32 vcc, s30, v33
	v_mul_f32_e32 v32, 0xbfb8aa3b, v32
	s_nop 0
	v_cndmask_b32_e64 v37, 0, 32, vcc
	v_ldexp_f32 v33, v33, v37
	v_log_f32_e32 v33, v33
	v_exp_f32_e32 v32, v32
	v_mul_f32_e32 v37, 0x3f317217, v33
	v_fma_f32 v37, v33, s24, -v37
	v_fmac_f32_e32 v37, 0x3377d1cf, v33
	v_fmac_f32_e32 v37, 0x3f317217, v33
	v_cmp_lt_f32_e64 s[8:9], |v33|, s25
	s_nop 1
	v_cndmask_b32_e64 v33, v33, v37, s[8:9]
	v_cndmask_b32_e32 v37, 0, v154, vcc
	v_sub_f32_e32 v33, v33, v37
	v_add_f32_e32 v33, v36, v33
	v_sub_f32_e32 v33, -0.5, v33
	v_mul_f32_e32 v33, 0x3fb8aa3b, v33
	v_exp_f32_e32 v33, v33
	v_add_co_u32_e32 v36, vcc, s47, v146
	v_mul_f32_e32 v33, 0xbfb8aa3b, v33
	v_exp_f32_e32 v33, v33
	v_addc_co_u32_e32 v37, vcc, 0, v147, vcc
	global_store_dwordx4 v[36:37], v[30:33], off
	v_add_f32_e32 v26, v26, v228
	v_max_f32_e64 v30, -v26, 0
	v_mul_f32_e64 v26, |v26|, s86
	v_exp_f32_e32 v26, v26
	v_add_f32_e32 v27, v27, v229
	v_add_f32_e32 v28, v28, v230
	v_add_f32_e32 v29, v29, v231
	v_add_f32_e32 v26, 1.0, v26
	v_cmp_gt_f32_e32 vcc, s30, v26
	s_nop 1
	v_cndmask_b32_e64 v36, 0, 32, vcc
	v_ldexp_f32 v26, v26, v36
	v_log_f32_e32 v26, v26
	s_nop 0
	v_mul_f32_e32 v36, 0x3f317217, v26
	v_fma_f32 v36, v26, s24, -v36
	v_fmac_f32_e32 v36, 0x3377d1cf, v26
	v_fmac_f32_e32 v36, 0x3f317217, v26
	v_cmp_lt_f32_e64 s[8:9], |v26|, s25
	s_nop 1
	v_cndmask_b32_e64 v26, v26, v36, s[8:9]
	v_cndmask_b32_e32 v36, 0, v154, vcc
	v_sub_f32_e32 v26, v26, v36
	v_add_f32_e32 v26, v30, v26
	v_max_f32_e64 v30, -v27, 0
	v_mul_f32_e64 v27, |v27|, s86
	v_exp_f32_e32 v27, v27
	v_sub_f32_e32 v26, -0.5, v26
	v_mul_f32_e32 v26, 0x3fb8aa3b, v26
	v_exp_f32_e32 v26, v26
	v_add_f32_e32 v27, 1.0, v27
	v_cmp_gt_f32_e32 vcc, s30, v27
	v_mul_f32_e32 v26, 0xbfb8aa3b, v26
	s_nop 0
	v_cndmask_b32_e64 v31, 0, 32, vcc
	v_ldexp_f32 v27, v27, v31
	v_log_f32_e32 v27, v27
	v_exp_f32_e32 v26, v26
	v_mul_f32_e32 v31, 0x3f317217, v27
	v_fma_f32 v31, v27, s24, -v31
	v_fmac_f32_e32 v31, 0x3377d1cf, v27
	v_fmac_f32_e32 v31, 0x3f317217, v27
	v_cmp_lt_f32_e64 s[8:9], |v27|, s25
	s_nop 1
	v_cndmask_b32_e64 v27, v27, v31, s[8:9]
	v_cndmask_b32_e32 v31, 0, v154, vcc
	v_sub_f32_e32 v27, v27, v31
	v_add_f32_e32 v27, v30, v27
	v_max_f32_e64 v30, -v28, 0
	v_mul_f32_e64 v28, |v28|, s86
	v_exp_f32_e32 v28, v28
	v_sub_f32_e32 v27, -0.5, v27
	v_mul_f32_e32 v27, 0x3fb8aa3b, v27
	v_exp_f32_e32 v27, v27
	v_add_f32_e32 v28, 1.0, v28
	v_cmp_gt_f32_e32 vcc, s30, v28
	v_mul_f32_e32 v27, 0xbfb8aa3b, v27
	s_nop 0
	v_cndmask_b32_e64 v31, 0, 32, vcc
	v_ldexp_f32 v28, v28, v31
	v_log_f32_e32 v28, v28
	v_exp_f32_e32 v27, v27
	v_mul_f32_e32 v31, 0x3f317217, v28
	v_fma_f32 v31, v28, s24, -v31
	v_fmac_f32_e32 v31, 0x3377d1cf, v28
	v_fmac_f32_e32 v31, 0x3f317217, v28
	v_cmp_lt_f32_e64 s[8:9], |v28|, s25
	s_nop 1
	v_cndmask_b32_e64 v28, v28, v31, s[8:9]
	v_cndmask_b32_e32 v31, 0, v154, vcc
	v_sub_f32_e32 v28, v28, v31
	v_add_f32_e32 v28, v30, v28
	v_max_f32_e64 v30, -v29, 0
	v_mul_f32_e64 v29, |v29|, s86
	v_exp_f32_e32 v29, v29
	v_sub_f32_e32 v28, -0.5, v28
	v_mul_f32_e32 v28, 0x3fb8aa3b, v28
	v_exp_f32_e32 v28, v28
	v_add_f32_e32 v29, 1.0, v29
	v_cmp_gt_f32_e32 vcc, s30, v29
	v_mul_f32_e32 v28, 0xbfb8aa3b, v28
	s_nop 0
	v_cndmask_b32_e64 v31, 0, 32, vcc
	v_ldexp_f32 v29, v29, v31
	v_log_f32_e32 v29, v29
	v_exp_f32_e32 v28, v28
	v_mul_f32_e32 v31, 0x3f317217, v29
	v_fma_f32 v31, v29, s24, -v31
	v_fmac_f32_e32 v31, 0x3377d1cf, v29
	v_fmac_f32_e32 v31, 0x3f317217, v29
	v_cmp_lt_f32_e64 s[8:9], |v29|, s25
	s_nop 1
	v_cndmask_b32_e64 v29, v29, v31, s[8:9]
	v_cndmask_b32_e32 v31, 0, v154, vcc
	v_sub_f32_e32 v29, v29, v31
	v_add_f32_e32 v29, v30, v29
	v_sub_f32_e32 v29, -0.5, v29
	v_mul_f32_e32 v29, 0x3fb8aa3b, v29
	v_exp_f32_e32 v29, v29
	s_nop 0
	v_mul_f32_e32 v29, 0xbfb8aa3b, v29
	v_exp_f32_e32 v29, v29
	global_store_dwordx4 v[40:41], v[26:29], off offset:64
	v_add_f32_e32 v22, v22, v232
	v_max_f32_e64 v26, -v22, 0
	v_mul_f32_e64 v22, |v22|, s86
	v_exp_f32_e32 v22, v22
	v_add_f32_e32 v23, v23, v233
	v_add_f32_e32 v24, v24, v234
	v_add_f32_e32 v25, v25, v235
	v_add_f32_e32 v22, 1.0, v22
	v_cmp_gt_f32_e32 vcc, s30, v22
	s_nop 1
	v_cndmask_b32_e64 v30, 0, 32, vcc
	v_ldexp_f32 v22, v22, v30
	v_log_f32_e32 v22, v22
	s_nop 0
	v_mul_f32_e32 v30, 0x3f317217, v22
	v_fma_f32 v30, v22, s24, -v30
	v_fmac_f32_e32 v30, 0x3377d1cf, v22
	v_fmac_f32_e32 v30, 0x3f317217, v22
	v_cmp_lt_f32_e64 s[8:9], |v22|, s25
	s_nop 1
	v_cndmask_b32_e64 v22, v22, v30, s[8:9]
	v_cndmask_b32_e32 v30, 0, v154, vcc
	v_sub_f32_e32 v22, v22, v30
	v_add_f32_e32 v22, v26, v22
	v_max_f32_e64 v26, -v23, 0
	v_mul_f32_e64 v23, |v23|, s86
	v_exp_f32_e32 v23, v23
	v_sub_f32_e32 v22, -0.5, v22
	v_mul_f32_e32 v22, 0x3fb8aa3b, v22
	v_exp_f32_e32 v22, v22
	v_add_f32_e32 v23, 1.0, v23
	v_cmp_gt_f32_e32 vcc, s30, v23
	v_mul_f32_e32 v22, 0xbfb8aa3b, v22
	s_nop 0
	v_cndmask_b32_e64 v27, 0, 32, vcc
	v_ldexp_f32 v23, v23, v27
	v_log_f32_e32 v23, v23
	v_exp_f32_e32 v22, v22
	v_mul_f32_e32 v27, 0x3f317217, v23
	v_fma_f32 v27, v23, s24, -v27
	v_fmac_f32_e32 v27, 0x3377d1cf, v23
	v_fmac_f32_e32 v27, 0x3f317217, v23
	v_cmp_lt_f32_e64 s[8:9], |v23|, s25
	s_nop 1
	v_cndmask_b32_e64 v23, v23, v27, s[8:9]
	v_cndmask_b32_e32 v27, 0, v154, vcc
	v_sub_f32_e32 v23, v23, v27
	v_add_f32_e32 v23, v26, v23
	v_max_f32_e64 v26, -v24, 0
	v_mul_f32_e64 v24, |v24|, s86
	v_exp_f32_e32 v24, v24
	v_sub_f32_e32 v23, -0.5, v23
	v_mul_f32_e32 v23, 0x3fb8aa3b, v23
	v_exp_f32_e32 v23, v23
	v_add_f32_e32 v24, 1.0, v24
	v_cmp_gt_f32_e32 vcc, s30, v24
	v_mul_f32_e32 v23, 0xbfb8aa3b, v23
	s_nop 0
	v_cndmask_b32_e64 v27, 0, 32, vcc
	v_ldexp_f32 v24, v24, v27
	v_log_f32_e32 v24, v24
	v_exp_f32_e32 v23, v23
	v_mul_f32_e32 v27, 0x3f317217, v24
	v_fma_f32 v27, v24, s24, -v27
	v_fmac_f32_e32 v27, 0x3377d1cf, v24
	v_fmac_f32_e32 v27, 0x3f317217, v24
	v_cmp_lt_f32_e64 s[8:9], |v24|, s25
	s_nop 1
	v_cndmask_b32_e64 v24, v24, v27, s[8:9]
	v_cndmask_b32_e32 v27, 0, v154, vcc
	v_sub_f32_e32 v24, v24, v27
	v_add_f32_e32 v24, v26, v24
	v_max_f32_e64 v26, -v25, 0
	v_mul_f32_e64 v25, |v25|, s86
	v_exp_f32_e32 v25, v25
	v_sub_f32_e32 v24, -0.5, v24
	v_mul_f32_e32 v24, 0x3fb8aa3b, v24
	v_exp_f32_e32 v24, v24
	v_add_f32_e32 v25, 1.0, v25
	v_cmp_gt_f32_e32 vcc, s30, v25
	v_mul_f32_e32 v24, 0xbfb8aa3b, v24
	s_nop 0
	v_cndmask_b32_e64 v27, 0, 32, vcc
	v_ldexp_f32 v25, v25, v27
	v_log_f32_e32 v25, v25
	v_exp_f32_e32 v24, v24
	v_mul_f32_e32 v27, 0x3f317217, v25
	v_fma_f32 v27, v25, s24, -v27
	v_fmac_f32_e32 v27, 0x3377d1cf, v25
	v_fmac_f32_e32 v27, 0x3f317217, v25
	v_cmp_lt_f32_e64 s[8:9], |v25|, s25
	s_nop 1
	v_cndmask_b32_e64 v25, v25, v27, s[8:9]
	v_cndmask_b32_e32 v27, 0, v154, vcc
	v_sub_f32_e32 v25, v25, v27
	v_add_f32_e32 v25, v26, v25
	v_sub_f32_e32 v25, -0.5, v25
	v_mul_f32_e32 v25, 0x3fb8aa3b, v25
	v_exp_f32_e32 v25, v25
	s_nop 0
	v_mul_f32_e32 v25, 0xbfb8aa3b, v25
	v_exp_f32_e32 v25, v25
	global_store_dwordx4 v[40:41], v[22:25], off offset:512
	v_add_f32_e32 v18, v18, v236
	v_max_f32_e64 v22, -v18, 0
	v_mul_f32_e64 v18, |v18|, s86
	v_exp_f32_e32 v18, v18
	v_add_f32_e32 v19, v19, v237
	v_add_f32_e32 v20, v20, v238
	v_add_f32_e32 v21, v21, v239
	v_add_f32_e32 v18, 1.0, v18
	v_cmp_gt_f32_e32 vcc, s30, v18
	s_nop 1
	v_cndmask_b32_e64 v26, 0, 32, vcc
	v_ldexp_f32 v18, v18, v26
	v_log_f32_e32 v18, v18
	s_nop 0
	v_mul_f32_e32 v26, 0x3f317217, v18
	v_fma_f32 v26, v18, s24, -v26
	v_fmac_f32_e32 v26, 0x3377d1cf, v18
	v_fmac_f32_e32 v26, 0x3f317217, v18
	v_cmp_lt_f32_e64 s[8:9], |v18|, s25
	s_nop 1
	v_cndmask_b32_e64 v18, v18, v26, s[8:9]
	v_cndmask_b32_e32 v26, 0, v154, vcc
	v_sub_f32_e32 v18, v18, v26
	v_add_f32_e32 v18, v22, v18
	v_max_f32_e64 v22, -v19, 0
	v_mul_f32_e64 v19, |v19|, s86
	v_exp_f32_e32 v19, v19
	v_sub_f32_e32 v18, -0.5, v18
	v_mul_f32_e32 v18, 0x3fb8aa3b, v18
	v_exp_f32_e32 v18, v18
	v_add_f32_e32 v19, 1.0, v19
	v_cmp_gt_f32_e32 vcc, s30, v19
	v_mul_f32_e32 v18, 0xbfb8aa3b, v18
	s_nop 0
	v_cndmask_b32_e64 v23, 0, 32, vcc
	v_ldexp_f32 v19, v19, v23
	v_log_f32_e32 v19, v19
	v_exp_f32_e32 v18, v18
	v_mul_f32_e32 v23, 0x3f317217, v19
	v_fma_f32 v23, v19, s24, -v23
	v_fmac_f32_e32 v23, 0x3377d1cf, v19
	v_fmac_f32_e32 v23, 0x3f317217, v19
	v_cmp_lt_f32_e64 s[8:9], |v19|, s25
	s_nop 1
	v_cndmask_b32_e64 v19, v19, v23, s[8:9]
	v_cndmask_b32_e32 v23, 0, v154, vcc
	v_sub_f32_e32 v19, v19, v23
	v_add_f32_e32 v19, v22, v19
	v_max_f32_e64 v22, -v20, 0
	v_mul_f32_e64 v20, |v20|, s86
	v_exp_f32_e32 v20, v20
	v_sub_f32_e32 v19, -0.5, v19
	v_mul_f32_e32 v19, 0x3fb8aa3b, v19
	v_exp_f32_e32 v19, v19
	v_add_f32_e32 v20, 1.0, v20
	v_cmp_gt_f32_e32 vcc, s30, v20
	v_mul_f32_e32 v19, 0xbfb8aa3b, v19
	s_nop 0
	v_cndmask_b32_e64 v23, 0, 32, vcc
	v_ldexp_f32 v20, v20, v23
	v_log_f32_e32 v20, v20
	v_exp_f32_e32 v19, v19
	v_mul_f32_e32 v23, 0x3f317217, v20
	v_fma_f32 v23, v20, s24, -v23
	v_fmac_f32_e32 v23, 0x3377d1cf, v20
	v_fmac_f32_e32 v23, 0x3f317217, v20
	v_cmp_lt_f32_e64 s[8:9], |v20|, s25
	s_nop 1
	v_cndmask_b32_e64 v20, v20, v23, s[8:9]
	v_cndmask_b32_e32 v23, 0, v154, vcc
	v_sub_f32_e32 v20, v20, v23
	v_add_f32_e32 v20, v22, v20
	v_max_f32_e64 v22, -v21, 0
	v_mul_f32_e64 v21, |v21|, s86
	v_exp_f32_e32 v21, v21
	v_sub_f32_e32 v20, -0.5, v20
	v_mul_f32_e32 v20, 0x3fb8aa3b, v20
	v_exp_f32_e32 v20, v20
	v_add_f32_e32 v21, 1.0, v21
	v_cmp_gt_f32_e32 vcc, s30, v21
	v_mul_f32_e32 v20, 0xbfb8aa3b, v20
	s_nop 0
	v_cndmask_b32_e64 v23, 0, 32, vcc
	v_ldexp_f32 v21, v21, v23
	v_log_f32_e32 v21, v21
	v_exp_f32_e32 v20, v20
	v_mul_f32_e32 v23, 0x3f317217, v21
	v_fma_f32 v23, v21, s24, -v23
	v_fmac_f32_e32 v23, 0x3377d1cf, v21
	v_fmac_f32_e32 v23, 0x3f317217, v21
	v_cmp_lt_f32_e64 s[8:9], |v21|, s25
	s_nop 1
	v_cndmask_b32_e64 v21, v21, v23, s[8:9]
	v_cndmask_b32_e32 v23, 0, v154, vcc
	v_sub_f32_e32 v21, v21, v23
	v_add_f32_e32 v21, v22, v21
	v_sub_f32_e32 v21, -0.5, v21
	v_mul_f32_e32 v21, 0x3fb8aa3b, v21
	v_exp_f32_e32 v21, v21
	v_lshl_add_u64 v[22:23], v[146:147], 0, s[4:5]
	v_mul_f32_e32 v21, 0xbfb8aa3b, v21
	v_exp_f32_e32 v21, v21
	global_store_dwordx4 v[40:41], v[18:21], off offset:576
	v_add_f32_e32 v14, v14, v224
	v_max_f32_e64 v18, -v14, 0
	v_mul_f32_e64 v14, |v14|, s86
	v_exp_f32_e32 v14, v14
	v_add_f32_e32 v15, v15, v225
	v_add_f32_e32 v16, v16, v226
	v_add_f32_e32 v17, v17, v227
	v_add_f32_e32 v14, 1.0, v14
	v_cmp_gt_f32_e32 vcc, s30, v14
	s_nop 1
	v_cndmask_b32_e64 v24, 0, 32, vcc
	v_ldexp_f32 v14, v14, v24
	v_log_f32_e32 v14, v14
	s_nop 0
	v_mul_f32_e32 v24, 0x3f317217, v14
	v_fma_f32 v24, v14, s24, -v24
	v_fmac_f32_e32 v24, 0x3377d1cf, v14
	v_fmac_f32_e32 v24, 0x3f317217, v14
	v_cmp_lt_f32_e64 s[8:9], |v14|, s25
	s_nop 1
	v_cndmask_b32_e64 v14, v14, v24, s[8:9]
	v_cndmask_b32_e32 v24, 0, v154, vcc
	v_sub_f32_e32 v14, v14, v24
	v_add_f32_e32 v14, v18, v14
	v_max_f32_e64 v18, -v15, 0
	v_mul_f32_e64 v15, |v15|, s86
	v_exp_f32_e32 v15, v15
	v_sub_f32_e32 v14, -0.5, v14
	v_mul_f32_e32 v14, 0x3fb8aa3b, v14
	v_exp_f32_e32 v14, v14
	v_add_f32_e32 v15, 1.0, v15
	v_cmp_gt_f32_e32 vcc, s30, v15
	v_mul_f32_e32 v14, 0xbfb8aa3b, v14
	s_nop 0
	v_cndmask_b32_e64 v19, 0, 32, vcc
	v_ldexp_f32 v15, v15, v19
	v_log_f32_e32 v15, v15
	v_exp_f32_e32 v14, v14
	v_mul_f32_e32 v19, 0x3f317217, v15
	v_fma_f32 v19, v15, s24, -v19
	v_fmac_f32_e32 v19, 0x3377d1cf, v15
	v_fmac_f32_e32 v19, 0x3f317217, v15
	v_cmp_lt_f32_e64 s[8:9], |v15|, s25
	s_nop 1
	v_cndmask_b32_e64 v15, v15, v19, s[8:9]
	v_cndmask_b32_e32 v19, 0, v154, vcc
	v_sub_f32_e32 v15, v15, v19
	v_add_f32_e32 v15, v18, v15
	v_max_f32_e64 v18, -v16, 0
	v_mul_f32_e64 v16, |v16|, s86
	v_exp_f32_e32 v16, v16
	v_sub_f32_e32 v15, -0.5, v15
	v_mul_f32_e32 v15, 0x3fb8aa3b, v15
	v_exp_f32_e32 v15, v15
	v_add_f32_e32 v16, 1.0, v16
	v_cmp_gt_f32_e32 vcc, s30, v16
	v_mul_f32_e32 v15, 0xbfb8aa3b, v15
	s_nop 0
	v_cndmask_b32_e64 v19, 0, 32, vcc
	v_ldexp_f32 v16, v16, v19
	v_log_f32_e32 v16, v16
	v_exp_f32_e32 v15, v15
	v_mul_f32_e32 v19, 0x3f317217, v16
	v_fma_f32 v19, v16, s24, -v19
	v_fmac_f32_e32 v19, 0x3377d1cf, v16
	v_fmac_f32_e32 v19, 0x3f317217, v16
	v_cmp_lt_f32_e64 s[8:9], |v16|, s25
	s_nop 1
	v_cndmask_b32_e64 v16, v16, v19, s[8:9]
	v_cndmask_b32_e32 v19, 0, v154, vcc
	v_sub_f32_e32 v16, v16, v19
	v_add_f32_e32 v16, v18, v16
	v_max_f32_e64 v18, -v17, 0
	v_mul_f32_e64 v17, |v17|, s86
	v_exp_f32_e32 v17, v17
	v_sub_f32_e32 v16, -0.5, v16
	v_mul_f32_e32 v16, 0x3fb8aa3b, v16
	v_exp_f32_e32 v16, v16
	v_add_f32_e32 v17, 1.0, v17
	v_cmp_gt_f32_e32 vcc, s30, v17
	v_mul_f32_e32 v16, 0xbfb8aa3b, v16
	s_nop 0
	v_cndmask_b32_e64 v19, 0, 32, vcc
	v_ldexp_f32 v17, v17, v19
	v_log_f32_e32 v17, v17
	v_exp_f32_e32 v16, v16
	v_mul_f32_e32 v19, 0x3f317217, v17
	v_fma_f32 v19, v17, s24, -v19
	v_fmac_f32_e32 v19, 0x3377d1cf, v17
	v_fmac_f32_e32 v19, 0x3f317217, v17
	v_cmp_lt_f32_e64 s[8:9], |v17|, s25
	s_nop 1
	v_cndmask_b32_e64 v17, v17, v19, s[8:9]
	v_cndmask_b32_e32 v19, 0, v154, vcc
	v_sub_f32_e32 v17, v17, v19
	v_add_f32_e32 v17, v18, v17
	v_sub_f32_e32 v17, -0.5, v17
	v_mul_f32_e32 v17, 0x3fb8aa3b, v17
	v_exp_f32_e32 v17, v17
	v_add_co_u32_e32 v18, vcc, s68, v146
	v_mul_f32_e32 v17, 0xbfb8aa3b, v17
	v_exp_f32_e32 v17, v17
	v_addc_co_u32_e32 v19, vcc, 0, v147, vcc
	global_store_dwordx4 v[18:19], v[14:17], off
	v_add_f32_e32 v10, v10, v228
	v_max_f32_e64 v14, -v10, 0
	v_mul_f32_e64 v10, |v10|, s86
	v_exp_f32_e32 v10, v10
	v_add_f32_e32 v11, v11, v229
	v_add_f32_e32 v12, v12, v230
	v_add_f32_e32 v13, v13, v231
	v_add_f32_e32 v10, 1.0, v10
	v_cmp_gt_f32_e32 vcc, s30, v10
	s_nop 1
	v_cndmask_b32_e64 v18, 0, 32, vcc
	v_ldexp_f32 v10, v10, v18
	v_log_f32_e32 v10, v10
	s_nop 0
	v_mul_f32_e32 v18, 0x3f317217, v10
	v_fma_f32 v18, v10, s24, -v18
	v_fmac_f32_e32 v18, 0x3377d1cf, v10
	v_fmac_f32_e32 v18, 0x3f317217, v10
	v_cmp_lt_f32_e64 s[8:9], |v10|, s25
	s_nop 1
	v_cndmask_b32_e64 v10, v10, v18, s[8:9]
	v_cndmask_b32_e32 v18, 0, v154, vcc
	v_sub_f32_e32 v10, v10, v18
	v_add_f32_e32 v10, v14, v10
	v_max_f32_e64 v14, -v11, 0
	v_mul_f32_e64 v11, |v11|, s86
	v_exp_f32_e32 v11, v11
	v_sub_f32_e32 v10, -0.5, v10
	v_mul_f32_e32 v10, 0x3fb8aa3b, v10
	v_exp_f32_e32 v10, v10
	v_add_f32_e32 v11, 1.0, v11
	v_cmp_gt_f32_e32 vcc, s30, v11
	v_mul_f32_e32 v10, 0xbfb8aa3b, v10
	s_nop 0
	v_cndmask_b32_e64 v15, 0, 32, vcc
	v_ldexp_f32 v11, v11, v15
	v_log_f32_e32 v11, v11
	v_exp_f32_e32 v10, v10
	v_mul_f32_e32 v15, 0x3f317217, v11
	v_fma_f32 v15, v11, s24, -v15
	v_fmac_f32_e32 v15, 0x3377d1cf, v11
	v_fmac_f32_e32 v15, 0x3f317217, v11
	v_cmp_lt_f32_e64 s[8:9], |v11|, s25
	s_nop 1
	v_cndmask_b32_e64 v11, v11, v15, s[8:9]
	v_cndmask_b32_e32 v15, 0, v154, vcc
	v_sub_f32_e32 v11, v11, v15
	v_add_f32_e32 v11, v14, v11
	v_max_f32_e64 v14, -v12, 0
	v_mul_f32_e64 v12, |v12|, s86
	v_exp_f32_e32 v12, v12
	v_sub_f32_e32 v11, -0.5, v11
	v_mul_f32_e32 v11, 0x3fb8aa3b, v11
	v_exp_f32_e32 v11, v11
	v_add_f32_e32 v12, 1.0, v12
	v_cmp_gt_f32_e32 vcc, s30, v12
	v_mul_f32_e32 v11, 0xbfb8aa3b, v11
	s_nop 0
	v_cndmask_b32_e64 v15, 0, 32, vcc
	v_ldexp_f32 v12, v12, v15
	v_log_f32_e32 v12, v12
	v_exp_f32_e32 v11, v11
	v_mul_f32_e32 v15, 0x3f317217, v12
	v_fma_f32 v15, v12, s24, -v15
	v_fmac_f32_e32 v15, 0x3377d1cf, v12
	v_fmac_f32_e32 v15, 0x3f317217, v12
	v_cmp_lt_f32_e64 s[8:9], |v12|, s25
	s_nop 1
	v_cndmask_b32_e64 v12, v12, v15, s[8:9]
	v_cndmask_b32_e32 v15, 0, v154, vcc
	v_sub_f32_e32 v12, v12, v15
	v_add_f32_e32 v12, v14, v12
	v_max_f32_e64 v14, -v13, 0
	v_mul_f32_e64 v13, |v13|, s86
	v_exp_f32_e32 v13, v13
	v_sub_f32_e32 v12, -0.5, v12
	v_mul_f32_e32 v12, 0x3fb8aa3b, v12
	v_exp_f32_e32 v12, v12
	v_add_f32_e32 v13, 1.0, v13
	v_cmp_gt_f32_e32 vcc, s30, v13
	v_mul_f32_e32 v12, 0xbfb8aa3b, v12
	s_nop 0
	v_cndmask_b32_e64 v15, 0, 32, vcc
	v_ldexp_f32 v13, v13, v15
	v_log_f32_e32 v13, v13
	v_exp_f32_e32 v12, v12
	v_mul_f32_e32 v15, 0x3f317217, v13
	v_fma_f32 v15, v13, s24, -v15
	v_fmac_f32_e32 v15, 0x3377d1cf, v13
	v_fmac_f32_e32 v15, 0x3f317217, v13
	v_cmp_lt_f32_e64 s[8:9], |v13|, s25
	s_nop 1
	v_cndmask_b32_e64 v13, v13, v15, s[8:9]
	v_cndmask_b32_e32 v15, 0, v154, vcc
	v_sub_f32_e32 v13, v13, v15
	v_add_f32_e32 v13, v14, v13
	v_sub_f32_e32 v13, -0.5, v13
	v_mul_f32_e32 v13, 0x3fb8aa3b, v13
	v_exp_f32_e32 v13, v13
	s_nop 0
	v_mul_f32_e32 v13, 0xbfb8aa3b, v13
	v_exp_f32_e32 v13, v13
	global_store_dwordx4 v[22:23], v[10:13], off offset:64
	v_add_f32_e32 v6, v6, v232
	v_max_f32_e64 v10, -v6, 0
	v_mul_f32_e64 v6, |v6|, s86
	v_exp_f32_e32 v6, v6
	v_add_f32_e32 v7, v7, v233
	v_add_f32_e32 v8, v8, v234
	v_add_f32_e32 v9, v9, v235
	v_add_f32_e32 v6, 1.0, v6
	v_cmp_gt_f32_e32 vcc, s30, v6
	s_nop 1
	v_cndmask_b32_e64 v14, 0, 32, vcc
	v_ldexp_f32 v6, v6, v14
	v_log_f32_e32 v6, v6
	s_nop 0
	v_mul_f32_e32 v14, 0x3f317217, v6
	v_fma_f32 v14, v6, s24, -v14
	v_fmac_f32_e32 v14, 0x3377d1cf, v6
	v_fmac_f32_e32 v14, 0x3f317217, v6
	v_cmp_lt_f32_e64 s[8:9], |v6|, s25
	s_nop 1
	v_cndmask_b32_e64 v6, v6, v14, s[8:9]
	v_cndmask_b32_e32 v14, 0, v154, vcc
	v_sub_f32_e32 v6, v6, v14
	v_add_f32_e32 v6, v10, v6
	v_max_f32_e64 v10, -v7, 0
	v_mul_f32_e64 v7, |v7|, s86
	v_exp_f32_e32 v7, v7
	v_sub_f32_e32 v6, -0.5, v6
	v_mul_f32_e32 v6, 0x3fb8aa3b, v6
	v_exp_f32_e32 v6, v6
	v_add_f32_e32 v7, 1.0, v7
	v_cmp_gt_f32_e32 vcc, s30, v7
	v_mul_f32_e32 v6, 0xbfb8aa3b, v6
	s_nop 0
	v_cndmask_b32_e64 v11, 0, 32, vcc
	v_ldexp_f32 v7, v7, v11
	v_log_f32_e32 v7, v7
	v_exp_f32_e32 v6, v6
	v_mul_f32_e32 v11, 0x3f317217, v7
	v_fma_f32 v11, v7, s24, -v11
	v_fmac_f32_e32 v11, 0x3377d1cf, v7
	v_fmac_f32_e32 v11, 0x3f317217, v7
	v_cmp_lt_f32_e64 s[8:9], |v7|, s25
	s_nop 1
	v_cndmask_b32_e64 v7, v7, v11, s[8:9]
	v_cndmask_b32_e32 v11, 0, v154, vcc
	v_sub_f32_e32 v7, v7, v11
	v_add_f32_e32 v7, v10, v7
	v_max_f32_e64 v10, -v8, 0
	v_mul_f32_e64 v8, |v8|, s86
	v_exp_f32_e32 v8, v8
	v_sub_f32_e32 v7, -0.5, v7
	v_mul_f32_e32 v7, 0x3fb8aa3b, v7
	v_exp_f32_e32 v7, v7
	v_add_f32_e32 v8, 1.0, v8
	v_cmp_gt_f32_e32 vcc, s30, v8
	v_mul_f32_e32 v7, 0xbfb8aa3b, v7
	s_nop 0
	v_cndmask_b32_e64 v11, 0, 32, vcc
	v_ldexp_f32 v8, v8, v11
	v_log_f32_e32 v8, v8
	v_exp_f32_e32 v7, v7
	v_mul_f32_e32 v11, 0x3f317217, v8
	v_fma_f32 v11, v8, s24, -v11
	v_fmac_f32_e32 v11, 0x3377d1cf, v8
	v_fmac_f32_e32 v11, 0x3f317217, v8
	v_cmp_lt_f32_e64 s[8:9], |v8|, s25
	s_nop 1
	v_cndmask_b32_e64 v8, v8, v11, s[8:9]
	v_cndmask_b32_e32 v11, 0, v154, vcc
	v_sub_f32_e32 v8, v8, v11
	v_add_f32_e32 v8, v10, v8
	v_max_f32_e64 v10, -v9, 0
	v_mul_f32_e64 v9, |v9|, s86
	v_exp_f32_e32 v9, v9
	v_sub_f32_e32 v8, -0.5, v8
	v_mul_f32_e32 v8, 0x3fb8aa3b, v8
	v_exp_f32_e32 v8, v8
	v_add_f32_e32 v9, 1.0, v9
	v_cmp_gt_f32_e32 vcc, s30, v9
	v_mul_f32_e32 v8, 0xbfb8aa3b, v8
	s_nop 0
	v_cndmask_b32_e64 v11, 0, 32, vcc
	v_ldexp_f32 v9, v9, v11
	v_log_f32_e32 v9, v9
	v_exp_f32_e32 v8, v8
	v_mul_f32_e32 v11, 0x3f317217, v9
	v_fma_f32 v11, v9, s24, -v11
	v_fmac_f32_e32 v11, 0x3377d1cf, v9
	v_fmac_f32_e32 v11, 0x3f317217, v9
	v_cmp_lt_f32_e64 s[8:9], |v9|, s25
	s_nop 1
	v_cndmask_b32_e64 v9, v9, v11, s[8:9]
	v_cndmask_b32_e32 v11, 0, v154, vcc
	v_sub_f32_e32 v9, v9, v11
	v_add_f32_e32 v9, v10, v9
	v_sub_f32_e32 v9, -0.5, v9
	v_mul_f32_e32 v9, 0x3fb8aa3b, v9
	v_exp_f32_e32 v9, v9
	s_nop 0
	v_mul_f32_e32 v9, 0xbfb8aa3b, v9
	v_exp_f32_e32 v9, v9
	global_store_dwordx4 v[22:23], v[6:9], off offset:512
	v_add_f32_e32 v2, v2, v236
	v_max_f32_e64 v6, -v2, 0
	v_mul_f32_e64 v2, |v2|, s86
	v_exp_f32_e32 v2, v2
	v_add_f32_e32 v3, v3, v237
	v_add_f32_e32 v4, v4, v238
	v_add_f32_e32 v5, v5, v239
	v_add_f32_e32 v2, 1.0, v2
	v_cmp_gt_f32_e32 vcc, s30, v2
	s_nop 1
	v_cndmask_b32_e64 v10, 0, 32, vcc
	v_ldexp_f32 v2, v2, v10
	v_log_f32_e32 v2, v2
	s_nop 0
	v_mul_f32_e32 v10, 0x3f317217, v2
	v_fma_f32 v10, v2, s24, -v10
	v_fmac_f32_e32 v10, 0x3377d1cf, v2
	v_fmac_f32_e32 v10, 0x3f317217, v2
	v_cmp_lt_f32_e64 s[8:9], |v2|, s25
	s_nop 1
	v_cndmask_b32_e64 v2, v2, v10, s[8:9]
	v_cndmask_b32_e32 v10, 0, v154, vcc
	v_sub_f32_e32 v2, v2, v10
	v_add_f32_e32 v2, v6, v2
	v_max_f32_e64 v6, -v3, 0
	v_mul_f32_e64 v3, |v3|, s86
	v_exp_f32_e32 v3, v3
	v_sub_f32_e32 v2, -0.5, v2
	v_mul_f32_e32 v2, 0x3fb8aa3b, v2
	v_exp_f32_e32 v2, v2
	v_add_f32_e32 v3, 1.0, v3
	v_cmp_gt_f32_e32 vcc, s30, v3
	v_mul_f32_e32 v2, 0xbfb8aa3b, v2
	s_nop 0
	v_cndmask_b32_e64 v7, 0, 32, vcc
	v_ldexp_f32 v3, v3, v7
	v_log_f32_e32 v3, v3
	v_exp_f32_e32 v2, v2
	v_mul_f32_e32 v7, 0x3f317217, v3
	v_fma_f32 v7, v3, s24, -v7
	v_fmac_f32_e32 v7, 0x3377d1cf, v3
	v_fmac_f32_e32 v7, 0x3f317217, v3
	v_cmp_lt_f32_e64 s[8:9], |v3|, s25
	s_nop 1
	v_cndmask_b32_e64 v3, v3, v7, s[8:9]
	v_cndmask_b32_e32 v7, 0, v154, vcc
	v_sub_f32_e32 v3, v3, v7
	v_add_f32_e32 v3, v6, v3
	v_max_f32_e64 v6, -v4, 0
	v_mul_f32_e64 v4, |v4|, s86
	v_exp_f32_e32 v4, v4
	v_sub_f32_e32 v3, -0.5, v3
	v_mul_f32_e32 v3, 0x3fb8aa3b, v3
	v_exp_f32_e32 v3, v3
	v_add_f32_e32 v4, 1.0, v4
	v_cmp_gt_f32_e32 vcc, s30, v4
	v_mul_f32_e32 v3, 0xbfb8aa3b, v3
	s_nop 0
	v_cndmask_b32_e64 v7, 0, 32, vcc
	v_ldexp_f32 v4, v4, v7
	v_log_f32_e32 v4, v4
	v_exp_f32_e32 v3, v3
	v_mul_f32_e32 v7, 0x3f317217, v4
	v_fma_f32 v7, v4, s24, -v7
	v_fmac_f32_e32 v7, 0x3377d1cf, v4
	v_fmac_f32_e32 v7, 0x3f317217, v4
	v_cmp_lt_f32_e64 s[8:9], |v4|, s25
	s_nop 1
	v_cndmask_b32_e64 v4, v4, v7, s[8:9]
	v_cndmask_b32_e32 v7, 0, v154, vcc
	v_sub_f32_e32 v4, v4, v7
	v_add_f32_e32 v4, v6, v4
	v_max_f32_e64 v6, -v5, 0
	v_mul_f32_e64 v5, |v5|, s86
	v_exp_f32_e32 v5, v5
	v_sub_f32_e32 v4, -0.5, v4
	v_mul_f32_e32 v4, 0x3fb8aa3b, v4
	v_exp_f32_e32 v4, v4
	v_add_f32_e32 v5, 1.0, v5
	v_cmp_gt_f32_e32 vcc, s30, v5
	v_mul_f32_e32 v4, 0xbfb8aa3b, v4
	s_nop 0
	v_cndmask_b32_e64 v7, 0, 32, vcc
	v_ldexp_f32 v5, v5, v7
	v_log_f32_e32 v5, v5
	v_exp_f32_e32 v4, v4
	v_mul_f32_e32 v7, 0x3f317217, v5
	v_fma_f32 v7, v5, s24, -v7
	v_fmac_f32_e32 v7, 0x3377d1cf, v5
	v_fmac_f32_e32 v7, 0x3f317217, v5
	v_cmp_lt_f32_e64 s[8:9], |v5|, s25
	s_nop 1
	v_cndmask_b32_e64 v5, v5, v7, s[8:9]
	v_cndmask_b32_e32 v7, 0, v154, vcc
	v_sub_f32_e32 v5, v5, v7
	v_add_f32_e32 v5, v6, v5
	v_sub_f32_e32 v5, -0.5, v5
	v_mul_f32_e32 v5, 0x3fb8aa3b, v5
	v_exp_f32_e32 v5, v5
	s_nop 0
	v_mul_f32_e32 v5, 0xbfb8aa3b, v5
	v_exp_f32_e32 v5, v5
	global_store_dwordx4 v[22:23], v[2:5], off offset:576
	s_branch .LBB0_779

.LBB0_1992:
	v_ashrrev_i32_e32 v151, 31, v150
	v_mov_b64_e32 v[152:153], s[6:7]
	v_mad_i64_i32 v[154:155], s[26:27], v148, s91, v[152:153]
	v_lshlrev_b64 v[4:5], 1, v[150:151]
	v_lshl_add_u64 v[150:151], v[154:155], 0, v[4:5]
	v_add_co_u32_e32 v154, vcc, s70, v150
	s_mov_b32 s2, s18
	s_nop 0
	v_addc_co_u32_e32 v155, vcc, 0, v151, vcc
	global_load_dwordx2 v[154:155], v[154:155], off offset:3072
	v_lshl_add_u64 v[150:151], v[150:151], 0, s[16:17]
	s_mov_b32 s8, s20
	s_mov_b64 s[40:41], s[24:25]
	s_mov_b64 s[42:43], s[22:23]
	v_mov_b32_e32 v218, v150
	v_mov_b32_e32 v219, v151
	v_ashrrev_i32_e32 v149, 31, v148
	v_lshlrev_b64 v[220:221], 12, v[148:149]
	v_lshl_add_u64 v[220:221], s[10:11], 0, v[220:221]
	v_lshl_add_u64 v[220:221], v[220:221], 0, v[4:5]
	v_mov_b32_e32 v210, 0x5c000
	v_mov_b32_e32 v211, 0
	v_mov_b32_e32 v212, 0x1cc000
	v_mov_b32_e32 v213, 0
	v_mov_b32_e32 v214, 0x10000
	v_mov_b32_e32 v215, 0
	v_mov_b32_e32 v216, 0x50000
	v_mov_b32_e32 v217, 0
	global_load_dwordx2 v[178:179], v[218:219], off
	global_load_dwordx2 v[180:181], v[218:219], off offset:32
	global_load_dwordx2 v[182:183], v[218:219], off offset:256
	global_load_dwordx2 v[184:185], v[218:219], off offset:288
	v_lshl_add_u64 v[218:219], v[218:219], 0, v[210:211]
	global_load_dwordx2 v[186:187], v[218:219], off
	global_load_dwordx2 v[188:189], v[218:219], off offset:32
	global_load_dwordx2 v[190:191], v[218:219], off offset:256
	global_load_dwordx2 v[192:193], v[218:219], off offset:288
	v_lshl_add_u64 v[218:219], v[218:219], 0, v[210:211]
	s_waitcnt vmcnt(4)
	v_lshlrev_b32_e32 v194, 16, v178
	v_and_b32_e32 v195, 0xffff0000, v178
	v_lshlrev_b32_e32 v196, 16, v179
	v_and_b32_e32 v197, 0xffff0000, v179
	v_lshlrev_b32_e32 v198, 16, v180
	v_and_b32_e32 v199, 0xffff0000, v180
	v_lshlrev_b32_e32 v200, 16, v181
	v_and_b32_e32 v201, 0xffff0000, v181
	v_lshlrev_b32_e32 v202, 16, v182
	v_and_b32_e32 v203, 0xffff0000, v182
	v_lshlrev_b32_e32 v204, 16, v183
	v_and_b32_e32 v205, 0xffff0000, v183
	v_lshlrev_b32_e32 v206, 16, v184
	v_and_b32_e32 v207, 0xffff0000, v184
	v_lshlrev_b32_e32 v208, 16, v185
	v_and_b32_e32 v209, 0xffff0000, v185
	v_mul_f32_e32 v194, 0xbfb8aa3b, v194
	v_mul_f32_e32 v195, 0xbfb8aa3b, v195
	v_mul_f32_e32 v196, 0xbfb8aa3b, v196
	v_mul_f32_e32 v197, 0xbfb8aa3b, v197
	v_mul_f32_e32 v198, 0xbfb8aa3b, v198
	v_mul_f32_e32 v199, 0xbfb8aa3b, v199
	v_mul_f32_e32 v200, 0xbfb8aa3b, v200
	v_mul_f32_e32 v201, 0xbfb8aa3b, v201
	v_mul_f32_e32 v202, 0xbfb8aa3b, v202
	v_mul_f32_e32 v203, 0xbfb8aa3b, v203
	v_mul_f32_e32 v204, 0xbfb8aa3b, v204
	v_mul_f32_e32 v205, 0xbfb8aa3b, v205
	v_mul_f32_e32 v206, 0xbfb8aa3b, v206
	v_mul_f32_e32 v207, 0xbfb8aa3b, v207
	v_mul_f32_e32 v208, 0xbfb8aa3b, v208
	v_mul_f32_e32 v209, 0xbfb8aa3b, v209
	v_exp_f32_e32 v194, v194
	v_exp_f32_e32 v195, v195
	v_exp_f32_e32 v196, v196
	v_exp_f32_e32 v197, v197
	v_exp_f32_e32 v198, v198
	v_exp_f32_e32 v199, v199
	v_exp_f32_e32 v200, v200
	v_exp_f32_e32 v201, v201
	v_exp_f32_e32 v202, v202
	v_exp_f32_e32 v203, v203
	v_exp_f32_e32 v204, v204
	v_exp_f32_e32 v205, v205
	v_exp_f32_e32 v206, v206
	v_exp_f32_e32 v207, v207
	v_exp_f32_e32 v208, v208
	v_exp_f32_e32 v209, v209
	v_add_f32_e32 v194, 1.0, v194
	v_add_f32_e32 v195, 1.0, v195
	v_add_f32_e32 v196, 1.0, v196
	v_add_f32_e32 v197, 1.0, v197
	v_add_f32_e32 v198, 1.0, v198
	v_add_f32_e32 v199, 1.0, v199
	v_add_f32_e32 v200, 1.0, v200
	v_add_f32_e32 v201, 1.0, v201
	v_add_f32_e32 v202, 1.0, v202
	v_add_f32_e32 v203, 1.0, v203
	v_add_f32_e32 v204, 1.0, v204
	v_add_f32_e32 v205, 1.0, v205
	v_add_f32_e32 v206, 1.0, v206
	v_add_f32_e32 v207, 1.0, v207
	v_add_f32_e32 v208, 1.0, v208
	v_add_f32_e32 v209, 1.0, v209
	v_rcp_f32_e32 v194, v194
	v_rcp_f32_e32 v195, v195
	v_rcp_f32_e32 v196, v196
	v_rcp_f32_e32 v197, v197
	v_rcp_f32_e32 v198, v198
	v_rcp_f32_e32 v199, v199
	v_rcp_f32_e32 v200, v200
	v_rcp_f32_e32 v201, v201
	v_rcp_f32_e32 v202, v202
	v_rcp_f32_e32 v203, v203
	v_rcp_f32_e32 v204, v204
	v_rcp_f32_e32 v205, v205
	v_rcp_f32_e32 v206, v206
	v_rcp_f32_e32 v207, v207
	v_rcp_f32_e32 v208, v208
	v_rcp_f32_e32 v209, v209
	v_mul_f32_e32 v132, v132, v194
	v_mul_f32_e32 v133, v133, v195
	v_mul_f32_e32 v134, v134, v196
	v_mul_f32_e32 v135, v135, v197
	v_mul_f32_e32 v128, v128, v198
	v_mul_f32_e32 v129, v129, v199
	v_mul_f32_e32 v130, v130, v200
	v_mul_f32_e32 v131, v131, v201
	v_mul_f32_e32 v124, v124, v202
	v_mul_f32_e32 v125, v125, v203
	v_mul_f32_e32 v126, v126, v204
	v_mul_f32_e32 v127, v127, v205
	v_mul_f32_e32 v120, v120, v206
	v_mul_f32_e32 v121, v121, v207
	v_mul_f32_e32 v122, v122, v208
	v_mul_f32_e32 v123, v123, v209
	v_cvt_pk_bf16_f32 v132, v132, v133
	v_cvt_pk_bf16_f32 v128, v128, v129
	v_cvt_pk_bf16_f32 v124, v124, v125
	v_cvt_pk_bf16_f32 v120, v120, v121
	s_nop 0
	v_cvt_pk_bf16_f32 v133, v134, v135
	v_cvt_pk_bf16_f32 v129, v130, v131
	v_cvt_pk_bf16_f32 v125, v126, v127
	v_cvt_pk_bf16_f32 v121, v122, v123
	global_store_dwordx2 v[220:221], v[132:133], off
	global_store_dwordx2 v[220:221], v[128:129], off offset:32
	global_store_dwordx2 v[220:221], v[124:125], off offset:256
	global_store_dwordx2 v[220:221], v[120:121], off offset:288
	v_lshl_add_u64 v[220:221], v[220:221], 0, v[214:215]
	global_load_dwordx2 v[178:179], v[218:219], off
	global_load_dwordx2 v[180:181], v[218:219], off offset:32
	global_load_dwordx2 v[182:183], v[218:219], off offset:256
	global_load_dwordx2 v[184:185], v[218:219], off offset:288
	v_lshl_add_u64 v[218:219], v[218:219], 0, v[210:211]
	s_waitcnt vmcnt(8)
	v_lshlrev_b32_e32 v194, 16, v186
	v_and_b32_e32 v195, 0xffff0000, v186
	v_lshlrev_b32_e32 v196, 16, v187
	v_and_b32_e32 v197, 0xffff0000, v187
	v_lshlrev_b32_e32 v198, 16, v188
	v_and_b32_e32 v199, 0xffff0000, v188
	v_lshlrev_b32_e32 v200, 16, v189
	v_and_b32_e32 v201, 0xffff0000, v189
	v_lshlrev_b32_e32 v202, 16, v190
	v_and_b32_e32 v203, 0xffff0000, v190
	v_lshlrev_b32_e32 v204, 16, v191
	v_and_b32_e32 v205, 0xffff0000, v191
	v_lshlrev_b32_e32 v206, 16, v192
	v_and_b32_e32 v207, 0xffff0000, v192
	v_lshlrev_b32_e32 v208, 16, v193
	v_and_b32_e32 v209, 0xffff0000, v193
	v_mul_f32_e32 v194, 0xbfb8aa3b, v194
	v_mul_f32_e32 v195, 0xbfb8aa3b, v195
	v_mul_f32_e32 v196, 0xbfb8aa3b, v196
	v_mul_f32_e32 v197, 0xbfb8aa3b, v197
	v_mul_f32_e32 v198, 0xbfb8aa3b, v198
	v_mul_f32_e32 v199, 0xbfb8aa3b, v199
	v_mul_f32_e32 v200, 0xbfb8aa3b, v200
	v_mul_f32_e32 v201, 0xbfb8aa3b, v201
	v_mul_f32_e32 v202, 0xbfb8aa3b, v202
	v_mul_f32_e32 v203, 0xbfb8aa3b, v203
	v_mul_f32_e32 v204, 0xbfb8aa3b, v204
	v_mul_f32_e32 v205, 0xbfb8aa3b, v205
	v_mul_f32_e32 v206, 0xbfb8aa3b, v206
	v_mul_f32_e32 v207, 0xbfb8aa3b, v207
	v_mul_f32_e32 v208, 0xbfb8aa3b, v208
	v_mul_f32_e32 v209, 0xbfb8aa3b, v209
	v_exp_f32_e32 v194, v194
	v_exp_f32_e32 v195, v195
	v_exp_f32_e32 v196, v196
	v_exp_f32_e32 v197, v197
	v_exp_f32_e32 v198, v198
	v_exp_f32_e32 v199, v199
	v_exp_f32_e32 v200, v200
	v_exp_f32_e32 v201, v201
	v_exp_f32_e32 v202, v202
	v_exp_f32_e32 v203, v203
	v_exp_f32_e32 v204, v204
	v_exp_f32_e32 v205, v205
	v_exp_f32_e32 v206, v206
	v_exp_f32_e32 v207, v207
	v_exp_f32_e32 v208, v208
	v_exp_f32_e32 v209, v209
	v_add_f32_e32 v194, 1.0, v194
	v_add_f32_e32 v195, 1.0, v195
	v_add_f32_e32 v196, 1.0, v196
	v_add_f32_e32 v197, 1.0, v197
	v_add_f32_e32 v198, 1.0, v198
	v_add_f32_e32 v199, 1.0, v199
	v_add_f32_e32 v200, 1.0, v200
	v_add_f32_e32 v201, 1.0, v201
	v_add_f32_e32 v202, 1.0, v202
	v_add_f32_e32 v203, 1.0, v203
	v_add_f32_e32 v204, 1.0, v204
	v_add_f32_e32 v205, 1.0, v205
	v_add_f32_e32 v206, 1.0, v206
	v_add_f32_e32 v207, 1.0, v207
	v_add_f32_e32 v208, 1.0, v208
	v_add_f32_e32 v209, 1.0, v209
	v_rcp_f32_e32 v194, v194
	v_rcp_f32_e32 v195, v195
	v_rcp_f32_e32 v196, v196
	v_rcp_f32_e32 v197, v197
	v_rcp_f32_e32 v198, v198
	v_rcp_f32_e32 v199, v199
	v_rcp_f32_e32 v200, v200
	v_rcp_f32_e32 v201, v201
	v_rcp_f32_e32 v202, v202
	v_rcp_f32_e32 v203, v203
	v_rcp_f32_e32 v204, v204
	v_rcp_f32_e32 v205, v205
	v_rcp_f32_e32 v206, v206
	v_rcp_f32_e32 v207, v207
	v_rcp_f32_e32 v208, v208
	v_rcp_f32_e32 v209, v209
	v_mul_f32_e32 v116, v116, v194
	v_mul_f32_e32 v117, v117, v195
	v_mul_f32_e32 v118, v118, v196
	v_mul_f32_e32 v119, v119, v197
	v_mul_f32_e32 v112, v112, v198
	v_mul_f32_e32 v113, v113, v199
	v_mul_f32_e32 v114, v114, v200
	v_mul_f32_e32 v115, v115, v201
	v_mul_f32_e32 v108, v108, v202
	v_mul_f32_e32 v109, v109, v203
	v_mul_f32_e32 v110, v110, v204
	v_mul_f32_e32 v111, v111, v205
	v_mul_f32_e32 v104, v104, v206
	v_mul_f32_e32 v105, v105, v207
	v_mul_f32_e32 v106, v106, v208
	v_mul_f32_e32 v107, v107, v209
	v_cvt_pk_bf16_f32 v116, v116, v117
	v_cvt_pk_bf16_f32 v112, v112, v113
	v_cvt_pk_bf16_f32 v108, v108, v109
	v_cvt_pk_bf16_f32 v104, v104, v105
	s_nop 0
	v_cvt_pk_bf16_f32 v117, v118, v119
	v_cvt_pk_bf16_f32 v113, v114, v115
	v_cvt_pk_bf16_f32 v109, v110, v111
	v_cvt_pk_bf16_f32 v105, v106, v107
	global_store_dwordx2 v[220:221], v[116:117], off
	global_store_dwordx2 v[220:221], v[112:113], off offset:32
	global_store_dwordx2 v[220:221], v[108:109], off offset:256
	global_store_dwordx2 v[220:221], v[104:105], off offset:288
	v_lshl_add_u64 v[220:221], v[220:221], 0, v[214:215]
	global_load_dwordx2 v[186:187], v[218:219], off
	global_load_dwordx2 v[188:189], v[218:219], off offset:32
	global_load_dwordx2 v[190:191], v[218:219], off offset:256
	global_load_dwordx2 v[192:193], v[218:219], off offset:288
	v_lshl_add_u64 v[218:219], v[218:219], 0, v[212:213]
	s_waitcnt vmcnt(8)
	v_lshlrev_b32_e32 v194, 16, v178
	v_and_b32_e32 v195, 0xffff0000, v178
	v_lshlrev_b32_e32 v196, 16, v179
	v_and_b32_e32 v197, 0xffff0000, v179
	v_lshlrev_b32_e32 v198, 16, v180
	v_and_b32_e32 v199, 0xffff0000, v180
	v_lshlrev_b32_e32 v200, 16, v181
	v_and_b32_e32 v201, 0xffff0000, v181
	v_lshlrev_b32_e32 v202, 16, v182
	v_and_b32_e32 v203, 0xffff0000, v182
	v_lshlrev_b32_e32 v204, 16, v183
	v_and_b32_e32 v205, 0xffff0000, v183
	v_lshlrev_b32_e32 v206, 16, v184
	v_and_b32_e32 v207, 0xffff0000, v184
	v_lshlrev_b32_e32 v208, 16, v185
	v_and_b32_e32 v209, 0xffff0000, v185
	v_mul_f32_e32 v194, 0xbfb8aa3b, v194
	v_mul_f32_e32 v195, 0xbfb8aa3b, v195
	v_mul_f32_e32 v196, 0xbfb8aa3b, v196
	v_mul_f32_e32 v197, 0xbfb8aa3b, v197
	v_mul_f32_e32 v198, 0xbfb8aa3b, v198
	v_mul_f32_e32 v199, 0xbfb8aa3b, v199
	v_mul_f32_e32 v200, 0xbfb8aa3b, v200
	v_mul_f32_e32 v201, 0xbfb8aa3b, v201
	v_mul_f32_e32 v202, 0xbfb8aa3b, v202
	v_mul_f32_e32 v203, 0xbfb8aa3b, v203
	v_mul_f32_e32 v204, 0xbfb8aa3b, v204
	v_mul_f32_e32 v205, 0xbfb8aa3b, v205
	v_mul_f32_e32 v206, 0xbfb8aa3b, v206
	v_mul_f32_e32 v207, 0xbfb8aa3b, v207
	v_mul_f32_e32 v208, 0xbfb8aa3b, v208
	v_mul_f32_e32 v209, 0xbfb8aa3b, v209
	v_exp_f32_e32 v194, v194
	v_exp_f32_e32 v195, v195
	v_exp_f32_e32 v196, v196
	v_exp_f32_e32 v197, v197
	v_exp_f32_e32 v198, v198
	v_exp_f32_e32 v199, v199
	v_exp_f32_e32 v200, v200
	v_exp_f32_e32 v201, v201
	v_exp_f32_e32 v202, v202
	v_exp_f32_e32 v203, v203
	v_exp_f32_e32 v204, v204
	v_exp_f32_e32 v205, v205
	v_exp_f32_e32 v206, v206
	v_exp_f32_e32 v207, v207
	v_exp_f32_e32 v208, v208
	v_exp_f32_e32 v209, v209
	v_add_f32_e32 v194, 1.0, v194
	v_add_f32_e32 v195, 1.0, v195
	v_add_f32_e32 v196, 1.0, v196
	v_add_f32_e32 v197, 1.0, v197
	v_add_f32_e32 v198, 1.0, v198
	v_add_f32_e32 v199, 1.0, v199
	v_add_f32_e32 v200, 1.0, v200
	v_add_f32_e32 v201, 1.0, v201
	v_add_f32_e32 v202, 1.0, v202
	v_add_f32_e32 v203, 1.0, v203
	v_add_f32_e32 v204, 1.0, v204
	v_add_f32_e32 v205, 1.0, v205
	v_add_f32_e32 v206, 1.0, v206
	v_add_f32_e32 v207, 1.0, v207
	v_add_f32_e32 v208, 1.0, v208
	v_add_f32_e32 v209, 1.0, v209
	v_rcp_f32_e32 v194, v194
	v_rcp_f32_e32 v195, v195
	v_rcp_f32_e32 v196, v196
	v_rcp_f32_e32 v197, v197
	v_rcp_f32_e32 v198, v198
	v_rcp_f32_e32 v199, v199
	v_rcp_f32_e32 v200, v200
	v_rcp_f32_e32 v201, v201
	v_rcp_f32_e32 v202, v202
	v_rcp_f32_e32 v203, v203
	v_rcp_f32_e32 v204, v204
	v_rcp_f32_e32 v205, v205
	v_rcp_f32_e32 v206, v206
	v_rcp_f32_e32 v207, v207
	v_rcp_f32_e32 v208, v208
	v_rcp_f32_e32 v209, v209
	v_mul_f32_e32 v100, v100, v194
	v_mul_f32_e32 v101, v101, v195
	v_mul_f32_e32 v102, v102, v196
	v_mul_f32_e32 v103, v103, v197
	v_mul_f32_e32 v96, v96, v198
	v_mul_f32_e32 v97, v97, v199
	v_mul_f32_e32 v98, v98, v200
	v_mul_f32_e32 v99, v99, v201
	v_mul_f32_e32 v92, v92, v202
	v_mul_f32_e32 v93, v93, v203
	v_mul_f32_e32 v94, v94, v204
	v_mul_f32_e32 v95, v95, v205
	v_mul_f32_e32 v88, v88, v206
	v_mul_f32_e32 v89, v89, v207
	v_mul_f32_e32 v90, v90, v208
	v_mul_f32_e32 v91, v91, v209
	v_cvt_pk_bf16_f32 v100, v100, v101
	v_cvt_pk_bf16_f32 v96, v96, v97
	v_cvt_pk_bf16_f32 v92, v92, v93
	v_cvt_pk_bf16_f32 v88, v88, v89
	s_nop 0
	v_cvt_pk_bf16_f32 v101, v102, v103
	v_cvt_pk_bf16_f32 v97, v98, v99
	v_cvt_pk_bf16_f32 v93, v94, v95
	v_cvt_pk_bf16_f32 v89, v90, v91
	global_store_dwordx2 v[220:221], v[100:101], off
	global_store_dwordx2 v[220:221], v[96:97], off offset:32
	global_store_dwordx2 v[220:221], v[92:93], off offset:256
	global_store_dwordx2 v[220:221], v[88:89], off offset:288
	v_lshl_add_u64 v[220:221], v[220:221], 0, v[214:215]
	global_load_dwordx2 v[178:179], v[218:219], off
	global_load_dwordx2 v[180:181], v[218:219], off offset:32
	global_load_dwordx2 v[182:183], v[218:219], off offset:256
	global_load_dwordx2 v[184:185], v[218:219], off offset:288
	v_lshl_add_u64 v[218:219], v[218:219], 0, v[210:211]
	s_waitcnt vmcnt(8)
	v_lshlrev_b32_e32 v194, 16, v186
	v_and_b32_e32 v195, 0xffff0000, v186
	v_lshlrev_b32_e32 v196, 16, v187
	v_and_b32_e32 v197, 0xffff0000, v187
	v_lshlrev_b32_e32 v198, 16, v188
	v_and_b32_e32 v199, 0xffff0000, v188
	v_lshlrev_b32_e32 v200, 16, v189
	v_and_b32_e32 v201, 0xffff0000, v189
	v_lshlrev_b32_e32 v202, 16, v190
	v_and_b32_e32 v203, 0xffff0000, v190
	v_lshlrev_b32_e32 v204, 16, v191
	v_and_b32_e32 v205, 0xffff0000, v191
	v_lshlrev_b32_e32 v206, 16, v192
	v_and_b32_e32 v207, 0xffff0000, v192
	v_lshlrev_b32_e32 v208, 16, v193
	v_and_b32_e32 v209, 0xffff0000, v193
	v_mul_f32_e32 v194, 0xbfb8aa3b, v194
	v_mul_f32_e32 v195, 0xbfb8aa3b, v195
	v_mul_f32_e32 v196, 0xbfb8aa3b, v196
	v_mul_f32_e32 v197, 0xbfb8aa3b, v197
	v_mul_f32_e32 v198, 0xbfb8aa3b, v198
	v_mul_f32_e32 v199, 0xbfb8aa3b, v199
	v_mul_f32_e32 v200, 0xbfb8aa3b, v200
	v_mul_f32_e32 v201, 0xbfb8aa3b, v201
	v_mul_f32_e32 v202, 0xbfb8aa3b, v202
	v_mul_f32_e32 v203, 0xbfb8aa3b, v203
	v_mul_f32_e32 v204, 0xbfb8aa3b, v204
	v_mul_f32_e32 v205, 0xbfb8aa3b, v205
	v_mul_f32_e32 v206, 0xbfb8aa3b, v206
	v_mul_f32_e32 v207, 0xbfb8aa3b, v207
	v_mul_f32_e32 v208, 0xbfb8aa3b, v208
	v_mul_f32_e32 v209, 0xbfb8aa3b, v209
	v_exp_f32_e32 v194, v194
	v_exp_f32_e32 v195, v195
	v_exp_f32_e32 v196, v196
	v_exp_f32_e32 v197, v197
	v_exp_f32_e32 v198, v198
	v_exp_f32_e32 v199, v199
	v_exp_f32_e32 v200, v200
	v_exp_f32_e32 v201, v201
	v_exp_f32_e32 v202, v202
	v_exp_f32_e32 v203, v203
	v_exp_f32_e32 v204, v204
	v_exp_f32_e32 v205, v205
	v_exp_f32_e32 v206, v206
	v_exp_f32_e32 v207, v207
	v_exp_f32_e32 v208, v208
	v_exp_f32_e32 v209, v209
	v_add_f32_e32 v194, 1.0, v194
	v_add_f32_e32 v195, 1.0, v195
	v_add_f32_e32 v196, 1.0, v196
	v_add_f32_e32 v197, 1.0, v197
	v_add_f32_e32 v198, 1.0, v198
	v_add_f32_e32 v199, 1.0, v199
	v_add_f32_e32 v200, 1.0, v200
	v_add_f32_e32 v201, 1.0, v201
	v_add_f32_e32 v202, 1.0, v202
	v_add_f32_e32 v203, 1.0, v203
	v_add_f32_e32 v204, 1.0, v204
	v_add_f32_e32 v205, 1.0, v205
	v_add_f32_e32 v206, 1.0, v206
	v_add_f32_e32 v207, 1.0, v207
	v_add_f32_e32 v208, 1.0, v208
	v_add_f32_e32 v209, 1.0, v209
	v_rcp_f32_e32 v194, v194
	v_rcp_f32_e32 v195, v195
	v_rcp_f32_e32 v196, v196
	v_rcp_f32_e32 v197, v197
	v_rcp_f32_e32 v198, v198
	v_rcp_f32_e32 v199, v199
	v_rcp_f32_e32 v200, v200
	v_rcp_f32_e32 v201, v201
	v_rcp_f32_e32 v202, v202
	v_rcp_f32_e32 v203, v203
	v_rcp_f32_e32 v204, v204
	v_rcp_f32_e32 v205, v205
	v_rcp_f32_e32 v206, v206
	v_rcp_f32_e32 v207, v207
	v_rcp_f32_e32 v208, v208
	v_rcp_f32_e32 v209, v209
	v_mul_f32_e32 v84, v84, v194
	v_mul_f32_e32 v85, v85, v195
	v_mul_f32_e32 v86, v86, v196
	v_mul_f32_e32 v87, v87, v197
	v_mul_f32_e32 v80, v80, v198
	v_mul_f32_e32 v81, v81, v199
	v_mul_f32_e32 v82, v82, v200
	v_mul_f32_e32 v83, v83, v201
	v_mul_f32_e32 v76, v76, v202
	v_mul_f32_e32 v77, v77, v203
	v_mul_f32_e32 v78, v78, v204
	v_mul_f32_e32 v79, v79, v205
	v_mul_f32_e32 v72, v72, v206
	v_mul_f32_e32 v73, v73, v207
	v_mul_f32_e32 v74, v74, v208
	v_mul_f32_e32 v75, v75, v209
	v_cvt_pk_bf16_f32 v84, v84, v85
	v_cvt_pk_bf16_f32 v80, v80, v81
	v_cvt_pk_bf16_f32 v76, v76, v77
	v_cvt_pk_bf16_f32 v72, v72, v73
	s_nop 0
	v_cvt_pk_bf16_f32 v85, v86, v87
	v_cvt_pk_bf16_f32 v81, v82, v83
	v_cvt_pk_bf16_f32 v77, v78, v79
	v_cvt_pk_bf16_f32 v73, v74, v75
	global_store_dwordx2 v[220:221], v[84:85], off
	global_store_dwordx2 v[220:221], v[80:81], off offset:32
	global_store_dwordx2 v[220:221], v[76:77], off offset:256
	global_store_dwordx2 v[220:221], v[72:73], off offset:288
	v_lshl_add_u64 v[220:221], v[220:221], 0, v[216:217]
	global_load_dwordx2 v[186:187], v[218:219], off
	global_load_dwordx2 v[188:189], v[218:219], off offset:32
	global_load_dwordx2 v[190:191], v[218:219], off offset:256
	global_load_dwordx2 v[192:193], v[218:219], off offset:288
	v_lshl_add_u64 v[218:219], v[218:219], 0, v[210:211]
	s_waitcnt vmcnt(8)
	v_lshlrev_b32_e32 v194, 16, v178
	v_and_b32_e32 v195, 0xffff0000, v178
	v_lshlrev_b32_e32 v196, 16, v179
	v_and_b32_e32 v197, 0xffff0000, v179
	v_lshlrev_b32_e32 v198, 16, v180
	v_and_b32_e32 v199, 0xffff0000, v180
	v_lshlrev_b32_e32 v200, 16, v181
	v_and_b32_e32 v201, 0xffff0000, v181
	v_lshlrev_b32_e32 v202, 16, v182
	v_and_b32_e32 v203, 0xffff0000, v182
	v_lshlrev_b32_e32 v204, 16, v183
	v_and_b32_e32 v205, 0xffff0000, v183
	v_lshlrev_b32_e32 v206, 16, v184
	v_and_b32_e32 v207, 0xffff0000, v184
	v_lshlrev_b32_e32 v208, 16, v185
	v_and_b32_e32 v209, 0xffff0000, v185
	v_mul_f32_e32 v194, 0xbfb8aa3b, v194
	v_mul_f32_e32 v195, 0xbfb8aa3b, v195
	v_mul_f32_e32 v196, 0xbfb8aa3b, v196
	v_mul_f32_e32 v197, 0xbfb8aa3b, v197
	v_mul_f32_e32 v198, 0xbfb8aa3b, v198
	v_mul_f32_e32 v199, 0xbfb8aa3b, v199
	v_mul_f32_e32 v200, 0xbfb8aa3b, v200
	v_mul_f32_e32 v201, 0xbfb8aa3b, v201
	v_mul_f32_e32 v202, 0xbfb8aa3b, v202
	v_mul_f32_e32 v203, 0xbfb8aa3b, v203
	v_mul_f32_e32 v204, 0xbfb8aa3b, v204
	v_mul_f32_e32 v205, 0xbfb8aa3b, v205
	v_mul_f32_e32 v206, 0xbfb8aa3b, v206
	v_mul_f32_e32 v207, 0xbfb8aa3b, v207
	v_mul_f32_e32 v208, 0xbfb8aa3b, v208
	v_mul_f32_e32 v209, 0xbfb8aa3b, v209
	v_exp_f32_e32 v194, v194
	v_exp_f32_e32 v195, v195
	v_exp_f32_e32 v196, v196
	v_exp_f32_e32 v197, v197
	v_exp_f32_e32 v198, v198
	v_exp_f32_e32 v199, v199
	v_exp_f32_e32 v200, v200
	v_exp_f32_e32 v201, v201
	v_exp_f32_e32 v202, v202
	v_exp_f32_e32 v203, v203
	v_exp_f32_e32 v204, v204
	v_exp_f32_e32 v205, v205
	v_exp_f32_e32 v206, v206
	v_exp_f32_e32 v207, v207
	v_exp_f32_e32 v208, v208
	v_exp_f32_e32 v209, v209
	v_add_f32_e32 v194, 1.0, v194
	v_add_f32_e32 v195, 1.0, v195
	v_add_f32_e32 v196, 1.0, v196
	v_add_f32_e32 v197, 1.0, v197
	v_add_f32_e32 v198, 1.0, v198
	v_add_f32_e32 v199, 1.0, v199
	v_add_f32_e32 v200, 1.0, v200
	v_add_f32_e32 v201, 1.0, v201
	v_add_f32_e32 v202, 1.0, v202
	v_add_f32_e32 v203, 1.0, v203
	v_add_f32_e32 v204, 1.0, v204
	v_add_f32_e32 v205, 1.0, v205
	v_add_f32_e32 v206, 1.0, v206
	v_add_f32_e32 v207, 1.0, v207
	v_add_f32_e32 v208, 1.0, v208
	v_add_f32_e32 v209, 1.0, v209
	v_rcp_f32_e32 v194, v194
	v_rcp_f32_e32 v195, v195
	v_rcp_f32_e32 v196, v196
	v_rcp_f32_e32 v197, v197
	v_rcp_f32_e32 v198, v198
	v_rcp_f32_e32 v199, v199
	v_rcp_f32_e32 v200, v200
	v_rcp_f32_e32 v201, v201
	v_rcp_f32_e32 v202, v202
	v_rcp_f32_e32 v203, v203
	v_rcp_f32_e32 v204, v204
	v_rcp_f32_e32 v205, v205
	v_rcp_f32_e32 v206, v206
	v_rcp_f32_e32 v207, v207
	v_rcp_f32_e32 v208, v208
	v_rcp_f32_e32 v209, v209
	v_mul_f32_e32 v68, v68, v194
	v_mul_f32_e32 v69, v69, v195
	v_mul_f32_e32 v70, v70, v196
	v_mul_f32_e32 v71, v71, v197
	v_mul_f32_e32 v64, v64, v198
	v_mul_f32_e32 v65, v65, v199
	v_mul_f32_e32 v66, v66, v200
	v_mul_f32_e32 v67, v67, v201
	v_mul_f32_e32 v60, v60, v202
	v_mul_f32_e32 v61, v61, v203
	v_mul_f32_e32 v62, v62, v204
	v_mul_f32_e32 v63, v63, v205
	v_mul_f32_e32 v56, v56, v206
	v_mul_f32_e32 v57, v57, v207
	v_mul_f32_e32 v58, v58, v208
	v_mul_f32_e32 v59, v59, v209
	v_cvt_pk_bf16_f32 v68, v68, v69
	v_cvt_pk_bf16_f32 v64, v64, v65
	v_cvt_pk_bf16_f32 v60, v60, v61
	v_cvt_pk_bf16_f32 v56, v56, v57
	s_nop 0
	v_cvt_pk_bf16_f32 v69, v70, v71
	v_cvt_pk_bf16_f32 v65, v66, v67
	v_cvt_pk_bf16_f32 v61, v62, v63
	v_cvt_pk_bf16_f32 v57, v58, v59
	global_store_dwordx2 v[220:221], v[68:69], off
	global_store_dwordx2 v[220:221], v[64:65], off offset:32
	global_store_dwordx2 v[220:221], v[60:61], off offset:256
	global_store_dwordx2 v[220:221], v[56:57], off offset:288
	v_lshl_add_u64 v[220:221], v[220:221], 0, v[214:215]
	global_load_dwordx2 v[178:179], v[218:219], off
	global_load_dwordx2 v[180:181], v[218:219], off offset:32
	global_load_dwordx2 v[182:183], v[218:219], off offset:256
	global_load_dwordx2 v[184:185], v[218:219], off offset:288
	v_lshl_add_u64 v[218:219], v[218:219], 0, v[210:211]
	s_waitcnt vmcnt(8)
	v_lshlrev_b32_e32 v194, 16, v186
	v_and_b32_e32 v195, 0xffff0000, v186
	v_lshlrev_b32_e32 v196, 16, v187
	v_and_b32_e32 v197, 0xffff0000, v187
	v_lshlrev_b32_e32 v198, 16, v188
	v_and_b32_e32 v199, 0xffff0000, v188
	v_lshlrev_b32_e32 v200, 16, v189
	v_and_b32_e32 v201, 0xffff0000, v189
	v_lshlrev_b32_e32 v202, 16, v190
	v_and_b32_e32 v203, 0xffff0000, v190
	v_lshlrev_b32_e32 v204, 16, v191
	v_and_b32_e32 v205, 0xffff0000, v191
	v_lshlrev_b32_e32 v206, 16, v192
	v_and_b32_e32 v207, 0xffff0000, v192
	v_lshlrev_b32_e32 v208, 16, v193
	v_and_b32_e32 v209, 0xffff0000, v193
	v_mul_f32_e32 v194, 0xbfb8aa3b, v194
	v_mul_f32_e32 v195, 0xbfb8aa3b, v195
	v_mul_f32_e32 v196, 0xbfb8aa3b, v196
	v_mul_f32_e32 v197, 0xbfb8aa3b, v197
	v_mul_f32_e32 v198, 0xbfb8aa3b, v198
	v_mul_f32_e32 v199, 0xbfb8aa3b, v199
	v_mul_f32_e32 v200, 0xbfb8aa3b, v200
	v_mul_f32_e32 v201, 0xbfb8aa3b, v201
	v_mul_f32_e32 v202, 0xbfb8aa3b, v202
	v_mul_f32_e32 v203, 0xbfb8aa3b, v203
	v_mul_f32_e32 v204, 0xbfb8aa3b, v204
	v_mul_f32_e32 v205, 0xbfb8aa3b, v205
	v_mul_f32_e32 v206, 0xbfb8aa3b, v206
	v_mul_f32_e32 v207, 0xbfb8aa3b, v207
	v_mul_f32_e32 v208, 0xbfb8aa3b, v208
	v_mul_f32_e32 v209, 0xbfb8aa3b, v209
	v_exp_f32_e32 v194, v194
	v_exp_f32_e32 v195, v195
	v_exp_f32_e32 v196, v196
	v_exp_f32_e32 v197, v197
	v_exp_f32_e32 v198, v198
	v_exp_f32_e32 v199, v199
	v_exp_f32_e32 v200, v200
	v_exp_f32_e32 v201, v201
	v_exp_f32_e32 v202, v202
	v_exp_f32_e32 v203, v203
	v_exp_f32_e32 v204, v204
	v_exp_f32_e32 v205, v205
	v_exp_f32_e32 v206, v206
	v_exp_f32_e32 v207, v207
	v_exp_f32_e32 v208, v208
	v_exp_f32_e32 v209, v209
	v_add_f32_e32 v194, 1.0, v194
	v_add_f32_e32 v195, 1.0, v195
	v_add_f32_e32 v196, 1.0, v196
	v_add_f32_e32 v197, 1.0, v197
	v_add_f32_e32 v198, 1.0, v198
	v_add_f32_e32 v199, 1.0, v199
	v_add_f32_e32 v200, 1.0, v200
	v_add_f32_e32 v201, 1.0, v201
	v_add_f32_e32 v202, 1.0, v202
	v_add_f32_e32 v203, 1.0, v203
	v_add_f32_e32 v204, 1.0, v204
	v_add_f32_e32 v205, 1.0, v205
	v_add_f32_e32 v206, 1.0, v206
	v_add_f32_e32 v207, 1.0, v207
	v_add_f32_e32 v208, 1.0, v208
	v_add_f32_e32 v209, 1.0, v209
	v_rcp_f32_e32 v194, v194
	v_rcp_f32_e32 v195, v195
	v_rcp_f32_e32 v196, v196
	v_rcp_f32_e32 v197, v197
	v_rcp_f32_e32 v198, v198
	v_rcp_f32_e32 v199, v199
	v_rcp_f32_e32 v200, v200
	v_rcp_f32_e32 v201, v201
	v_rcp_f32_e32 v202, v202
	v_rcp_f32_e32 v203, v203
	v_rcp_f32_e32 v204, v204
	v_rcp_f32_e32 v205, v205
	v_rcp_f32_e32 v206, v206
	v_rcp_f32_e32 v207, v207
	v_rcp_f32_e32 v208, v208
	v_rcp_f32_e32 v209, v209
	v_mul_f32_e32 v52, v52, v194
	v_mul_f32_e32 v53, v53, v195
	v_mul_f32_e32 v54, v54, v196
	v_mul_f32_e32 v55, v55, v197
	v_mul_f32_e32 v48, v48, v198
	v_mul_f32_e32 v49, v49, v199
	v_mul_f32_e32 v50, v50, v200
	v_mul_f32_e32 v51, v51, v201
	v_mul_f32_e32 v44, v44, v202
	v_mul_f32_e32 v45, v45, v203
	v_mul_f32_e32 v46, v46, v204
	v_mul_f32_e32 v47, v47, v205
	v_mul_f32_e32 v40, v40, v206
	v_mul_f32_e32 v41, v41, v207
	v_mul_f32_e32 v42, v42, v208
	v_mul_f32_e32 v43, v43, v209
	v_cvt_pk_bf16_f32 v52, v52, v53
	v_cvt_pk_bf16_f32 v48, v48, v49
	v_cvt_pk_bf16_f32 v44, v44, v45
	v_cvt_pk_bf16_f32 v40, v40, v41
	s_nop 0
	v_cvt_pk_bf16_f32 v53, v54, v55
	v_cvt_pk_bf16_f32 v49, v50, v51
	v_cvt_pk_bf16_f32 v45, v46, v47
	v_cvt_pk_bf16_f32 v41, v42, v43
	global_store_dwordx2 v[220:221], v[52:53], off
	global_store_dwordx2 v[220:221], v[48:49], off offset:32
	global_store_dwordx2 v[220:221], v[44:45], off offset:256
	global_store_dwordx2 v[220:221], v[40:41], off offset:288
	v_lshl_add_u64 v[220:221], v[220:221], 0, v[214:215]
	global_load_dwordx2 v[186:187], v[218:219], off
	global_load_dwordx2 v[188:189], v[218:219], off offset:32
	global_load_dwordx2 v[190:191], v[218:219], off offset:256
	global_load_dwordx2 v[192:193], v[218:219], off offset:288
	v_lshl_add_u64 v[218:219], v[218:219], 0, v[212:213]
	s_waitcnt vmcnt(8)
	v_lshlrev_b32_e32 v194, 16, v178
	v_and_b32_e32 v195, 0xffff0000, v178
	v_lshlrev_b32_e32 v196, 16, v179
	v_and_b32_e32 v197, 0xffff0000, v179
	v_lshlrev_b32_e32 v198, 16, v180
	v_and_b32_e32 v199, 0xffff0000, v180
	v_lshlrev_b32_e32 v200, 16, v181
	v_and_b32_e32 v201, 0xffff0000, v181
	v_lshlrev_b32_e32 v202, 16, v182
	v_and_b32_e32 v203, 0xffff0000, v182
	v_lshlrev_b32_e32 v204, 16, v183
	v_and_b32_e32 v205, 0xffff0000, v183
	v_lshlrev_b32_e32 v206, 16, v184
	v_and_b32_e32 v207, 0xffff0000, v184
	v_lshlrev_b32_e32 v208, 16, v185
	v_and_b32_e32 v209, 0xffff0000, v185
	v_mul_f32_e32 v194, 0xbfb8aa3b, v194
	v_mul_f32_e32 v195, 0xbfb8aa3b, v195
	v_mul_f32_e32 v196, 0xbfb8aa3b, v196
	v_mul_f32_e32 v197, 0xbfb8aa3b, v197
	v_mul_f32_e32 v198, 0xbfb8aa3b, v198
	v_mul_f32_e32 v199, 0xbfb8aa3b, v199
	v_mul_f32_e32 v200, 0xbfb8aa3b, v200
	v_mul_f32_e32 v201, 0xbfb8aa3b, v201
	v_mul_f32_e32 v202, 0xbfb8aa3b, v202
	v_mul_f32_e32 v203, 0xbfb8aa3b, v203
	v_mul_f32_e32 v204, 0xbfb8aa3b, v204
	v_mul_f32_e32 v205, 0xbfb8aa3b, v205
	v_mul_f32_e32 v206, 0xbfb8aa3b, v206
	v_mul_f32_e32 v207, 0xbfb8aa3b, v207
	v_mul_f32_e32 v208, 0xbfb8aa3b, v208
	v_mul_f32_e32 v209, 0xbfb8aa3b, v209
	v_exp_f32_e32 v194, v194
	v_exp_f32_e32 v195, v195
	v_exp_f32_e32 v196, v196
	v_exp_f32_e32 v197, v197
	v_exp_f32_e32 v198, v198
	v_exp_f32_e32 v199, v199
	v_exp_f32_e32 v200, v200
	v_exp_f32_e32 v201, v201
	v_exp_f32_e32 v202, v202
	v_exp_f32_e32 v203, v203
	v_exp_f32_e32 v204, v204
	v_exp_f32_e32 v205, v205
	v_exp_f32_e32 v206, v206
	v_exp_f32_e32 v207, v207
	v_exp_f32_e32 v208, v208
	v_exp_f32_e32 v209, v209
	v_add_f32_e32 v194, 1.0, v194
	v_add_f32_e32 v195, 1.0, v195
	v_add_f32_e32 v196, 1.0, v196
	v_add_f32_e32 v197, 1.0, v197
	v_add_f32_e32 v198, 1.0, v198
	v_add_f32_e32 v199, 1.0, v199
	v_add_f32_e32 v200, 1.0, v200
	v_add_f32_e32 v201, 1.0, v201
	v_add_f32_e32 v202, 1.0, v202
	v_add_f32_e32 v203, 1.0, v203
	v_add_f32_e32 v204, 1.0, v204
	v_add_f32_e32 v205, 1.0, v205
	v_add_f32_e32 v206, 1.0, v206
	v_add_f32_e32 v207, 1.0, v207
	v_add_f32_e32 v208, 1.0, v208
	v_add_f32_e32 v209, 1.0, v209
	v_rcp_f32_e32 v194, v194
	v_rcp_f32_e32 v195, v195
	v_rcp_f32_e32 v196, v196
	v_rcp_f32_e32 v197, v197
	v_rcp_f32_e32 v198, v198
	v_rcp_f32_e32 v199, v199
	v_rcp_f32_e32 v200, v200
	v_rcp_f32_e32 v201, v201
	v_rcp_f32_e32 v202, v202
	v_rcp_f32_e32 v203, v203
	v_rcp_f32_e32 v204, v204
	v_rcp_f32_e32 v205, v205
	v_rcp_f32_e32 v206, v206
	v_rcp_f32_e32 v207, v207
	v_rcp_f32_e32 v208, v208
	v_rcp_f32_e32 v209, v209
	v_mul_f32_e32 v36, v36, v194
	v_mul_f32_e32 v37, v37, v195
	v_mul_f32_e32 v38, v38, v196
	v_mul_f32_e32 v39, v39, v197
	v_mul_f32_e32 v30, v30, v198
	v_mul_f32_e32 v31, v31, v199
	v_mul_f32_e32 v32, v32, v200
	v_mul_f32_e32 v33, v33, v201
	v_mul_f32_e32 v26, v26, v202
	v_mul_f32_e32 v27, v27, v203
	v_mul_f32_e32 v28, v28, v204
	v_mul_f32_e32 v29, v29, v205
	v_mul_f32_e32 v22, v22, v206
	v_mul_f32_e32 v23, v23, v207
	v_mul_f32_e32 v24, v24, v208
	v_mul_f32_e32 v25, v25, v209
	v_cvt_pk_bf16_f32 v36, v36, v37
	v_cvt_pk_bf16_f32 v30, v30, v31
	v_cvt_pk_bf16_f32 v26, v26, v27
	v_cvt_pk_bf16_f32 v22, v22, v23
	s_nop 0
	v_cvt_pk_bf16_f32 v37, v38, v39
	v_cvt_pk_bf16_f32 v31, v32, v33
	v_cvt_pk_bf16_f32 v27, v28, v29
	v_cvt_pk_bf16_f32 v23, v24, v25
	global_store_dwordx2 v[220:221], v[36:37], off
	global_store_dwordx2 v[220:221], v[30:31], off offset:32
	global_store_dwordx2 v[220:221], v[26:27], off offset:256
	global_store_dwordx2 v[220:221], v[22:23], off offset:288
	v_lshl_add_u64 v[220:221], v[220:221], 0, v[214:215]
	s_waitcnt vmcnt(4)
	v_lshlrev_b32_e32 v194, 16, v186
	v_and_b32_e32 v195, 0xffff0000, v186
	v_lshlrev_b32_e32 v196, 16, v187
	v_and_b32_e32 v197, 0xffff0000, v187
	v_lshlrev_b32_e32 v198, 16, v188
	v_and_b32_e32 v199, 0xffff0000, v188
	v_lshlrev_b32_e32 v200, 16, v189
	v_and_b32_e32 v201, 0xffff0000, v189
	v_lshlrev_b32_e32 v202, 16, v190
	v_and_b32_e32 v203, 0xffff0000, v190
	v_lshlrev_b32_e32 v204, 16, v191
	v_and_b32_e32 v205, 0xffff0000, v191
	v_lshlrev_b32_e32 v206, 16, v192
	v_and_b32_e32 v207, 0xffff0000, v192
	v_lshlrev_b32_e32 v208, 16, v193
	v_and_b32_e32 v209, 0xffff0000, v193
	v_mul_f32_e32 v194, 0xbfb8aa3b, v194
	v_mul_f32_e32 v195, 0xbfb8aa3b, v195
	v_mul_f32_e32 v196, 0xbfb8aa3b, v196
	v_mul_f32_e32 v197, 0xbfb8aa3b, v197
	v_mul_f32_e32 v198, 0xbfb8aa3b, v198
	v_mul_f32_e32 v199, 0xbfb8aa3b, v199
	v_mul_f32_e32 v200, 0xbfb8aa3b, v200
	v_mul_f32_e32 v201, 0xbfb8aa3b, v201
	v_mul_f32_e32 v202, 0xbfb8aa3b, v202
	v_mul_f32_e32 v203, 0xbfb8aa3b, v203
	v_mul_f32_e32 v204, 0xbfb8aa3b, v204
	v_mul_f32_e32 v205, 0xbfb8aa3b, v205
	v_mul_f32_e32 v206, 0xbfb8aa3b, v206
	v_mul_f32_e32 v207, 0xbfb8aa3b, v207
	v_mul_f32_e32 v208, 0xbfb8aa3b, v208
	v_mul_f32_e32 v209, 0xbfb8aa3b, v209
	v_exp_f32_e32 v194, v194
	v_exp_f32_e32 v195, v195
	v_exp_f32_e32 v196, v196
	v_exp_f32_e32 v197, v197
	v_exp_f32_e32 v198, v198
	v_exp_f32_e32 v199, v199
	v_exp_f32_e32 v200, v200
	v_exp_f32_e32 v201, v201
	v_exp_f32_e32 v202, v202
	v_exp_f32_e32 v203, v203
	v_exp_f32_e32 v204, v204
	v_exp_f32_e32 v205, v205
	v_exp_f32_e32 v206, v206
	v_exp_f32_e32 v207, v207
	v_exp_f32_e32 v208, v208
	v_exp_f32_e32 v209, v209
	v_add_f32_e32 v194, 1.0, v194
	v_add_f32_e32 v195, 1.0, v195
	v_add_f32_e32 v196, 1.0, v196
	v_add_f32_e32 v197, 1.0, v197
	v_add_f32_e32 v198, 1.0, v198
	v_add_f32_e32 v199, 1.0, v199
	v_add_f32_e32 v200, 1.0, v200
	v_add_f32_e32 v201, 1.0, v201
	v_add_f32_e32 v202, 1.0, v202
	v_add_f32_e32 v203, 1.0, v203
	v_add_f32_e32 v204, 1.0, v204
	v_add_f32_e32 v205, 1.0, v205
	v_add_f32_e32 v206, 1.0, v206
	v_add_f32_e32 v207, 1.0, v207
	v_add_f32_e32 v208, 1.0, v208
	v_add_f32_e32 v209, 1.0, v209
	v_rcp_f32_e32 v194, v194
	v_rcp_f32_e32 v195, v195
	v_rcp_f32_e32 v196, v196
	v_rcp_f32_e32 v197, v197
	v_rcp_f32_e32 v198, v198
	v_rcp_f32_e32 v199, v199
	v_rcp_f32_e32 v200, v200
	v_rcp_f32_e32 v201, v201
	v_rcp_f32_e32 v202, v202
	v_rcp_f32_e32 v203, v203
	v_rcp_f32_e32 v204, v204
	v_rcp_f32_e32 v205, v205
	v_rcp_f32_e32 v206, v206
	v_rcp_f32_e32 v207, v207
	v_rcp_f32_e32 v208, v208
	v_rcp_f32_e32 v209, v209
	v_mul_f32_e32 v18, v18, v194
	v_mul_f32_e32 v19, v19, v195
	v_mul_f32_e32 v20, v20, v196
	v_mul_f32_e32 v21, v21, v197
	v_mul_f32_e32 v14, v14, v198
	v_mul_f32_e32 v15, v15, v199
	v_mul_f32_e32 v16, v16, v200
	v_mul_f32_e32 v17, v17, v201
	v_mul_f32_e32 v10, v10, v202
	v_mul_f32_e32 v11, v11, v203
	v_mul_f32_e32 v12, v12, v204
	v_mul_f32_e32 v13, v13, v205
	v_mul_f32_e32 v6, v6, v206
	v_mul_f32_e32 v7, v7, v207
	v_mul_f32_e32 v8, v8, v208
	v_mul_f32_e32 v9, v9, v209
	v_cvt_pk_bf16_f32 v18, v18, v19
	v_cvt_pk_bf16_f32 v14, v14, v15
	v_cvt_pk_bf16_f32 v10, v10, v11
	v_cvt_pk_bf16_f32 v6, v6, v7
	s_nop 0
	v_cvt_pk_bf16_f32 v19, v20, v21
	v_cvt_pk_bf16_f32 v15, v16, v17
	v_cvt_pk_bf16_f32 v11, v12, v13
	v_cvt_pk_bf16_f32 v7, v8, v9
	global_store_dwordx2 v[220:221], v[18:19], off
	global_store_dwordx2 v[220:221], v[14:15], off offset:32
	global_store_dwordx2 v[220:221], v[10:11], off offset:256
	global_store_dwordx2 v[220:221], v[6:7], off offset:288
	v_lshl_add_u64 v[220:221], v[220:221], 0, v[216:217]
	s_and_b64 vcc, exec, s[0:1]
	s_cbranch_vccnz .LBB0_2005

.LBB0_2165:
	ds_read_b128 v[144:147], v156
	ds_read_b128 v[148:151], v156 offset:1024
	ds_read_b128 v[160:163], v156 offset:2048
	ds_read_b128 v[174:177], v156 offset:3072
	s_add_u32 s40, s26, 0xfff80080
	s_addc_u32 s41, s27, -1
	s_cmp_eq_u32 s60, 28
	s_cselect_b32 s43, s2, s41
	s_cselect_b32 s42, s19, s40
	s_cselect_b32 s41, s17, s59
	s_cselect_b32 s40, s29, s31
	v_lshl_add_u64 v[152:153], s[26:27], 0, v[136:137]
	s_add_i32 m0, s45, 0xc000
	ds_read_b128 v[178:181], v157
	ds_read_b128 v[182:185], v157 offset:1024
	ds_read_b128 v[186:189], v157 offset:2048
	ds_read_b128 v[190:193], v157 offset:3072
	ds_read_b128 v[194:197], v157 offset:4096
	ds_read_b128 v[198:201], v157 offset:5120
	ds_read_b128 v[202:205], v157 offset:6144
	ds_read_b128 v[206:209], v157 offset:7168
	global_load_lds_dwordx4 v[152:153], off
	v_lshl_add_u64 v[152:153], s[26:27], 0, v[138:139]
	s_add_i32 m0, s45, 0xe000
	s_nop 0
	global_load_lds_dwordx4 v[152:153], off
	s_waitcnt lgkmcnt(8)
	s_barrier
	s_waitcnt lgkmcnt(0)
	s_setprio 1
	s_waitcnt lgkmcnt(0)
	v_mfma_f32_16x16x32_bf16 v[128:131], v[144:147], v[178:181], v[128:131]
	v_mfma_f32_16x16x32_bf16 v[124:127], v[160:163], v[178:181], v[124:127]
	v_mfma_f32_16x16x32_bf16 v[112:115], v[144:147], v[186:189], v[112:115]
	v_mfma_f32_16x16x32_bf16 v[108:111], v[160:163], v[186:189], v[108:111]
	v_mfma_f32_16x16x32_bf16 v[96:99], v[144:147], v[194:197], v[96:99]
	v_mfma_f32_16x16x32_bf16 v[92:95], v[160:163], v[194:197], v[92:95]
	v_mfma_f32_16x16x32_bf16 v[80:83], v[144:147], v[202:205], v[80:83]
	v_mfma_f32_16x16x32_bf16 v[76:79], v[160:163], v[202:205], v[76:79]
	v_mfma_f32_16x16x32_bf16 v[128:131], v[148:151], v[182:185], v[128:131]
	v_mfma_f32_16x16x32_bf16 v[124:127], v[174:177], v[182:185], v[124:127]
	v_mfma_f32_16x16x32_bf16 v[112:115], v[148:151], v[190:193], v[112:115]
	v_mfma_f32_16x16x32_bf16 v[108:111], v[174:177], v[190:193], v[108:111]
	v_mfma_f32_16x16x32_bf16 v[96:99], v[148:151], v[198:201], v[96:99]
	v_mfma_f32_16x16x32_bf16 v[92:95], v[174:177], v[198:201], v[92:95]
	v_mfma_f32_16x16x32_bf16 v[80:83], v[148:151], v[206:209], v[80:83]
	v_mfma_f32_16x16x32_bf16 v[76:79], v[174:177], v[206:209], v[76:79]
	s_setprio 0
	s_barrier
	s_add_i32 s61, s57, s44
	v_lshl_add_u64 v[152:153], s[40:41], 0, v[132:133]
	s_mov_b32 m0, s61
	ds_read_b128 v[210:213], v158
	ds_read_b128 v[214:217], v158 offset:1024
	ds_read_b128 v[218:221], v158 offset:2048
	ds_read_b128 v[222:225], v158 offset:3072
	global_load_lds_dwordx4 v[152:153], off
	v_lshl_add_u64 v[164:165], s[40:41], 0, v[134:135]
	s_add_i32 m0, s61, 0x2000
	s_nop 0
	global_load_lds_dwordx4 v[164:165], off
	s_barrier
	s_waitcnt lgkmcnt(0)
	s_setprio 1
	s_waitcnt lgkmcnt(0)
	v_mfma_f32_16x16x32_bf16 v[120:123], v[210:213], v[178:181], v[120:123]
	v_mfma_f32_16x16x32_bf16 v[116:119], v[218:221], v[178:181], v[116:119]
	v_mfma_f32_16x16x32_bf16 v[104:107], v[210:213], v[186:189], v[104:107]
	v_mfma_f32_16x16x32_bf16 v[100:103], v[218:221], v[186:189], v[100:103]
	v_mfma_f32_16x16x32_bf16 v[88:91], v[210:213], v[194:197], v[88:91]
	v_mfma_f32_16x16x32_bf16 v[84:87], v[218:221], v[194:197], v[84:87]
	v_mfma_f32_16x16x32_bf16 v[72:75], v[210:213], v[202:205], v[72:75]
	v_mfma_f32_16x16x32_bf16 v[68:71], v[218:221], v[202:205], v[68:71]
	v_mfma_f32_16x16x32_bf16 v[120:123], v[214:217], v[182:185], v[120:123]
	v_mfma_f32_16x16x32_bf16 v[116:119], v[222:225], v[182:185], v[116:119]
	v_mfma_f32_16x16x32_bf16 v[104:107], v[214:217], v[190:193], v[104:107]
	v_mfma_f32_16x16x32_bf16 v[100:103], v[222:225], v[190:193], v[100:103]
	v_mfma_f32_16x16x32_bf16 v[88:91], v[214:217], v[198:201], v[88:91]
	v_mfma_f32_16x16x32_bf16 v[84:87], v[222:225], v[198:201], v[84:87]
	v_mfma_f32_16x16x32_bf16 v[72:75], v[214:217], v[206:209], v[72:75]
	v_mfma_f32_16x16x32_bf16 v[68:71], v[222:225], v[206:209], v[68:71]
	s_setprio 0
	s_mov_b32 m0, s45
	v_lshl_add_u64 v[226:227], s[42:43], 0, v[132:133]
	s_barrier
	ds_read_b128 v[178:181], v157 offset:16384
	ds_read_b128 v[182:185], v157 offset:17408
	ds_read_b128 v[186:189], v157 offset:18432
	ds_read_b128 v[190:193], v157 offset:19456
	ds_read_b128 v[194:197], v157 offset:20480
	ds_read_b128 v[198:201], v157 offset:21504
	ds_read_b128 v[202:205], v157 offset:22528
	ds_read_b128 v[206:209], v157 offset:23552
	global_load_lds_dwordx4 v[226:227], off
	v_lshl_add_u64 v[228:229], s[42:43], 0, v[134:135]
	s_mov_b32 m0, s46
	s_nop 0
	global_load_lds_dwordx4 v[228:229], off
	s_barrier
	s_waitcnt lgkmcnt(0)
	s_setprio 1
	s_waitcnt lgkmcnt(0)
	v_mfma_f32_16x16x32_bf16 v[64:67], v[144:147], v[178:181], v[64:67]
	v_mfma_f32_16x16x32_bf16 v[60:63], v[160:163], v[178:181], v[60:63]
	v_mfma_f32_16x16x32_bf16 v[48:51], v[144:147], v[186:189], v[48:51]
	v_mfma_f32_16x16x32_bf16 v[44:47], v[160:163], v[186:189], v[44:47]
	v_mfma_f32_16x16x32_bf16 v[30:33], v[144:147], v[194:197], v[30:33]
	v_mfma_f32_16x16x32_bf16 v[26:29], v[160:163], v[194:197], v[26:29]
	v_mfma_f32_16x16x32_bf16 v[14:17], v[144:147], v[202:205], v[14:17]
	v_mfma_f32_16x16x32_bf16 v[10:13], v[160:163], v[202:205], v[10:13]
	v_mfma_f32_16x16x32_bf16 v[64:67], v[148:151], v[182:185], v[64:67]
	v_mfma_f32_16x16x32_bf16 v[60:63], v[174:177], v[182:185], v[60:63]
	v_mfma_f32_16x16x32_bf16 v[48:51], v[148:151], v[190:193], v[48:51]
	v_mfma_f32_16x16x32_bf16 v[44:47], v[174:177], v[190:193], v[44:47]
	v_mfma_f32_16x16x32_bf16 v[30:33], v[148:151], v[198:201], v[30:33]
	v_mfma_f32_16x16x32_bf16 v[26:29], v[174:177], v[198:201], v[26:29]
	v_mfma_f32_16x16x32_bf16 v[14:17], v[148:151], v[206:209], v[14:17]
	v_mfma_f32_16x16x32_bf16 v[10:13], v[174:177], v[206:209], v[10:13]
	s_setprio 0
	s_barrier
	s_add_u32 s62, s40, 0x80000
	s_addc_u32 s63, s41, 0
	s_add_i32 s61, s58, s44
	v_lshl_add_u64 v[144:145], s[62:63], 0, v[132:133]
	s_mov_b32 m0, s61
	s_nop 0
	global_load_lds_dwordx4 v[144:145], off
	v_lshl_add_u64 v[144:145], s[62:63], 0, v[134:135]
	s_add_i32 m0, s61, 0x2000
	s_nop 0
	global_load_lds_dwordx4 v[144:145], off
	s_waitcnt vmcnt(6)
	s_barrier
	s_setprio 1
	v_mfma_f32_16x16x32_bf16 v[56:59], v[210:213], v[178:181], v[56:59]
	v_mfma_f32_16x16x32_bf16 v[52:55], v[218:221], v[178:181], v[52:55]
	v_mfma_f32_16x16x32_bf16 v[40:43], v[210:213], v[186:189], v[40:43]
	v_mfma_f32_16x16x32_bf16 v[36:39], v[218:221], v[186:189], v[36:39]
	v_mfma_f32_16x16x32_bf16 v[22:25], v[210:213], v[194:197], v[22:25]
	v_mfma_f32_16x16x32_bf16 v[18:21], v[218:221], v[194:197], v[18:21]
	v_mfma_f32_16x16x32_bf16 v[6:9], v[210:213], v[202:205], v[6:9]
	v_mfma_f32_16x16x32_bf16 v[2:5], v[218:221], v[202:205], v[2:5]
	v_mfma_f32_16x16x32_bf16 v[56:59], v[214:217], v[182:185], v[56:59]
	v_mfma_f32_16x16x32_bf16 v[52:55], v[222:225], v[182:185], v[52:55]
	v_mfma_f32_16x16x32_bf16 v[40:43], v[214:217], v[190:193], v[40:43]
	v_mfma_f32_16x16x32_bf16 v[36:39], v[222:225], v[190:193], v[36:39]
	v_mfma_f32_16x16x32_bf16 v[22:25], v[214:217], v[198:201], v[22:25]
	v_mfma_f32_16x16x32_bf16 v[18:21], v[222:225], v[198:201], v[18:21]
	v_mfma_f32_16x16x32_bf16 v[6:9], v[214:217], v[206:209], v[6:9]
	v_mfma_f32_16x16x32_bf16 v[2:5], v[222:225], v[206:209], v[2:5]
	s_setprio 0
	s_add_i32 s61, 0, 0x18000
	v_add_u32_e32 v159, s61, v154
	s_barrier
	ds_read_b128 v[144:147], v159
	ds_read_b128 v[148:151], v159 offset:1024
	ds_read_b128 v[160:163], v159 offset:2048
	ds_read_b128 v[174:177], v159 offset:3072
	s_add_u32 s42, s42, 0x80000
	s_addc_u32 s43, s43, 0
	s_mov_b32 m0, s47
	v_lshl_add_u64 v[210:211], s[42:43], 0, v[132:133]
	ds_read_b128 v[178:181], v157 offset:32768
	ds_read_b128 v[182:185], v157 offset:33792
	ds_read_b128 v[186:189], v157 offset:34816
	ds_read_b128 v[190:193], v157 offset:35840
	ds_read_b128 v[194:197], v157 offset:36864
	ds_read_b128 v[198:201], v157 offset:37888
	ds_read_b128 v[202:205], v157 offset:38912
	ds_read_b128 v[206:209], v157 offset:39936
	global_load_lds_dwordx4 v[210:211], off
	v_lshl_add_u64 v[210:211], s[42:43], 0, v[134:135]
	s_mov_b32 m0, s48
	s_nop 0
	global_load_lds_dwordx4 v[210:211], off
	s_waitcnt lgkmcnt(8)
	s_barrier
	s_waitcnt lgkmcnt(0)
	s_setprio 1
	s_waitcnt lgkmcnt(0)
	v_mfma_f32_16x16x32_bf16 v[128:131], v[144:147], v[178:181], v[128:131]
	v_mfma_f32_16x16x32_bf16 v[124:127], v[160:163], v[178:181], v[124:127]
	v_mfma_f32_16x16x32_bf16 v[112:115], v[144:147], v[186:189], v[112:115]
	v_mfma_f32_16x16x32_bf16 v[108:111], v[160:163], v[186:189], v[108:111]
	v_mfma_f32_16x16x32_bf16 v[96:99], v[144:147], v[194:197], v[96:99]
	v_mfma_f32_16x16x32_bf16 v[92:95], v[160:163], v[194:197], v[92:95]
	v_mfma_f32_16x16x32_bf16 v[80:83], v[144:147], v[202:205], v[80:83]
	v_mfma_f32_16x16x32_bf16 v[76:79], v[160:163], v[202:205], v[76:79]
	v_mfma_f32_16x16x32_bf16 v[128:131], v[148:151], v[182:185], v[128:131]
	v_mfma_f32_16x16x32_bf16 v[124:127], v[174:177], v[182:185], v[124:127]
	v_mfma_f32_16x16x32_bf16 v[112:115], v[148:151], v[190:193], v[112:115]
	v_mfma_f32_16x16x32_bf16 v[108:111], v[174:177], v[190:193], v[108:111]
	v_mfma_f32_16x16x32_bf16 v[96:99], v[148:151], v[198:201], v[96:99]
	v_mfma_f32_16x16x32_bf16 v[92:95], v[174:177], v[198:201], v[92:95]
	v_mfma_f32_16x16x32_bf16 v[80:83], v[148:151], v[206:209], v[80:83]
	v_mfma_f32_16x16x32_bf16 v[76:79], v[174:177], v[206:209], v[76:79]
	s_setprio 0
	s_barrier
	s_add_i32 s42, 0, 0x1c000
	s_add_i32 s43, s61, s44
	v_add_u32_e32 v159, s42, v154
	v_lshl_add_u64 v[152:153], v[152:153], 0, s[10:11]
	s_mov_b32 m0, s43
	ds_read_b128 v[210:213], v159
	ds_read_b128 v[214:217], v159 offset:1024
	ds_read_b128 v[218:221], v159 offset:2048
	ds_read_b128 v[222:225], v159 offset:3072
	global_load_lds_dwordx4 v[152:153], off
	v_lshl_add_u64 v[152:153], v[164:165], 0, s[10:11]
	s_add_i32 m0, s43, 0x2000
	s_nop 0
	global_load_lds_dwordx4 v[152:153], off
	s_barrier
	s_waitcnt lgkmcnt(0)
	s_setprio 1
	s_waitcnt lgkmcnt(0)
	v_mfma_f32_16x16x32_bf16 v[120:123], v[210:213], v[178:181], v[120:123]
	v_mfma_f32_16x16x32_bf16 v[116:119], v[218:221], v[178:181], v[116:119]
	v_mfma_f32_16x16x32_bf16 v[104:107], v[210:213], v[186:189], v[104:107]
	v_mfma_f32_16x16x32_bf16 v[100:103], v[218:221], v[186:189], v[100:103]
	v_mfma_f32_16x16x32_bf16 v[88:91], v[210:213], v[194:197], v[88:91]
	v_mfma_f32_16x16x32_bf16 v[84:87], v[218:221], v[194:197], v[84:87]
	v_mfma_f32_16x16x32_bf16 v[72:75], v[210:213], v[202:205], v[72:75]
	v_mfma_f32_16x16x32_bf16 v[68:71], v[218:221], v[202:205], v[68:71]
	v_mfma_f32_16x16x32_bf16 v[120:123], v[214:217], v[182:185], v[120:123]
	v_mfma_f32_16x16x32_bf16 v[116:119], v[222:225], v[182:185], v[116:119]
	v_mfma_f32_16x16x32_bf16 v[104:107], v[214:217], v[190:193], v[104:107]
	v_mfma_f32_16x16x32_bf16 v[100:103], v[222:225], v[190:193], v[100:103]
	v_mfma_f32_16x16x32_bf16 v[88:91], v[214:217], v[198:201], v[88:91]
	v_mfma_f32_16x16x32_bf16 v[84:87], v[222:225], v[198:201], v[84:87]
	v_mfma_f32_16x16x32_bf16 v[72:75], v[214:217], v[206:209], v[72:75]
	v_mfma_f32_16x16x32_bf16 v[68:71], v[222:225], v[206:209], v[68:71]
	s_setprio 0
	s_mov_b32 m0, s53
	v_lshl_add_u64 v[152:153], v[226:227], 0, s[10:11]
	s_barrier
	ds_read_b128 v[178:181], v157 offset:49152
	ds_read_b128 v[182:185], v157 offset:50176
	ds_read_b128 v[186:189], v157 offset:51200
	ds_read_b128 v[190:193], v157 offset:52224
	ds_read_b128 v[194:197], v157 offset:53248
	ds_read_b128 v[198:201], v157 offset:54272
	ds_read_b128 v[202:205], v157 offset:55296
	ds_read_b128 v[206:209], v157 offset:56320
	global_load_lds_dwordx4 v[152:153], off
	v_lshl_add_u64 v[152:153], v[228:229], 0, s[10:11]
	s_mov_b32 m0, s54
	s_nop 0
	global_load_lds_dwordx4 v[152:153], off
	s_barrier
	s_waitcnt lgkmcnt(0)
	s_setprio 1
	s_waitcnt lgkmcnt(0)
	v_mfma_f32_16x16x32_bf16 v[64:67], v[144:147], v[178:181], v[64:67]
	v_mfma_f32_16x16x32_bf16 v[60:63], v[160:163], v[178:181], v[60:63]
	v_mfma_f32_16x16x32_bf16 v[48:51], v[144:147], v[186:189], v[48:51]
	v_mfma_f32_16x16x32_bf16 v[44:47], v[160:163], v[186:189], v[44:47]
	v_mfma_f32_16x16x32_bf16 v[30:33], v[144:147], v[194:197], v[30:33]
	v_mfma_f32_16x16x32_bf16 v[26:29], v[160:163], v[194:197], v[26:29]
	v_mfma_f32_16x16x32_bf16 v[14:17], v[144:147], v[202:205], v[14:17]
	v_mfma_f32_16x16x32_bf16 v[10:13], v[160:163], v[202:205], v[10:13]
	v_mfma_f32_16x16x32_bf16 v[64:67], v[148:151], v[182:185], v[64:67]
	v_mfma_f32_16x16x32_bf16 v[60:63], v[174:177], v[182:185], v[60:63]
	v_mfma_f32_16x16x32_bf16 v[48:51], v[148:151], v[190:193], v[48:51]
	v_mfma_f32_16x16x32_bf16 v[44:47], v[174:177], v[190:193], v[44:47]
	v_mfma_f32_16x16x32_bf16 v[30:33], v[148:151], v[198:201], v[30:33]
	v_mfma_f32_16x16x32_bf16 v[26:29], v[174:177], v[198:201], v[26:29]
	v_mfma_f32_16x16x32_bf16 v[14:17], v[148:151], v[206:209], v[14:17]
	v_mfma_f32_16x16x32_bf16 v[10:13], v[174:177], v[206:209], v[10:13]
	s_setprio 0
	s_barrier
	s_add_u32 s40, s40, 0x80080
	s_addc_u32 s41, s41, 0
	s_add_i32 s42, s42, s44
	v_lshl_add_u64 v[144:145], s[40:41], 0, v[132:133]
	s_mov_b32 m0, s42
	s_nop 0
	global_load_lds_dwordx4 v[144:145], off
	v_lshl_add_u64 v[144:145], s[40:41], 0, v[134:135]
	s_add_i32 m0, s42, 0x2000
	s_nop 0
	global_load_lds_dwordx4 v[144:145], off
	s_waitcnt vmcnt(6)
	s_barrier
	s_setprio 1
	v_mfma_f32_16x16x32_bf16 v[56:59], v[210:213], v[178:181], v[56:59]
	v_mfma_f32_16x16x32_bf16 v[52:55], v[218:221], v[178:181], v[52:55]
	v_mfma_f32_16x16x32_bf16 v[40:43], v[210:213], v[186:189], v[40:43]
	v_mfma_f32_16x16x32_bf16 v[36:39], v[218:221], v[186:189], v[36:39]
	v_mfma_f32_16x16x32_bf16 v[22:25], v[210:213], v[194:197], v[22:25]
	v_mfma_f32_16x16x32_bf16 v[18:21], v[218:221], v[194:197], v[18:21]
	v_mfma_f32_16x16x32_bf16 v[6:9], v[210:213], v[202:205], v[6:9]
	v_mfma_f32_16x16x32_bf16 v[2:5], v[218:221], v[202:205], v[2:5]
	v_mfma_f32_16x16x32_bf16 v[56:59], v[214:217], v[182:185], v[56:59]
	v_mfma_f32_16x16x32_bf16 v[52:55], v[222:225], v[182:185], v[52:55]
	v_mfma_f32_16x16x32_bf16 v[40:43], v[214:217], v[190:193], v[40:43]
	v_mfma_f32_16x16x32_bf16 v[36:39], v[222:225], v[190:193], v[36:39]
	v_mfma_f32_16x16x32_bf16 v[22:25], v[214:217], v[198:201], v[22:25]
	v_mfma_f32_16x16x32_bf16 v[18:21], v[222:225], v[198:201], v[18:21]
	v_mfma_f32_16x16x32_bf16 v[6:9], v[214:217], v[206:209], v[6:9]
	v_mfma_f32_16x16x32_bf16 v[2:5], v[222:225], v[206:209], v[2:5]
	s_setprio 0
	s_add_i32 s60, s60, 2
	s_add_u32 s26, s26, 0x100
	s_addc_u32 s27, s27, 0
	s_add_u32 s31, s31, 0x100
	s_addc_u32 s59, s59, 0
	s_cmp_gt_u32 s60, 29
	s_barrier
	s_cbranch_scc0 .LBB0_2165
	s_lshl_b32 s2, s24, 8
	s_add_i32 s2, s2, s52
	v_or_b32_e32 v144, s2, v166
	s_ashr_i32 s2, s2, 11
	s_mul_hi_i32 s17, s2, 0xc000
	s_mul_i32 s2, s2, 0xc000
	v_readlane_b32 s60, v254, 5
	v_lshl_or_b32 v164, s25, 8, v155
	s_add_u32 s2, s6, s2
	v_ashrrev_i32_e32 v145, 31, v144
	v_readlane_b32 s61, v254, 6
	s_addc_u32 s17, s7, s17
	v_ashrrev_i32_e32 v165, 31, v164
	v_lshlrev_b64 v[148:149], 13, v[144:145]
	v_readlane_b32 s62, v254, 7
	v_readlane_b32 s63, v254, 8
	s_mov_b64 s[36:37], s[60:61]
	s_add_u32 s24, s2, 0x4000
	v_lshlrev_b64 v[146:147], 2, v[164:165]
	v_lshl_add_u64 v[148:149], s[36:37], 0, v[148:149]
	s_addc_u32 s25, s17, 0
	v_lshl_add_u64 v[178:179], v[148:149], 0, v[146:147]
	v_lshlrev_b64 v[224:225], 12, v[144:145]
	v_lshlrev_b64 v[148:149], 1, v[164:165]
	v_lshl_add_u64 v[224:225], s[8:9], 0, v[224:225]
	v_lshl_add_u64 v[224:225], v[224:225], 0, v[148:149]
	v_mov_b32_e32 v222, v178
	v_mov_b32_e32 v223, v179
	v_lshl_add_u64 v[152:153], s[24:25], 0, v[146:147]
	global_load_dwordx4 v[230:233], v[152:153], off
	global_load_dwordx4 v[234:237], v[152:153], off offset:64
	global_load_dwordx4 v[238:241], v[152:153], off offset:512
	global_load_dwordx4 v[242:245], v[152:153], off offset:576
	v_mov_b32_e32 v214, 0x20000
	v_mov_b32_e32 v215, 0
	v_mov_b32_e32 v216, 0xa0000
	v_mov_b32_e32 v217, 0
	v_mov_b32_e32 v218, 0x10000
	v_mov_b32_e32 v219, 0
	v_mov_b32_e32 v220, 0x50000
	v_mov_b32_e32 v221, 0
	global_load_dwordx4 v[182:185], v[222:223], off
	global_load_dwordx4 v[186:189], v[222:223], off offset:64
	global_load_dwordx4 v[190:193], v[222:223], off offset:512
	global_load_dwordx4 v[194:197], v[222:223], off offset:576
	v_lshl_add_u64 v[222:223], v[222:223], 0, v[214:215]
	global_load_dwordx4 v[198:201], v[222:223], off
	global_load_dwordx4 v[202:205], v[222:223], off offset:64
	global_load_dwordx4 v[206:209], v[222:223], off offset:512
	global_load_dwordx4 v[210:213], v[222:223], off offset:576
	v_lshl_add_u64 v[222:223], v[222:223], 0, v[214:215]
	s_waitcnt vmcnt(4)
	v_pk_mul_f32 v[182:183], v[182:183], s[14:15] op_sel_hi:[1,0]
	v_pk_mul_f32 v[184:185], v[184:185], s[14:15] op_sel_hi:[1,0]
	v_pk_mul_f32 v[186:187], v[186:187], s[14:15] op_sel_hi:[1,0]
	v_pk_mul_f32 v[188:189], v[188:189], s[14:15] op_sel_hi:[1,0]
	v_pk_mul_f32 v[190:191], v[190:191], s[14:15] op_sel_hi:[1,0]
	v_pk_mul_f32 v[192:193], v[192:193], s[14:15] op_sel_hi:[1,0]
	v_pk_mul_f32 v[194:195], v[194:195], s[14:15] op_sel_hi:[1,0]
	v_pk_mul_f32 v[196:197], v[196:197], s[14:15] op_sel_hi:[1,0]
	v_pk_fma_f32 v[128:129], v[128:129], v[230:231], v[182:183]
	v_pk_fma_f32 v[130:131], v[130:131], v[232:233], v[184:185]
	v_pk_fma_f32 v[124:125], v[124:125], v[234:235], v[186:187]
	v_pk_fma_f32 v[126:127], v[126:127], v[236:237], v[188:189]
	v_pk_fma_f32 v[120:121], v[120:121], v[238:239], v[190:191]
	v_pk_fma_f32 v[122:123], v[122:123], v[240:241], v[192:193]
	v_pk_fma_f32 v[116:117], v[116:117], v[242:243], v[194:195]
	v_pk_fma_f32 v[118:119], v[118:119], v[244:245], v[196:197]
	v_cvt_pk_bf16_f32 v128, v128, v129
	v_cvt_pk_bf16_f32 v124, v124, v125
	v_cvt_pk_bf16_f32 v120, v120, v121
	v_cvt_pk_bf16_f32 v116, v116, v117
	s_nop 0
	v_cvt_pk_bf16_f32 v129, v130, v131
	v_cvt_pk_bf16_f32 v125, v126, v127
	v_cvt_pk_bf16_f32 v121, v122, v123
	v_cvt_pk_bf16_f32 v117, v118, v119
	global_store_dwordx2 v[224:225], v[128:129], off
	global_store_dwordx2 v[224:225], v[124:125], off offset:32
	global_store_dwordx2 v[224:225], v[120:121], off offset:256
	global_store_dwordx2 v[224:225], v[116:117], off offset:288
	v_lshl_add_u64 v[224:225], v[224:225], 0, v[218:219]
	global_load_dwordx4 v[182:185], v[222:223], off
	global_load_dwordx4 v[186:189], v[222:223], off offset:64
	global_load_dwordx4 v[190:193], v[222:223], off offset:512
	global_load_dwordx4 v[194:197], v[222:223], off offset:576
	v_lshl_add_u64 v[222:223], v[222:223], 0, v[214:215]
	s_waitcnt vmcnt(8)
	v_pk_mul_f32 v[198:199], v[198:199], s[14:15] op_sel_hi:[1,0]
	v_pk_mul_f32 v[200:201], v[200:201], s[14:15] op_sel_hi:[1,0]
	v_pk_mul_f32 v[202:203], v[202:203], s[14:15] op_sel_hi:[1,0]
	v_pk_mul_f32 v[204:205], v[204:205], s[14:15] op_sel_hi:[1,0]
	v_pk_mul_f32 v[206:207], v[206:207], s[14:15] op_sel_hi:[1,0]
	v_pk_mul_f32 v[208:209], v[208:209], s[14:15] op_sel_hi:[1,0]
	v_pk_mul_f32 v[210:211], v[210:211], s[14:15] op_sel_hi:[1,0]
	v_pk_mul_f32 v[212:213], v[212:213], s[14:15] op_sel_hi:[1,0]
	v_pk_fma_f32 v[112:113], v[112:113], v[230:231], v[198:199]
	v_pk_fma_f32 v[114:115], v[114:115], v[232:233], v[200:201]
	v_pk_fma_f32 v[108:109], v[108:109], v[234:235], v[202:203]
	v_pk_fma_f32 v[110:111], v[110:111], v[236:237], v[204:205]
	v_pk_fma_f32 v[104:105], v[104:105], v[238:239], v[206:207]
	v_pk_fma_f32 v[106:107], v[106:107], v[240:241], v[208:209]
	v_pk_fma_f32 v[100:101], v[100:101], v[242:243], v[210:211]
	v_pk_fma_f32 v[102:103], v[102:103], v[244:245], v[212:213]
	v_cvt_pk_bf16_f32 v112, v112, v113
	v_cvt_pk_bf16_f32 v108, v108, v109
	v_cvt_pk_bf16_f32 v104, v104, v105
	v_cvt_pk_bf16_f32 v100, v100, v101
	s_nop 0
	v_cvt_pk_bf16_f32 v113, v114, v115
	v_cvt_pk_bf16_f32 v109, v110, v111
	v_cvt_pk_bf16_f32 v105, v106, v107
	v_cvt_pk_bf16_f32 v101, v102, v103
	global_store_dwordx2 v[224:225], v[112:113], off
	global_store_dwordx2 v[224:225], v[108:109], off offset:32
	global_store_dwordx2 v[224:225], v[104:105], off offset:256
	global_store_dwordx2 v[224:225], v[100:101], off offset:288
	v_lshl_add_u64 v[224:225], v[224:225], 0, v[218:219]
	global_load_dwordx4 v[198:201], v[222:223], off
	global_load_dwordx4 v[202:205], v[222:223], off offset:64
	global_load_dwordx4 v[206:209], v[222:223], off offset:512
	global_load_dwordx4 v[210:213], v[222:223], off offset:576
	v_lshl_add_u64 v[222:223], v[222:223], 0, v[216:217]
	s_waitcnt vmcnt(8)
	v_pk_mul_f32 v[182:183], v[182:183], s[14:15] op_sel_hi:[1,0]
	v_pk_mul_f32 v[184:185], v[184:185], s[14:15] op_sel_hi:[1,0]
	v_pk_mul_f32 v[186:187], v[186:187], s[14:15] op_sel_hi:[1,0]
	v_pk_mul_f32 v[188:189], v[188:189], s[14:15] op_sel_hi:[1,0]
	v_pk_mul_f32 v[190:191], v[190:191], s[14:15] op_sel_hi:[1,0]
	v_pk_mul_f32 v[192:193], v[192:193], s[14:15] op_sel_hi:[1,0]
	v_pk_mul_f32 v[194:195], v[194:195], s[14:15] op_sel_hi:[1,0]
	v_pk_mul_f32 v[196:197], v[196:197], s[14:15] op_sel_hi:[1,0]
	v_pk_fma_f32 v[96:97], v[96:97], v[230:231], v[182:183]
	v_pk_fma_f32 v[98:99], v[98:99], v[232:233], v[184:185]
	v_pk_fma_f32 v[92:93], v[92:93], v[234:235], v[186:187]
	v_pk_fma_f32 v[94:95], v[94:95], v[236:237], v[188:189]
	v_pk_fma_f32 v[88:89], v[88:89], v[238:239], v[190:191]
	v_pk_fma_f32 v[90:91], v[90:91], v[240:241], v[192:193]
	v_pk_fma_f32 v[84:85], v[84:85], v[242:243], v[194:195]
	v_pk_fma_f32 v[86:87], v[86:87], v[244:245], v[196:197]
	v_cvt_pk_bf16_f32 v96, v96, v97
	v_cvt_pk_bf16_f32 v92, v92, v93
	v_cvt_pk_bf16_f32 v88, v88, v89
	v_cvt_pk_bf16_f32 v84, v84, v85
	s_nop 0
	v_cvt_pk_bf16_f32 v97, v98, v99
	v_cvt_pk_bf16_f32 v93, v94, v95
	v_cvt_pk_bf16_f32 v89, v90, v91
	v_cvt_pk_bf16_f32 v85, v86, v87
	global_store_dwordx2 v[224:225], v[96:97], off
	global_store_dwordx2 v[224:225], v[92:93], off offset:32
	global_store_dwordx2 v[224:225], v[88:89], off offset:256
	global_store_dwordx2 v[224:225], v[84:85], off offset:288
	v_lshl_add_u64 v[224:225], v[224:225], 0, v[218:219]
	global_load_dwordx4 v[182:185], v[222:223], off
	global_load_dwordx4 v[186:189], v[222:223], off offset:64
	global_load_dwordx4 v[190:193], v[222:223], off offset:512
	global_load_dwordx4 v[194:197], v[222:223], off offset:576
	v_lshl_add_u64 v[222:223], v[222:223], 0, v[214:215]
	s_waitcnt vmcnt(8)
	v_pk_mul_f32 v[198:199], v[198:199], s[14:15] op_sel_hi:[1,0]
	v_pk_mul_f32 v[200:201], v[200:201], s[14:15] op_sel_hi:[1,0]
	v_pk_mul_f32 v[202:203], v[202:203], s[14:15] op_sel_hi:[1,0]
	v_pk_mul_f32 v[204:205], v[204:205], s[14:15] op_sel_hi:[1,0]
	v_pk_mul_f32 v[206:207], v[206:207], s[14:15] op_sel_hi:[1,0]
	v_pk_mul_f32 v[208:209], v[208:209], s[14:15] op_sel_hi:[1,0]
	v_pk_mul_f32 v[210:211], v[210:211], s[14:15] op_sel_hi:[1,0]
	v_pk_mul_f32 v[212:213], v[212:213], s[14:15] op_sel_hi:[1,0]
	v_pk_fma_f32 v[80:81], v[80:81], v[230:231], v[198:199]
	v_pk_fma_f32 v[82:83], v[82:83], v[232:233], v[200:201]
	v_pk_fma_f32 v[76:77], v[76:77], v[234:235], v[202:203]
	v_pk_fma_f32 v[78:79], v[78:79], v[236:237], v[204:205]
	v_pk_fma_f32 v[72:73], v[72:73], v[238:239], v[206:207]
	v_pk_fma_f32 v[74:75], v[74:75], v[240:241], v[208:209]
	v_pk_fma_f32 v[68:69], v[68:69], v[242:243], v[210:211]
	v_pk_fma_f32 v[70:71], v[70:71], v[244:245], v[212:213]
	v_cvt_pk_bf16_f32 v80, v80, v81
	v_cvt_pk_bf16_f32 v76, v76, v77
	v_cvt_pk_bf16_f32 v72, v72, v73
	v_cvt_pk_bf16_f32 v68, v68, v69
	s_nop 0
	v_cvt_pk_bf16_f32 v81, v82, v83
	v_cvt_pk_bf16_f32 v77, v78, v79
	v_cvt_pk_bf16_f32 v73, v74, v75
	v_cvt_pk_bf16_f32 v69, v70, v71
	global_store_dwordx2 v[224:225], v[80:81], off
	global_store_dwordx2 v[224:225], v[76:77], off offset:32
	global_store_dwordx2 v[224:225], v[72:73], off offset:256
	global_store_dwordx2 v[224:225], v[68:69], off offset:288
	v_lshl_add_u64 v[224:225], v[224:225], 0, v[220:221]
	global_load_dwordx4 v[198:201], v[222:223], off
	global_load_dwordx4 v[202:205], v[222:223], off offset:64
	global_load_dwordx4 v[206:209], v[222:223], off offset:512
	global_load_dwordx4 v[210:213], v[222:223], off offset:576
	v_lshl_add_u64 v[222:223], v[222:223], 0, v[214:215]
	s_waitcnt vmcnt(8)
	v_pk_mul_f32 v[182:183], v[182:183], s[14:15] op_sel_hi:[1,0]
	v_pk_mul_f32 v[184:185], v[184:185], s[14:15] op_sel_hi:[1,0]
	v_pk_mul_f32 v[186:187], v[186:187], s[14:15] op_sel_hi:[1,0]
	v_pk_mul_f32 v[188:189], v[188:189], s[14:15] op_sel_hi:[1,0]
	v_pk_mul_f32 v[190:191], v[190:191], s[14:15] op_sel_hi:[1,0]
	v_pk_mul_f32 v[192:193], v[192:193], s[14:15] op_sel_hi:[1,0]
	v_pk_mul_f32 v[194:195], v[194:195], s[14:15] op_sel_hi:[1,0]
	v_pk_mul_f32 v[196:197], v[196:197], s[14:15] op_sel_hi:[1,0]
	v_pk_fma_f32 v[64:65], v[64:65], v[230:231], v[182:183]
	v_pk_fma_f32 v[66:67], v[66:67], v[232:233], v[184:185]
	v_pk_fma_f32 v[60:61], v[60:61], v[234:235], v[186:187]
	v_pk_fma_f32 v[62:63], v[62:63], v[236:237], v[188:189]
	v_pk_fma_f32 v[56:57], v[56:57], v[238:239], v[190:191]
	v_pk_fma_f32 v[58:59], v[58:59], v[240:241], v[192:193]
	v_pk_fma_f32 v[52:53], v[52:53], v[242:243], v[194:195]
	v_pk_fma_f32 v[54:55], v[54:55], v[244:245], v[196:197]
	v_cvt_pk_bf16_f32 v64, v64, v65
	v_cvt_pk_bf16_f32 v60, v60, v61
	v_cvt_pk_bf16_f32 v56, v56, v57
	v_cvt_pk_bf16_f32 v52, v52, v53
	s_nop 0
	v_cvt_pk_bf16_f32 v65, v66, v67
	v_cvt_pk_bf16_f32 v61, v62, v63
	v_cvt_pk_bf16_f32 v57, v58, v59
	v_cvt_pk_bf16_f32 v53, v54, v55
	global_store_dwordx2 v[224:225], v[64:65], off
	global_store_dwordx2 v[224:225], v[60:61], off offset:32
	global_store_dwordx2 v[224:225], v[56:57], off offset:256
	global_store_dwordx2 v[224:225], v[52:53], off offset:288
	v_lshl_add_u64 v[224:225], v[224:225], 0, v[218:219]
	global_load_dwordx4 v[182:185], v[222:223], off
	global_load_dwordx4 v[186:189], v[222:223], off offset:64
	global_load_dwordx4 v[190:193], v[222:223], off offset:512
	global_load_dwordx4 v[194:197], v[222:223], off offset:576
	v_lshl_add_u64 v[222:223], v[222:223], 0, v[214:215]
	s_waitcnt vmcnt(8)
	v_pk_mul_f32 v[198:199], v[198:199], s[14:15] op_sel_hi:[1,0]
	v_pk_mul_f32 v[200:201], v[200:201], s[14:15] op_sel_hi:[1,0]
	v_pk_mul_f32 v[202:203], v[202:203], s[14:15] op_sel_hi:[1,0]
	v_pk_mul_f32 v[204:205], v[204:205], s[14:15] op_sel_hi:[1,0]
	v_pk_mul_f32 v[206:207], v[206:207], s[14:15] op_sel_hi:[1,0]
	v_pk_mul_f32 v[208:209], v[208:209], s[14:15] op_sel_hi:[1,0]
	v_pk_mul_f32 v[210:211], v[210:211], s[14:15] op_sel_hi:[1,0]
	v_pk_mul_f32 v[212:213], v[212:213], s[14:15] op_sel_hi:[1,0]
	v_pk_fma_f32 v[48:49], v[48:49], v[230:231], v[198:199]
	v_pk_fma_f32 v[50:51], v[50:51], v[232:233], v[200:201]
	v_pk_fma_f32 v[44:45], v[44:45], v[234:235], v[202:203]
	v_pk_fma_f32 v[46:47], v[46:47], v[236:237], v[204:205]
	v_pk_fma_f32 v[40:41], v[40:41], v[238:239], v[206:207]
	v_pk_fma_f32 v[42:43], v[42:43], v[240:241], v[208:209]
	v_pk_fma_f32 v[36:37], v[36:37], v[242:243], v[210:211]
	v_pk_fma_f32 v[38:39], v[38:39], v[244:245], v[212:213]
	v_cvt_pk_bf16_f32 v48, v48, v49
	v_cvt_pk_bf16_f32 v44, v44, v45
	v_cvt_pk_bf16_f32 v40, v40, v41
	v_cvt_pk_bf16_f32 v36, v36, v37
	s_nop 0
	v_cvt_pk_bf16_f32 v49, v50, v51
	v_cvt_pk_bf16_f32 v45, v46, v47
	v_cvt_pk_bf16_f32 v41, v42, v43
	v_cvt_pk_bf16_f32 v37, v38, v39
	global_store_dwordx2 v[224:225], v[48:49], off
	global_store_dwordx2 v[224:225], v[44:45], off offset:32
	global_store_dwordx2 v[224:225], v[40:41], off offset:256
	global_store_dwordx2 v[224:225], v[36:37], off offset:288
	v_lshl_add_u64 v[224:225], v[224:225], 0, v[218:219]
	global_load_dwordx4 v[198:201], v[222:223], off
	global_load_dwordx4 v[202:205], v[222:223], off offset:64
	global_load_dwordx4 v[206:209], v[222:223], off offset:512
	global_load_dwordx4 v[210:213], v[222:223], off offset:576
	v_lshl_add_u64 v[222:223], v[222:223], 0, v[216:217]
	s_waitcnt vmcnt(8)
	v_pk_mul_f32 v[182:183], v[182:183], s[14:15] op_sel_hi:[1,0]
	v_pk_mul_f32 v[184:185], v[184:185], s[14:15] op_sel_hi:[1,0]
	v_pk_mul_f32 v[186:187], v[186:187], s[14:15] op_sel_hi:[1,0]
	v_pk_mul_f32 v[188:189], v[188:189], s[14:15] op_sel_hi:[1,0]
	v_pk_mul_f32 v[190:191], v[190:191], s[14:15] op_sel_hi:[1,0]
	v_pk_mul_f32 v[192:193], v[192:193], s[14:15] op_sel_hi:[1,0]
	v_pk_mul_f32 v[194:195], v[194:195], s[14:15] op_sel_hi:[1,0]
	v_pk_mul_f32 v[196:197], v[196:197], s[14:15] op_sel_hi:[1,0]
	v_pk_fma_f32 v[30:31], v[30:31], v[230:231], v[182:183]
	v_pk_fma_f32 v[32:33], v[32:33], v[232:233], v[184:185]
	v_pk_fma_f32 v[26:27], v[26:27], v[234:235], v[186:187]
	v_pk_fma_f32 v[28:29], v[28:29], v[236:237], v[188:189]
	v_pk_fma_f32 v[22:23], v[22:23], v[238:239], v[190:191]
	v_pk_fma_f32 v[24:25], v[24:25], v[240:241], v[192:193]
	v_pk_fma_f32 v[18:19], v[18:19], v[242:243], v[194:195]
	v_pk_fma_f32 v[20:21], v[20:21], v[244:245], v[196:197]
	v_cvt_pk_bf16_f32 v30, v30, v31
	v_cvt_pk_bf16_f32 v26, v26, v27
	v_cvt_pk_bf16_f32 v22, v22, v23
	v_cvt_pk_bf16_f32 v18, v18, v19
	s_nop 0
	v_cvt_pk_bf16_f32 v31, v32, v33
	v_cvt_pk_bf16_f32 v27, v28, v29
	v_cvt_pk_bf16_f32 v23, v24, v25
	v_cvt_pk_bf16_f32 v19, v20, v21
	global_store_dwordx2 v[224:225], v[30:31], off
	global_store_dwordx2 v[224:225], v[26:27], off offset:32
	global_store_dwordx2 v[224:225], v[22:23], off offset:256
	global_store_dwordx2 v[224:225], v[18:19], off offset:288
	v_lshl_add_u64 v[224:225], v[224:225], 0, v[218:219]
	s_waitcnt vmcnt(4)
	v_pk_mul_f32 v[198:199], v[198:199], s[14:15] op_sel_hi:[1,0]
	v_pk_mul_f32 v[200:201], v[200:201], s[14:15] op_sel_hi:[1,0]
	v_pk_mul_f32 v[202:203], v[202:203], s[14:15] op_sel_hi:[1,0]
	v_pk_mul_f32 v[204:205], v[204:205], s[14:15] op_sel_hi:[1,0]
	v_pk_mul_f32 v[206:207], v[206:207], s[14:15] op_sel_hi:[1,0]
	v_pk_mul_f32 v[208:209], v[208:209], s[14:15] op_sel_hi:[1,0]
	v_pk_mul_f32 v[210:211], v[210:211], s[14:15] op_sel_hi:[1,0]
	v_pk_mul_f32 v[212:213], v[212:213], s[14:15] op_sel_hi:[1,0]
	v_pk_fma_f32 v[14:15], v[14:15], v[230:231], v[198:199]
	v_pk_fma_f32 v[16:17], v[16:17], v[232:233], v[200:201]
	v_pk_fma_f32 v[10:11], v[10:11], v[234:235], v[202:203]
	v_pk_fma_f32 v[12:13], v[12:13], v[236:237], v[204:205]
	v_pk_fma_f32 v[6:7], v[6:7], v[238:239], v[206:207]
	v_pk_fma_f32 v[8:9], v[8:9], v[240:241], v[208:209]
	v_pk_fma_f32 v[2:3], v[2:3], v[242:243], v[210:211]
	v_pk_fma_f32 v[4:5], v[4:5], v[244:245], v[212:213]
	v_cvt_pk_bf16_f32 v14, v14, v15
	v_cvt_pk_bf16_f32 v10, v10, v11
	v_cvt_pk_bf16_f32 v6, v6, v7
	v_cvt_pk_bf16_f32 v2, v2, v3
	s_nop 0
	v_cvt_pk_bf16_f32 v15, v16, v17
	v_cvt_pk_bf16_f32 v11, v12, v13
	v_cvt_pk_bf16_f32 v7, v8, v9
	v_cvt_pk_bf16_f32 v3, v4, v5
	global_store_dwordx2 v[224:225], v[14:15], off
	global_store_dwordx2 v[224:225], v[10:11], off offset:32
	global_store_dwordx2 v[224:225], v[6:7], off offset:256
	global_store_dwordx2 v[224:225], v[2:3], off offset:288
	v_lshl_add_u64 v[224:225], v[224:225], 0, v[220:221]
	s_mov_b64 s[40:41], s[22:23]
	s_mov_b64 s[26:27], s[20:21]
	s_and_b64 vcc, exec, s[0:1]
	v_readlane_b32 s64, v254, 9
	v_readlane_b32 s65, v254, 10
	v_readlane_b32 s66, v254, 11
	v_readlane_b32 s67, v254, 12
	v_readlane_b32 s68, v254, 13
	v_readlane_b32 s69, v254, 14
	v_readlane_b32 s70, v254, 15
	v_readlane_b32 s71, v254, 16
	v_readlane_b32 s72, v254, 17
	v_readlane_b32 s73, v254, 18
	v_readlane_b32 s74, v254, 19
	v_readlane_b32 s75, v254, 20
	s_mov_b64 s[38:39], s[62:63]
	s_mov_b32 s25, s16
	s_mov_b32 s24, s18
	s_cbranch_vccz .LBB0_2158
	s_waitcnt vmcnt(0)
	s_cmpk_gt_u32 s5, 0xff
	s_cbranch_scc1 .LBB0_2169
	s_barrier

.LBB0_2602:
	ds_read_b128 v[144:147], v154
	ds_read_b128 v[148:151], v154 offset:1024
	ds_read_b128 v[158:161], v154 offset:2048
	ds_read_b128 v[162:165], v154 offset:3072
	s_add_u32 s22, s20, 0xffea0080
	s_addc_u32 s23, s21, -1
	s_cmpk_eq_i32 s31, 0x54
	s_cselect_b32 s25, s7, s23
	s_cselect_b32 s24, s6, s22
	s_cselect_b32 s23, s9, s29
	s_cselect_b32 s22, s8, s2
	v_lshl_add_u64 v[200:201], s[20:21], 0, v[136:137]
	s_add_i32 m0, s33, 0xc000
	ds_read_b128 v[168:171], v155
	ds_read_b128 v[172:175], v155 offset:1024
	ds_read_b128 v[176:179], v155 offset:2048
	ds_read_b128 v[180:183], v155 offset:3072
	ds_read_b128 v[184:187], v155 offset:4096
	ds_read_b128 v[188:191], v155 offset:5120
	ds_read_b128 v[192:195], v155 offset:6144
	ds_read_b128 v[196:199], v155 offset:7168
	global_load_lds_dwordx4 v[200:201], off
	v_lshl_add_u64 v[200:201], s[20:21], 0, v[138:139]
	s_add_i32 m0, s33, 0xe000
	s_nop 0
	global_load_lds_dwordx4 v[200:201], off
	s_waitcnt lgkmcnt(8)
	s_barrier
	s_waitcnt lgkmcnt(0)
	s_setprio 1
	s_waitcnt lgkmcnt(0)
	v_mfma_f32_16x16x32_bf16 v[128:131], v[144:147], v[168:171], v[128:131]
	v_mfma_f32_16x16x32_bf16 v[124:127], v[158:161], v[168:171], v[124:127]
	v_mfma_f32_16x16x32_bf16 v[112:115], v[144:147], v[176:179], v[112:115]
	v_mfma_f32_16x16x32_bf16 v[108:111], v[158:161], v[176:179], v[108:111]
	v_mfma_f32_16x16x32_bf16 v[96:99], v[144:147], v[184:187], v[96:99]
	v_mfma_f32_16x16x32_bf16 v[92:95], v[158:161], v[184:187], v[92:95]
	v_mfma_f32_16x16x32_bf16 v[80:83], v[144:147], v[192:195], v[80:83]
	v_mfma_f32_16x16x32_bf16 v[76:79], v[158:161], v[192:195], v[76:79]
	v_mfma_f32_16x16x32_bf16 v[128:131], v[148:151], v[172:175], v[128:131]
	v_mfma_f32_16x16x32_bf16 v[124:127], v[162:165], v[172:175], v[124:127]
	v_mfma_f32_16x16x32_bf16 v[112:115], v[148:151], v[180:183], v[112:115]
	v_mfma_f32_16x16x32_bf16 v[108:111], v[162:165], v[180:183], v[108:111]
	v_mfma_f32_16x16x32_bf16 v[96:99], v[148:151], v[188:191], v[96:99]
	v_mfma_f32_16x16x32_bf16 v[92:95], v[162:165], v[188:191], v[92:95]
	v_mfma_f32_16x16x32_bf16 v[80:83], v[148:151], v[196:199], v[80:83]
	v_mfma_f32_16x16x32_bf16 v[76:79], v[162:165], v[196:199], v[76:79]
	s_setprio 0
	s_barrier
	s_add_i32 s51, s45, s30
	v_lshl_add_u64 v[216:217], s[22:23], 0, v[132:133]
	s_mov_b32 m0, s51
	ds_read_b128 v[200:203], v157
	ds_read_b128 v[204:207], v157 offset:1024
	ds_read_b128 v[208:211], v157 offset:2048
	ds_read_b128 v[212:215], v157 offset:3072
	global_load_lds_dwordx4 v[216:217], off
	v_lshl_add_u64 v[218:219], s[22:23], 0, v[134:135]
	s_add_i32 m0, s51, 0x2000
	s_nop 0
	global_load_lds_dwordx4 v[218:219], off
	s_barrier
	s_waitcnt lgkmcnt(0)
	s_setprio 1
	s_waitcnt lgkmcnt(0)
	v_mfma_f32_16x16x32_bf16 v[120:123], v[200:203], v[168:171], v[120:123]
	v_mfma_f32_16x16x32_bf16 v[116:119], v[208:211], v[168:171], v[116:119]
	v_mfma_f32_16x16x32_bf16 v[104:107], v[200:203], v[176:179], v[104:107]
	v_mfma_f32_16x16x32_bf16 v[100:103], v[208:211], v[176:179], v[100:103]
	v_mfma_f32_16x16x32_bf16 v[88:91], v[200:203], v[184:187], v[88:91]
	v_mfma_f32_16x16x32_bf16 v[84:87], v[208:211], v[184:187], v[84:87]
	v_mfma_f32_16x16x32_bf16 v[72:75], v[200:203], v[192:195], v[72:75]
	v_mfma_f32_16x16x32_bf16 v[68:71], v[208:211], v[192:195], v[68:71]
	v_mfma_f32_16x16x32_bf16 v[120:123], v[204:207], v[172:175], v[120:123]
	v_mfma_f32_16x16x32_bf16 v[116:119], v[212:215], v[172:175], v[116:119]
	v_mfma_f32_16x16x32_bf16 v[104:107], v[204:207], v[180:183], v[104:107]
	v_mfma_f32_16x16x32_bf16 v[100:103], v[212:215], v[180:183], v[100:103]
	v_mfma_f32_16x16x32_bf16 v[88:91], v[204:207], v[188:191], v[88:91]
	v_mfma_f32_16x16x32_bf16 v[84:87], v[212:215], v[188:191], v[84:87]
	v_mfma_f32_16x16x32_bf16 v[72:75], v[204:207], v[196:199], v[72:75]
	v_mfma_f32_16x16x32_bf16 v[68:71], v[212:215], v[196:199], v[68:71]
	s_setprio 0
	s_mov_b32 m0, s33
	v_lshl_add_u64 v[220:221], s[24:25], 0, v[132:133]
	s_barrier
	ds_read_b128 v[168:171], v155 offset:16384
	ds_read_b128 v[172:175], v155 offset:17408
	ds_read_b128 v[176:179], v155 offset:18432
	ds_read_b128 v[180:183], v155 offset:19456
	ds_read_b128 v[184:187], v155 offset:20480
	ds_read_b128 v[188:191], v155 offset:21504
	ds_read_b128 v[192:195], v155 offset:22528
	ds_read_b128 v[196:199], v155 offset:23552
	global_load_lds_dwordx4 v[220:221], off
	v_lshl_add_u64 v[222:223], s[24:25], 0, v[134:135]
	s_mov_b32 m0, s36
	s_nop 0
	global_load_lds_dwordx4 v[222:223], off
	s_barrier
	s_waitcnt lgkmcnt(0)
	s_setprio 1
	s_waitcnt lgkmcnt(0)
	v_mfma_f32_16x16x32_bf16 v[64:67], v[144:147], v[168:171], v[64:67]
	v_mfma_f32_16x16x32_bf16 v[60:63], v[158:161], v[168:171], v[60:63]
	v_mfma_f32_16x16x32_bf16 v[48:51], v[144:147], v[176:179], v[48:51]
	v_mfma_f32_16x16x32_bf16 v[44:47], v[158:161], v[176:179], v[44:47]
	v_mfma_f32_16x16x32_bf16 v[30:33], v[144:147], v[184:187], v[30:33]
	v_mfma_f32_16x16x32_bf16 v[26:29], v[158:161], v[184:187], v[26:29]
	v_mfma_f32_16x16x32_bf16 v[14:17], v[144:147], v[192:195], v[14:17]
	v_mfma_f32_16x16x32_bf16 v[10:13], v[158:161], v[192:195], v[10:13]
	v_mfma_f32_16x16x32_bf16 v[64:67], v[148:151], v[172:175], v[64:67]
	v_mfma_f32_16x16x32_bf16 v[60:63], v[162:165], v[172:175], v[60:63]
	v_mfma_f32_16x16x32_bf16 v[48:51], v[148:151], v[180:183], v[48:51]
	v_mfma_f32_16x16x32_bf16 v[44:47], v[162:165], v[180:183], v[44:47]
	v_mfma_f32_16x16x32_bf16 v[30:33], v[148:151], v[188:191], v[30:33]
	v_mfma_f32_16x16x32_bf16 v[26:29], v[162:165], v[188:191], v[26:29]
	v_mfma_f32_16x16x32_bf16 v[14:17], v[148:151], v[196:199], v[14:17]
	v_mfma_f32_16x16x32_bf16 v[10:13], v[162:165], v[196:199], v[10:13]
	s_setprio 0
	s_barrier
	s_add_u32 s52, s22, 0x160000
	s_addc_u32 s53, s23, 0
	s_add_i32 s51, s46, s30
	v_lshl_add_u64 v[144:145], s[52:53], 0, v[132:133]
	s_mov_b32 m0, s51
	s_nop 0
	global_load_lds_dwordx4 v[144:145], off
	v_lshl_add_u64 v[144:145], s[52:53], 0, v[134:135]
	s_add_i32 m0, s51, 0x2000
	s_nop 0
	global_load_lds_dwordx4 v[144:145], off
	s_waitcnt vmcnt(6)
	s_barrier
	s_setprio 1
	v_mfma_f32_16x16x32_bf16 v[56:59], v[200:203], v[168:171], v[56:59]
	v_mfma_f32_16x16x32_bf16 v[52:55], v[208:211], v[168:171], v[52:55]
	v_mfma_f32_16x16x32_bf16 v[40:43], v[200:203], v[176:179], v[40:43]
	v_mfma_f32_16x16x32_bf16 v[36:39], v[208:211], v[176:179], v[36:39]
	v_mfma_f32_16x16x32_bf16 v[22:25], v[200:203], v[184:187], v[22:25]
	v_mfma_f32_16x16x32_bf16 v[18:21], v[208:211], v[184:187], v[18:21]
	v_mfma_f32_16x16x32_bf16 v[6:9], v[200:203], v[192:195], v[6:9]
	v_mfma_f32_16x16x32_bf16 v[2:5], v[208:211], v[192:195], v[2:5]
	v_mfma_f32_16x16x32_bf16 v[56:59], v[204:207], v[172:175], v[56:59]
	v_mfma_f32_16x16x32_bf16 v[52:55], v[212:215], v[172:175], v[52:55]
	v_mfma_f32_16x16x32_bf16 v[40:43], v[204:207], v[180:183], v[40:43]
	v_mfma_f32_16x16x32_bf16 v[36:39], v[212:215], v[180:183], v[36:39]
	v_mfma_f32_16x16x32_bf16 v[22:25], v[204:207], v[188:191], v[22:25]
	v_mfma_f32_16x16x32_bf16 v[18:21], v[212:215], v[188:191], v[18:21]
	v_mfma_f32_16x16x32_bf16 v[6:9], v[204:207], v[196:199], v[6:9]
	v_mfma_f32_16x16x32_bf16 v[2:5], v[212:215], v[196:199], v[2:5]
	s_setprio 0
	s_add_i32 s51, 0, 0x18000
	v_add_u32_e32 v162, s51, v152
	s_barrier
	ds_read_b128 v[144:147], v162
	ds_read_b128 v[148:151], v162 offset:1024
	ds_read_b128 v[158:161], v162 offset:2048
	ds_read_b128 v[162:165], v162 offset:3072
	s_add_u32 s24, s24, 0x160000
	s_addc_u32 s25, s25, 0
	s_mov_b32 m0, s37
	v_lshl_add_u64 v[200:201], s[24:25], 0, v[132:133]
	ds_read_b128 v[168:171], v155 offset:32768
	ds_read_b128 v[172:175], v155 offset:33792
	ds_read_b128 v[176:179], v155 offset:34816
	ds_read_b128 v[180:183], v155 offset:35840
	ds_read_b128 v[184:187], v155 offset:36864
	ds_read_b128 v[188:191], v155 offset:37888
	ds_read_b128 v[192:195], v155 offset:38912
	ds_read_b128 v[196:199], v155 offset:39936
	global_load_lds_dwordx4 v[200:201], off
	v_lshl_add_u64 v[200:201], s[24:25], 0, v[134:135]
	s_mov_b32 m0, s38
	s_nop 0
	global_load_lds_dwordx4 v[200:201], off
	s_waitcnt lgkmcnt(8)
	s_barrier
	s_waitcnt lgkmcnt(0)
	s_setprio 1
	s_waitcnt lgkmcnt(0)
	v_mfma_f32_16x16x32_bf16 v[128:131], v[144:147], v[168:171], v[128:131]
	v_mfma_f32_16x16x32_bf16 v[124:127], v[158:161], v[168:171], v[124:127]
	v_mfma_f32_16x16x32_bf16 v[112:115], v[144:147], v[176:179], v[112:115]
	v_mfma_f32_16x16x32_bf16 v[108:111], v[158:161], v[176:179], v[108:111]
	v_mfma_f32_16x16x32_bf16 v[96:99], v[144:147], v[184:187], v[96:99]
	v_mfma_f32_16x16x32_bf16 v[92:95], v[158:161], v[184:187], v[92:95]
	v_mfma_f32_16x16x32_bf16 v[80:83], v[144:147], v[192:195], v[80:83]
	v_mfma_f32_16x16x32_bf16 v[76:79], v[158:161], v[192:195], v[76:79]
	v_mfma_f32_16x16x32_bf16 v[128:131], v[148:151], v[172:175], v[128:131]
	v_mfma_f32_16x16x32_bf16 v[124:127], v[162:165], v[172:175], v[124:127]
	v_mfma_f32_16x16x32_bf16 v[112:115], v[148:151], v[180:183], v[112:115]
	v_mfma_f32_16x16x32_bf16 v[108:111], v[162:165], v[180:183], v[108:111]
	v_mfma_f32_16x16x32_bf16 v[96:99], v[148:151], v[188:191], v[96:99]
	v_mfma_f32_16x16x32_bf16 v[92:95], v[162:165], v[188:191], v[92:95]
	v_mfma_f32_16x16x32_bf16 v[80:83], v[148:151], v[196:199], v[80:83]
	v_mfma_f32_16x16x32_bf16 v[76:79], v[162:165], v[196:199], v[76:79]
	s_setprio 0
	s_barrier
	s_add_i32 s24, 0, 0x1c000
	s_add_i32 s25, s51, s30
	v_add_u32_e32 v212, s24, v152
	v_lshl_add_u64 v[216:217], v[216:217], 0, s[14:15]
	s_mov_b32 m0, s25
	ds_read_b128 v[200:203], v212
	ds_read_b128 v[204:207], v212 offset:1024
	ds_read_b128 v[208:211], v212 offset:2048
	ds_read_b128 v[212:215], v212 offset:3072
	global_load_lds_dwordx4 v[216:217], off
	v_lshl_add_u64 v[216:217], v[218:219], 0, s[14:15]
	s_add_i32 m0, s25, 0x2000
	s_nop 0
	global_load_lds_dwordx4 v[216:217], off
	s_barrier
	s_waitcnt lgkmcnt(0)
	s_setprio 1
	s_waitcnt lgkmcnt(0)
	v_mfma_f32_16x16x32_bf16 v[120:123], v[200:203], v[168:171], v[120:123]
	v_mfma_f32_16x16x32_bf16 v[116:119], v[208:211], v[168:171], v[116:119]
	v_mfma_f32_16x16x32_bf16 v[104:107], v[200:203], v[176:179], v[104:107]
	v_mfma_f32_16x16x32_bf16 v[100:103], v[208:211], v[176:179], v[100:103]
	v_mfma_f32_16x16x32_bf16 v[88:91], v[200:203], v[184:187], v[88:91]
	v_mfma_f32_16x16x32_bf16 v[84:87], v[208:211], v[184:187], v[84:87]
	v_mfma_f32_16x16x32_bf16 v[72:75], v[200:203], v[192:195], v[72:75]
	v_mfma_f32_16x16x32_bf16 v[68:71], v[208:211], v[192:195], v[68:71]
	v_mfma_f32_16x16x32_bf16 v[120:123], v[204:207], v[172:175], v[120:123]
	v_mfma_f32_16x16x32_bf16 v[116:119], v[212:215], v[172:175], v[116:119]
	v_mfma_f32_16x16x32_bf16 v[104:107], v[204:207], v[180:183], v[104:107]
	v_mfma_f32_16x16x32_bf16 v[100:103], v[212:215], v[180:183], v[100:103]
	v_mfma_f32_16x16x32_bf16 v[88:91], v[204:207], v[188:191], v[88:91]
	v_mfma_f32_16x16x32_bf16 v[84:87], v[212:215], v[188:191], v[84:87]
	v_mfma_f32_16x16x32_bf16 v[72:75], v[204:207], v[196:199], v[72:75]
	v_mfma_f32_16x16x32_bf16 v[68:71], v[212:215], v[196:199], v[68:71]
	s_setprio 0
	s_mov_b32 m0, s41
	v_lshl_add_u64 v[216:217], v[220:221], 0, s[14:15]
	s_barrier
	ds_read_b128 v[168:171], v155 offset:49152
	ds_read_b128 v[172:175], v155 offset:50176
	ds_read_b128 v[176:179], v155 offset:51200
	ds_read_b128 v[180:183], v155 offset:52224
	ds_read_b128 v[184:187], v155 offset:53248
	ds_read_b128 v[188:191], v155 offset:54272
	ds_read_b128 v[192:195], v155 offset:55296
	ds_read_b128 v[196:199], v155 offset:56320
	global_load_lds_dwordx4 v[216:217], off
	v_lshl_add_u64 v[216:217], v[222:223], 0, s[14:15]
	s_mov_b32 m0, s42
	s_nop 0
	global_load_lds_dwordx4 v[216:217], off
	s_barrier
	s_waitcnt lgkmcnt(0)
	s_setprio 1
	s_waitcnt lgkmcnt(0)
	v_mfma_f32_16x16x32_bf16 v[64:67], v[144:147], v[168:171], v[64:67]
	v_mfma_f32_16x16x32_bf16 v[60:63], v[158:161], v[168:171], v[60:63]
	v_mfma_f32_16x16x32_bf16 v[48:51], v[144:147], v[176:179], v[48:51]
	v_mfma_f32_16x16x32_bf16 v[44:47], v[158:161], v[176:179], v[44:47]
	v_mfma_f32_16x16x32_bf16 v[30:33], v[144:147], v[184:187], v[30:33]
	v_mfma_f32_16x16x32_bf16 v[26:29], v[158:161], v[184:187], v[26:29]
	v_mfma_f32_16x16x32_bf16 v[14:17], v[144:147], v[192:195], v[14:17]
	v_mfma_f32_16x16x32_bf16 v[10:13], v[158:161], v[192:195], v[10:13]
	v_mfma_f32_16x16x32_bf16 v[64:67], v[148:151], v[172:175], v[64:67]
	v_mfma_f32_16x16x32_bf16 v[60:63], v[162:165], v[172:175], v[60:63]
	v_mfma_f32_16x16x32_bf16 v[48:51], v[148:151], v[180:183], v[48:51]
	v_mfma_f32_16x16x32_bf16 v[44:47], v[162:165], v[180:183], v[44:47]
	v_mfma_f32_16x16x32_bf16 v[30:33], v[148:151], v[188:191], v[30:33]
	v_mfma_f32_16x16x32_bf16 v[26:29], v[162:165], v[188:191], v[26:29]
	v_mfma_f32_16x16x32_bf16 v[14:17], v[148:151], v[196:199], v[14:17]
	v_mfma_f32_16x16x32_bf16 v[10:13], v[162:165], v[196:199], v[10:13]
	s_setprio 0
	s_barrier
	s_add_u32 s22, s22, 0x160080
	s_addc_u32 s23, s23, 0
	s_add_i32 s24, s24, s30
	v_lshl_add_u64 v[144:145], s[22:23], 0, v[132:133]
	s_mov_b32 m0, s24
	s_nop 0
	global_load_lds_dwordx4 v[144:145], off
	v_lshl_add_u64 v[144:145], s[22:23], 0, v[134:135]
	s_add_i32 m0, s24, 0x2000
	s_nop 0
	global_load_lds_dwordx4 v[144:145], off
	s_waitcnt vmcnt(6)
	s_barrier
	s_setprio 1
	v_mfma_f32_16x16x32_bf16 v[56:59], v[200:203], v[168:171], v[56:59]
	v_mfma_f32_16x16x32_bf16 v[52:55], v[208:211], v[168:171], v[52:55]
	v_mfma_f32_16x16x32_bf16 v[40:43], v[200:203], v[176:179], v[40:43]
	v_mfma_f32_16x16x32_bf16 v[36:39], v[208:211], v[176:179], v[36:39]
	v_mfma_f32_16x16x32_bf16 v[22:25], v[200:203], v[184:187], v[22:25]
	v_mfma_f32_16x16x32_bf16 v[18:21], v[208:211], v[184:187], v[18:21]
	v_mfma_f32_16x16x32_bf16 v[6:9], v[200:203], v[192:195], v[6:9]
	v_mfma_f32_16x16x32_bf16 v[2:5], v[208:211], v[192:195], v[2:5]
	v_mfma_f32_16x16x32_bf16 v[56:59], v[204:207], v[172:175], v[56:59]
	v_mfma_f32_16x16x32_bf16 v[52:55], v[212:215], v[172:175], v[52:55]
	v_mfma_f32_16x16x32_bf16 v[40:43], v[204:207], v[180:183], v[40:43]
	v_mfma_f32_16x16x32_bf16 v[36:39], v[212:215], v[180:183], v[36:39]
	v_mfma_f32_16x16x32_bf16 v[22:25], v[204:207], v[188:191], v[22:25]
	v_mfma_f32_16x16x32_bf16 v[18:21], v[212:215], v[188:191], v[18:21]
	v_mfma_f32_16x16x32_bf16 v[6:9], v[204:207], v[196:199], v[6:9]
	v_mfma_f32_16x16x32_bf16 v[2:5], v[212:215], v[196:199], v[2:5]
	s_setprio 0
	s_add_i32 s31, s31, 2
	s_add_u32 s20, s20, 0x100
	s_addc_u32 s21, s21, 0
	s_add_u32 s2, s2, 0x100
	s_addc_u32 s29, s29, 0
	s_cmpk_gt_u32 s31, 0x55
	s_barrier
	s_cbranch_scc0 .LBB0_2602
	s_lshl_b32 s2, s49, 8
	s_add_i32 s2, s2, s40
	v_or_b32_e32 v146, s2, v166
	s_ashr_i32 s2, s2, 11
	v_lshl_or_b32 v162, s50, 8, v153
	s_mul_hi_i32 s20, s2, 0xc000
	s_mul_i32 s2, s2, 0xc000
	v_ashrrev_i32_e32 v147, 31, v146
	s_add_u32 s2, s10, s2
	v_ashrrev_i32_e32 v163, 31, v162
	v_lshlrev_b64 v[144:145], 12, v[146:147]
	v_lshl_add_u64 v[144:145], s[12:13], 0, v[144:145]
	v_lshlrev_b64 v[148:149], 1, v[162:163]
	s_addc_u32 s21, s11, s20
	v_lshl_add_u64 v[164:165], v[144:145], 0, v[148:149]
	s_add_u32 s20, s2, 0xa000
	global_load_dwordx2 v[168:169], v[164:165], off nt
	s_addc_u32 s21, s21, 0
	v_lshlrev_b64 v[144:145], 2, v[162:163]
	v_lshl_add_u64 v[150:151], s[20:21], 0, v[144:145]
	global_load_dwordx4 v[158:161], v[150:151], off
	v_lshlrev_b64 v[170:171], 13, v[146:147]
	v_lshl_add_u64 v[170:171], s[82:83], 0, v[170:171]
	v_lshl_add_u64 v[170:171], v[170:171], 0, v[144:145]
	s_mov_b32 s50, s47
	s_mov_b32 s49, s48
	s_mov_b64 s[22:23], s[8:9]
	s_and_b64 vcc, exec, s[0:1]
	v_mov_b32_e32 v206, v164
	v_mov_b32_e32 v207, v165
	v_mov_b32_e32 v208, v170
	v_mov_b32_e32 v209, v171
	v_lshl_add_u64 v[210:211], s[20:21], 0, v[144:145]
	global_load_dwordx4 v[224:227], v[210:211], off
	global_load_dwordx4 v[228:231], v[210:211], off offset:64
	global_load_dwordx4 v[232:235], v[210:211], off offset:512
	global_load_dwordx4 v[236:239], v[210:211], off offset:576
	v_mov_b32_e32 v198, 0x10000
	v_mov_b32_e32 v199, 0
	v_mov_b32_e32 v200, 0x50000
	v_mov_b32_e32 v201, 0
	v_mov_b32_e32 v202, 0x20000
	v_mov_b32_e32 v203, 0
	v_mov_b32_e32 v204, 0xa0000
	v_mov_b32_e32 v205, 0
	global_load_dwordx2 v[240:241], v[206:207], off nt
	global_load_dwordx2 v[242:243], v[206:207], off offset:32 nt
	global_load_dwordx2 v[244:245], v[206:207], off offset:256 nt
	global_load_dwordx2 v[246:247], v[206:207], off offset:288 nt
	v_lshl_add_u64 v[206:207], v[206:207], 0, v[198:199]
	global_load_dwordx2 v[174:175], v[206:207], off nt
	global_load_dwordx2 v[176:177], v[206:207], off offset:32 nt
	global_load_dwordx2 v[178:179], v[206:207], off offset:256 nt
	global_load_dwordx2 v[180:181], v[206:207], off offset:288 nt
	v_lshl_add_u64 v[206:207], v[206:207], 0, v[198:199]
	s_waitcnt vmcnt(4)
	v_lshlrev_b32_e32 v182, 16, v240
	v_and_b32_e32 v183, 0xffff0000, v240
	v_lshlrev_b32_e32 v184, 16, v241
	v_and_b32_e32 v185, 0xffff0000, v241
	v_lshlrev_b32_e32 v186, 16, v242
	v_and_b32_e32 v187, 0xffff0000, v242
	v_lshlrev_b32_e32 v188, 16, v243
	v_and_b32_e32 v189, 0xffff0000, v243
	v_lshlrev_b32_e32 v190, 16, v244
	v_and_b32_e32 v191, 0xffff0000, v244
	v_lshlrev_b32_e32 v192, 16, v245
	v_and_b32_e32 v193, 0xffff0000, v245
	v_lshlrev_b32_e32 v194, 16, v246
	v_and_b32_e32 v195, 0xffff0000, v246
	v_lshlrev_b32_e32 v196, 16, v247
	v_and_b32_e32 v197, 0xffff0000, v247
	v_pk_mul_f32 v[182:183], v[182:183], s[18:19] op_sel_hi:[1,0]
	v_pk_mul_f32 v[184:185], v[184:185], s[18:19] op_sel_hi:[1,0]
	v_pk_mul_f32 v[186:187], v[186:187], s[18:19] op_sel_hi:[1,0]
	v_pk_mul_f32 v[188:189], v[188:189], s[18:19] op_sel_hi:[1,0]
	v_pk_mul_f32 v[190:191], v[190:191], s[18:19] op_sel_hi:[1,0]
	v_pk_mul_f32 v[192:193], v[192:193], s[18:19] op_sel_hi:[1,0]
	v_pk_mul_f32 v[194:195], v[194:195], s[18:19] op_sel_hi:[1,0]
	v_pk_mul_f32 v[196:197], v[196:197], s[18:19] op_sel_hi:[1,0]
	v_pk_fma_f32 v[128:129], v[128:129], v[224:225], v[182:183]
	v_pk_fma_f32 v[130:131], v[130:131], v[226:227], v[184:185]
	v_pk_fma_f32 v[124:125], v[124:125], v[228:229], v[186:187]
	v_pk_fma_f32 v[126:127], v[126:127], v[230:231], v[188:189]
	v_pk_fma_f32 v[120:121], v[120:121], v[232:233], v[190:191]
	v_pk_fma_f32 v[122:123], v[122:123], v[234:235], v[192:193]
	v_pk_fma_f32 v[116:117], v[116:117], v[236:237], v[194:195]
	v_pk_fma_f32 v[118:119], v[118:119], v[238:239], v[196:197]
	s_nop 0
	global_store_dwordx4 v[208:209], v[128:131], off
	global_store_dwordx4 v[208:209], v[124:127], off offset:64
	global_store_dwordx4 v[208:209], v[120:123], off offset:512
	global_store_dwordx4 v[208:209], v[116:119], off offset:576
	v_lshl_add_u64 v[208:209], v[208:209], 0, v[202:203]
	global_load_dwordx2 v[240:241], v[206:207], off nt
	global_load_dwordx2 v[242:243], v[206:207], off offset:32 nt
	global_load_dwordx2 v[244:245], v[206:207], off offset:256 nt
	global_load_dwordx2 v[246:247], v[206:207], off offset:288 nt
	v_lshl_add_u64 v[206:207], v[206:207], 0, v[198:199]
	s_waitcnt vmcnt(8)
	v_lshlrev_b32_e32 v182, 16, v174
	v_and_b32_e32 v183, 0xffff0000, v174
	v_lshlrev_b32_e32 v184, 16, v175
	v_and_b32_e32 v185, 0xffff0000, v175
	v_lshlrev_b32_e32 v186, 16, v176
	v_and_b32_e32 v187, 0xffff0000, v176
	v_lshlrev_b32_e32 v188, 16, v177
	v_and_b32_e32 v189, 0xffff0000, v177
	v_lshlrev_b32_e32 v190, 16, v178
	v_and_b32_e32 v191, 0xffff0000, v178
	v_lshlrev_b32_e32 v192, 16, v179
	v_and_b32_e32 v193, 0xffff0000, v179
	v_lshlrev_b32_e32 v194, 16, v180
	v_and_b32_e32 v195, 0xffff0000, v180
	v_lshlrev_b32_e32 v196, 16, v181
	v_and_b32_e32 v197, 0xffff0000, v181
	v_pk_mul_f32 v[182:183], v[182:183], s[18:19] op_sel_hi:[1,0]
	v_pk_mul_f32 v[184:185], v[184:185], s[18:19] op_sel_hi:[1,0]
	v_pk_mul_f32 v[186:187], v[186:187], s[18:19] op_sel_hi:[1,0]
	v_pk_mul_f32 v[188:189], v[188:189], s[18:19] op_sel_hi:[1,0]
	v_pk_mul_f32 v[190:191], v[190:191], s[18:19] op_sel_hi:[1,0]
	v_pk_mul_f32 v[192:193], v[192:193], s[18:19] op_sel_hi:[1,0]
	v_pk_mul_f32 v[194:195], v[194:195], s[18:19] op_sel_hi:[1,0]
	v_pk_mul_f32 v[196:197], v[196:197], s[18:19] op_sel_hi:[1,0]
	v_pk_fma_f32 v[112:113], v[112:113], v[224:225], v[182:183]
	v_pk_fma_f32 v[114:115], v[114:115], v[226:227], v[184:185]
	v_pk_fma_f32 v[108:109], v[108:109], v[228:229], v[186:187]
	v_pk_fma_f32 v[110:111], v[110:111], v[230:231], v[188:189]
	v_pk_fma_f32 v[104:105], v[104:105], v[232:233], v[190:191]
	v_pk_fma_f32 v[106:107], v[106:107], v[234:235], v[192:193]
	v_pk_fma_f32 v[100:101], v[100:101], v[236:237], v[194:195]
	v_pk_fma_f32 v[102:103], v[102:103], v[238:239], v[196:197]
	s_nop 0
	global_store_dwordx4 v[208:209], v[112:115], off
	global_store_dwordx4 v[208:209], v[108:111], off offset:64
	global_store_dwordx4 v[208:209], v[104:107], off offset:512
	global_store_dwordx4 v[208:209], v[100:103], off offset:576
	v_lshl_add_u64 v[208:209], v[208:209], 0, v[202:203]
	global_load_dwordx2 v[174:175], v[206:207], off nt
	global_load_dwordx2 v[176:177], v[206:207], off offset:32 nt
	global_load_dwordx2 v[178:179], v[206:207], off offset:256 nt
	global_load_dwordx2 v[180:181], v[206:207], off offset:288 nt
	v_lshl_add_u64 v[206:207], v[206:207], 0, v[200:201]
	s_waitcnt vmcnt(8)
	v_lshlrev_b32_e32 v182, 16, v240
	v_and_b32_e32 v183, 0xffff0000, v240
	v_lshlrev_b32_e32 v184, 16, v241
	v_and_b32_e32 v185, 0xffff0000, v241
	v_lshlrev_b32_e32 v186, 16, v242
	v_and_b32_e32 v187, 0xffff0000, v242
	v_lshlrev_b32_e32 v188, 16, v243
	v_and_b32_e32 v189, 0xffff0000, v243
	v_lshlrev_b32_e32 v190, 16, v244
	v_and_b32_e32 v191, 0xffff0000, v244
	v_lshlrev_b32_e32 v192, 16, v245
	v_and_b32_e32 v193, 0xffff0000, v245
	v_lshlrev_b32_e32 v194, 16, v246
	v_and_b32_e32 v195, 0xffff0000, v246
	v_lshlrev_b32_e32 v196, 16, v247
	v_and_b32_e32 v197, 0xffff0000, v247
	v_pk_mul_f32 v[182:183], v[182:183], s[18:19] op_sel_hi:[1,0]
	v_pk_mul_f32 v[184:185], v[184:185], s[18:19] op_sel_hi:[1,0]
	v_pk_mul_f32 v[186:187], v[186:187], s[18:19] op_sel_hi:[1,0]
	v_pk_mul_f32 v[188:189], v[188:189], s[18:19] op_sel_hi:[1,0]
	v_pk_mul_f32 v[190:191], v[190:191], s[18:19] op_sel_hi:[1,0]
	v_pk_mul_f32 v[192:193], v[192:193], s[18:19] op_sel_hi:[1,0]
	v_pk_mul_f32 v[194:195], v[194:195], s[18:19] op_sel_hi:[1,0]
	v_pk_mul_f32 v[196:197], v[196:197], s[18:19] op_sel_hi:[1,0]
	v_pk_fma_f32 v[96:97], v[96:97], v[224:225], v[182:183]
	v_pk_fma_f32 v[98:99], v[98:99], v[226:227], v[184:185]
	v_pk_fma_f32 v[92:93], v[92:93], v[228:229], v[186:187]
	v_pk_fma_f32 v[94:95], v[94:95], v[230:231], v[188:189]
	v_pk_fma_f32 v[88:89], v[88:89], v[232:233], v[190:191]
	v_pk_fma_f32 v[90:91], v[90:91], v[234:235], v[192:193]
	v_pk_fma_f32 v[84:85], v[84:85], v[236:237], v[194:195]
	v_pk_fma_f32 v[86:87], v[86:87], v[238:239], v[196:197]
	s_nop 0
	global_store_dwordx4 v[208:209], v[96:99], off
	global_store_dwordx4 v[208:209], v[92:95], off offset:64
	global_store_dwordx4 v[208:209], v[88:91], off offset:512
	global_store_dwordx4 v[208:209], v[84:87], off offset:576
	v_lshl_add_u64 v[208:209], v[208:209], 0, v[202:203]
	global_load_dwordx2 v[240:241], v[206:207], off nt
	global_load_dwordx2 v[242:243], v[206:207], off offset:32 nt
	global_load_dwordx2 v[244:245], v[206:207], off offset:256 nt
	global_load_dwordx2 v[246:247], v[206:207], off offset:288 nt
	v_lshl_add_u64 v[206:207], v[206:207], 0, v[198:199]
	s_waitcnt vmcnt(8)
	v_lshlrev_b32_e32 v182, 16, v174
	v_and_b32_e32 v183, 0xffff0000, v174
	v_lshlrev_b32_e32 v184, 16, v175
	v_and_b32_e32 v185, 0xffff0000, v175
	v_lshlrev_b32_e32 v186, 16, v176
	v_and_b32_e32 v187, 0xffff0000, v176
	v_lshlrev_b32_e32 v188, 16, v177
	v_and_b32_e32 v189, 0xffff0000, v177
	v_lshlrev_b32_e32 v190, 16, v178
	v_and_b32_e32 v191, 0xffff0000, v178
	v_lshlrev_b32_e32 v192, 16, v179
	v_and_b32_e32 v193, 0xffff0000, v179
	v_lshlrev_b32_e32 v194, 16, v180
	v_and_b32_e32 v195, 0xffff0000, v180
	v_lshlrev_b32_e32 v196, 16, v181
	v_and_b32_e32 v197, 0xffff0000, v181
	v_pk_mul_f32 v[182:183], v[182:183], s[18:19] op_sel_hi:[1,0]
	v_pk_mul_f32 v[184:185], v[184:185], s[18:19] op_sel_hi:[1,0]
	v_pk_mul_f32 v[186:187], v[186:187], s[18:19] op_sel_hi:[1,0]
	v_pk_mul_f32 v[188:189], v[188:189], s[18:19] op_sel_hi:[1,0]
	v_pk_mul_f32 v[190:191], v[190:191], s[18:19] op_sel_hi:[1,0]
	v_pk_mul_f32 v[192:193], v[192:193], s[18:19] op_sel_hi:[1,0]
	v_pk_mul_f32 v[194:195], v[194:195], s[18:19] op_sel_hi:[1,0]
	v_pk_mul_f32 v[196:197], v[196:197], s[18:19] op_sel_hi:[1,0]
	v_pk_fma_f32 v[80:81], v[80:81], v[224:225], v[182:183]
	v_pk_fma_f32 v[82:83], v[82:83], v[226:227], v[184:185]
	v_pk_fma_f32 v[76:77], v[76:77], v[228:229], v[186:187]
	v_pk_fma_f32 v[78:79], v[78:79], v[230:231], v[188:189]
	v_pk_fma_f32 v[72:73], v[72:73], v[232:233], v[190:191]
	v_pk_fma_f32 v[74:75], v[74:75], v[234:235], v[192:193]
	v_pk_fma_f32 v[68:69], v[68:69], v[236:237], v[194:195]
	v_pk_fma_f32 v[70:71], v[70:71], v[238:239], v[196:197]
	s_nop 0
	global_store_dwordx4 v[208:209], v[80:83], off
	global_store_dwordx4 v[208:209], v[76:79], off offset:64
	global_store_dwordx4 v[208:209], v[72:75], off offset:512
	global_store_dwordx4 v[208:209], v[68:71], off offset:576
	v_lshl_add_u64 v[208:209], v[208:209], 0, v[204:205]
	global_load_dwordx2 v[174:175], v[206:207], off nt
	global_load_dwordx2 v[176:177], v[206:207], off offset:32 nt
	global_load_dwordx2 v[178:179], v[206:207], off offset:256 nt
	global_load_dwordx2 v[180:181], v[206:207], off offset:288 nt
	v_lshl_add_u64 v[206:207], v[206:207], 0, v[198:199]
	s_waitcnt vmcnt(8)
	v_lshlrev_b32_e32 v182, 16, v240
	v_and_b32_e32 v183, 0xffff0000, v240
	v_lshlrev_b32_e32 v184, 16, v241
	v_and_b32_e32 v185, 0xffff0000, v241
	v_lshlrev_b32_e32 v186, 16, v242
	v_and_b32_e32 v187, 0xffff0000, v242
	v_lshlrev_b32_e32 v188, 16, v243
	v_and_b32_e32 v189, 0xffff0000, v243
	v_lshlrev_b32_e32 v190, 16, v244
	v_and_b32_e32 v191, 0xffff0000, v244
	v_lshlrev_b32_e32 v192, 16, v245
	v_and_b32_e32 v193, 0xffff0000, v245
	v_lshlrev_b32_e32 v194, 16, v246
	v_and_b32_e32 v195, 0xffff0000, v246
	v_lshlrev_b32_e32 v196, 16, v247
	v_and_b32_e32 v197, 0xffff0000, v247
	v_pk_mul_f32 v[182:183], v[182:183], s[18:19] op_sel_hi:[1,0]
	v_pk_mul_f32 v[184:185], v[184:185], s[18:19] op_sel_hi:[1,0]
	v_pk_mul_f32 v[186:187], v[186:187], s[18:19] op_sel_hi:[1,0]
	v_pk_mul_f32 v[188:189], v[188:189], s[18:19] op_sel_hi:[1,0]
	v_pk_mul_f32 v[190:191], v[190:191], s[18:19] op_sel_hi:[1,0]
	v_pk_mul_f32 v[192:193], v[192:193], s[18:19] op_sel_hi:[1,0]
	v_pk_mul_f32 v[194:195], v[194:195], s[18:19] op_sel_hi:[1,0]
	v_pk_mul_f32 v[196:197], v[196:197], s[18:19] op_sel_hi:[1,0]
	v_pk_fma_f32 v[64:65], v[64:65], v[224:225], v[182:183]
	v_pk_fma_f32 v[66:67], v[66:67], v[226:227], v[184:185]
	v_pk_fma_f32 v[60:61], v[60:61], v[228:229], v[186:187]
	v_pk_fma_f32 v[62:63], v[62:63], v[230:231], v[188:189]
	v_pk_fma_f32 v[56:57], v[56:57], v[232:233], v[190:191]
	v_pk_fma_f32 v[58:59], v[58:59], v[234:235], v[192:193]
	v_pk_fma_f32 v[52:53], v[52:53], v[236:237], v[194:195]
	v_pk_fma_f32 v[54:55], v[54:55], v[238:239], v[196:197]
	s_nop 0
	global_store_dwordx4 v[208:209], v[64:67], off
	global_store_dwordx4 v[208:209], v[60:63], off offset:64
	global_store_dwordx4 v[208:209], v[56:59], off offset:512
	global_store_dwordx4 v[208:209], v[52:55], off offset:576
	v_lshl_add_u64 v[208:209], v[208:209], 0, v[202:203]
	global_load_dwordx2 v[240:241], v[206:207], off nt
	global_load_dwordx2 v[242:243], v[206:207], off offset:32 nt
	global_load_dwordx2 v[244:245], v[206:207], off offset:256 nt
	global_load_dwordx2 v[246:247], v[206:207], off offset:288 nt
	v_lshl_add_u64 v[206:207], v[206:207], 0, v[198:199]
	s_waitcnt vmcnt(8)
	v_lshlrev_b32_e32 v182, 16, v174
	v_and_b32_e32 v183, 0xffff0000, v174
	v_lshlrev_b32_e32 v184, 16, v175
	v_and_b32_e32 v185, 0xffff0000, v175
	v_lshlrev_b32_e32 v186, 16, v176
	v_and_b32_e32 v187, 0xffff0000, v176
	v_lshlrev_b32_e32 v188, 16, v177
	v_and_b32_e32 v189, 0xffff0000, v177
	v_lshlrev_b32_e32 v190, 16, v178
	v_and_b32_e32 v191, 0xffff0000, v178
	v_lshlrev_b32_e32 v192, 16, v179
	v_and_b32_e32 v193, 0xffff0000, v179
	v_lshlrev_b32_e32 v194, 16, v180
	v_and_b32_e32 v195, 0xffff0000, v180
	v_lshlrev_b32_e32 v196, 16, v181
	v_and_b32_e32 v197, 0xffff0000, v181
	v_pk_mul_f32 v[182:183], v[182:183], s[18:19] op_sel_hi:[1,0]
	v_pk_mul_f32 v[184:185], v[184:185], s[18:19] op_sel_hi:[1,0]
	v_pk_mul_f32 v[186:187], v[186:187], s[18:19] op_sel_hi:[1,0]
	v_pk_mul_f32 v[188:189], v[188:189], s[18:19] op_sel_hi:[1,0]
	v_pk_mul_f32 v[190:191], v[190:191], s[18:19] op_sel_hi:[1,0]
	v_pk_mul_f32 v[192:193], v[192:193], s[18:19] op_sel_hi:[1,0]
	v_pk_mul_f32 v[194:195], v[194:195], s[18:19] op_sel_hi:[1,0]
	v_pk_mul_f32 v[196:197], v[196:197], s[18:19] op_sel_hi:[1,0]
	v_pk_fma_f32 v[48:49], v[48:49], v[224:225], v[182:183]
	v_pk_fma_f32 v[50:51], v[50:51], v[226:227], v[184:185]
	v_pk_fma_f32 v[44:45], v[44:45], v[228:229], v[186:187]
	v_pk_fma_f32 v[46:47], v[46:47], v[230:231], v[188:189]
	v_pk_fma_f32 v[40:41], v[40:41], v[232:233], v[190:191]
	v_pk_fma_f32 v[42:43], v[42:43], v[234:235], v[192:193]
	v_pk_fma_f32 v[36:37], v[36:37], v[236:237], v[194:195]
	v_pk_fma_f32 v[38:39], v[38:39], v[238:239], v[196:197]
	s_nop 0
	global_store_dwordx4 v[208:209], v[48:51], off
	global_store_dwordx4 v[208:209], v[44:47], off offset:64
	global_store_dwordx4 v[208:209], v[40:43], off offset:512
	global_store_dwordx4 v[208:209], v[36:39], off offset:576
	v_lshl_add_u64 v[208:209], v[208:209], 0, v[202:203]
	global_load_dwordx2 v[174:175], v[206:207], off nt
	global_load_dwordx2 v[176:177], v[206:207], off offset:32 nt
	global_load_dwordx2 v[178:179], v[206:207], off offset:256 nt
	global_load_dwordx2 v[180:181], v[206:207], off offset:288 nt
	v_lshl_add_u64 v[206:207], v[206:207], 0, v[200:201]
	s_waitcnt vmcnt(8)
	v_lshlrev_b32_e32 v182, 16, v240
	v_and_b32_e32 v183, 0xffff0000, v240
	v_lshlrev_b32_e32 v184, 16, v241
	v_and_b32_e32 v185, 0xffff0000, v241
	v_lshlrev_b32_e32 v186, 16, v242
	v_and_b32_e32 v187, 0xffff0000, v242
	v_lshlrev_b32_e32 v188, 16, v243
	v_and_b32_e32 v189, 0xffff0000, v243
	v_lshlrev_b32_e32 v190, 16, v244
	v_and_b32_e32 v191, 0xffff0000, v244
	v_lshlrev_b32_e32 v192, 16, v245
	v_and_b32_e32 v193, 0xffff0000, v245
	v_lshlrev_b32_e32 v194, 16, v246
	v_and_b32_e32 v195, 0xffff0000, v246
	v_lshlrev_b32_e32 v196, 16, v247
	v_and_b32_e32 v197, 0xffff0000, v247
	v_pk_mul_f32 v[182:183], v[182:183], s[18:19] op_sel_hi:[1,0]
	v_pk_mul_f32 v[184:185], v[184:185], s[18:19] op_sel_hi:[1,0]
	v_pk_mul_f32 v[186:187], v[186:187], s[18:19] op_sel_hi:[1,0]
	v_pk_mul_f32 v[188:189], v[188:189], s[18:19] op_sel_hi:[1,0]
	v_pk_mul_f32 v[190:191], v[190:191], s[18:19] op_sel_hi:[1,0]
	v_pk_mul_f32 v[192:193], v[192:193], s[18:19] op_sel_hi:[1,0]
	v_pk_mul_f32 v[194:195], v[194:195], s[18:19] op_sel_hi:[1,0]
	v_pk_mul_f32 v[196:197], v[196:197], s[18:19] op_sel_hi:[1,0]
	v_pk_fma_f32 v[30:31], v[30:31], v[224:225], v[182:183]
	v_pk_fma_f32 v[32:33], v[32:33], v[226:227], v[184:185]
	v_pk_fma_f32 v[26:27], v[26:27], v[228:229], v[186:187]
	v_pk_fma_f32 v[28:29], v[28:29], v[230:231], v[188:189]
	v_pk_fma_f32 v[22:23], v[22:23], v[232:233], v[190:191]
	v_pk_fma_f32 v[24:25], v[24:25], v[234:235], v[192:193]
	v_pk_fma_f32 v[18:19], v[18:19], v[236:237], v[194:195]
	v_pk_fma_f32 v[20:21], v[20:21], v[238:239], v[196:197]
	s_nop 0
	global_store_dwordx4 v[208:209], v[30:33], off
	global_store_dwordx4 v[208:209], v[26:29], off offset:64
	global_store_dwordx4 v[208:209], v[22:25], off offset:512
	global_store_dwordx4 v[208:209], v[18:21], off offset:576
	v_lshl_add_u64 v[208:209], v[208:209], 0, v[202:203]
	s_waitcnt vmcnt(4)
	v_lshlrev_b32_e32 v182, 16, v174
	v_and_b32_e32 v183, 0xffff0000, v174
	v_lshlrev_b32_e32 v184, 16, v175
	v_and_b32_e32 v185, 0xffff0000, v175
	v_lshlrev_b32_e32 v186, 16, v176
	v_and_b32_e32 v187, 0xffff0000, v176
	v_lshlrev_b32_e32 v188, 16, v177
	v_and_b32_e32 v189, 0xffff0000, v177
	v_lshlrev_b32_e32 v190, 16, v178
	v_and_b32_e32 v191, 0xffff0000, v178
	v_lshlrev_b32_e32 v192, 16, v179
	v_and_b32_e32 v193, 0xffff0000, v179
	v_lshlrev_b32_e32 v194, 16, v180
	v_and_b32_e32 v195, 0xffff0000, v180
	v_lshlrev_b32_e32 v196, 16, v181
	v_and_b32_e32 v197, 0xffff0000, v181
	v_pk_mul_f32 v[182:183], v[182:183], s[18:19] op_sel_hi:[1,0]
	v_pk_mul_f32 v[184:185], v[184:185], s[18:19] op_sel_hi:[1,0]
	v_pk_mul_f32 v[186:187], v[186:187], s[18:19] op_sel_hi:[1,0]
	v_pk_mul_f32 v[188:189], v[188:189], s[18:19] op_sel_hi:[1,0]
	v_pk_mul_f32 v[190:191], v[190:191], s[18:19] op_sel_hi:[1,0]
	v_pk_mul_f32 v[192:193], v[192:193], s[18:19] op_sel_hi:[1,0]
	v_pk_mul_f32 v[194:195], v[194:195], s[18:19] op_sel_hi:[1,0]
	v_pk_mul_f32 v[196:197], v[196:197], s[18:19] op_sel_hi:[1,0]
	v_pk_fma_f32 v[14:15], v[14:15], v[224:225], v[182:183]
	v_pk_fma_f32 v[16:17], v[16:17], v[226:227], v[184:185]
	v_pk_fma_f32 v[10:11], v[10:11], v[228:229], v[186:187]
	v_pk_fma_f32 v[12:13], v[12:13], v[230:231], v[188:189]
	v_pk_fma_f32 v[6:7], v[6:7], v[232:233], v[190:191]
	v_pk_fma_f32 v[8:9], v[8:9], v[234:235], v[192:193]
	v_pk_fma_f32 v[2:3], v[2:3], v[236:237], v[194:195]
	v_pk_fma_f32 v[4:5], v[4:5], v[238:239], v[196:197]
	s_nop 0
	global_store_dwordx4 v[208:209], v[14:17], off
	global_store_dwordx4 v[208:209], v[10:13], off offset:64
	global_store_dwordx4 v[208:209], v[6:9], off offset:512
	global_store_dwordx4 v[208:209], v[2:5], off offset:576
	v_lshl_add_u64 v[208:209], v[208:209], 0, v[204:205]
	s_mov_b64 s[20:21], s[6:7]
	s_cbranch_vccz .LBB0_2591
	s_waitcnt vmcnt(0)
	s_cmpk_gt_u32 s5, 0xff
	s_cbranch_scc1 .LBB0_2606
	s_barrier
